# plus: GEMM phase-2/6 B1 fragment LDS reads hoisted into the previous phase's MFMA block
# baseline (speedup 1.0000x reference)
.LBB0_304:
	s_add_u32 s2, s68, 0xfff80080
	s_addc_u32 s17, s69, -1
	s_add_i32 s26, 0, 0x10000
	v_add_u32_e32 v156, s26, v141
	ds_read_b128 v[144:147], v156
	ds_read_b128 v[148:151], v156 offset:1024
	ds_read_b128 v[152:155], v156 offset:2048
	ds_read_b128 v[156:159], v156 offset:3072
	s_cmp_eq_u32 s44, 28
	s_cselect_b32 s73, s55, s17
	s_cselect_b32 s72, s83, s2
	s_cselect_b32 s71, s24, s92
	s_cselect_b32 s70, s25, s43
	v_lshl_add_u64 v[164:165], s[68:69], 0, v[136:137]
	s_add_i32 m0, s58, 0xc000
	ds_read_b128 v[160:163], v143
	ds_read_b128 v[188:191], v143 offset:1024
	ds_read_b128 v[192:195], v143 offset:2048
	ds_read_b128 v[196:199], v143 offset:3072
	ds_read_b128 v[200:203], v143 offset:4096
	ds_read_b128 v[216:219], v143 offset:5120
	ds_read_b128 v[220:223], v143 offset:6144
	ds_read_b128 v[224:227], v143 offset:7168
	global_load_lds_dwordx4 v[164:165], off
	v_lshl_add_u64 v[164:165], s[68:69], 0, v[138:139]
	s_add_i32 m0, s58, 0xe000
	s_nop 0
	global_load_lds_dwordx4 v[164:165], off
	s_waitcnt lgkmcnt(8)
	s_barrier
	s_waitcnt lgkmcnt(7)
	v_mfma_f32_16x16x32_bf16 v[126:129], v[144:147], v[160:163], v[126:129]
	v_mfma_f32_16x16x32_bf16 v[122:125], v[152:155], v[160:163], v[122:125]
	s_waitcnt lgkmcnt(5)
	v_mfma_f32_16x16x32_bf16 v[118:121], v[144:147], v[192:195], v[118:121]
	v_mfma_f32_16x16x32_bf16 v[114:117], v[152:155], v[192:195], v[114:117]
	s_waitcnt lgkmcnt(3)
	v_mfma_f32_16x16x32_bf16 v[102:105], v[144:147], v[200:203], v[102:105]
	v_mfma_f32_16x16x32_bf16 v[98:101], v[152:155], v[200:203], v[98:101]
	s_waitcnt lgkmcnt(1)
	v_mfma_f32_16x16x32_bf16 v[86:89], v[144:147], v[220:223], v[86:89]
	v_mfma_f32_16x16x32_bf16 v[82:85], v[152:155], v[220:223], v[82:85]
	s_add_i32 s2, 0, 0x14000
	v_add_u32_e32 v164, s2, v141
	ds_read_b128 v[228:231], v164
	ds_read_b128 v[232:235], v164 offset:1024
	ds_read_b128 v[236:239], v164 offset:2048
	ds_read_b128 v[240:243], v164 offset:3072
	v_mfma_f32_16x16x32_bf16 v[126:129], v[148:151], v[188:191], v[126:129]
	v_mfma_f32_16x16x32_bf16 v[122:125], v[156:159], v[188:191], v[122:125]
	v_mfma_f32_16x16x32_bf16 v[118:121], v[148:151], v[196:199], v[118:121]
	v_mfma_f32_16x16x32_bf16 v[114:117], v[156:159], v[196:199], v[114:117]
	v_mfma_f32_16x16x32_bf16 v[102:105], v[148:151], v[216:219], v[102:105]
	v_mfma_f32_16x16x32_bf16 v[98:101], v[156:159], v[216:219], v[98:101]
	s_waitcnt lgkmcnt(4)
	v_mfma_f32_16x16x32_bf16 v[86:89], v[148:151], v[224:227], v[86:89]
	v_mfma_f32_16x16x32_bf16 v[82:85], v[156:159], v[224:227], v[82:85]
	s_barrier
	s_add_i32 s17, s26, s3
	v_lshl_add_u64 v[164:165], s[70:71], 0, v[0:1]
	s_mov_b32 m0, s17
	v_lshl_add_u64 v[204:205], s[70:71], 0, v[130:131]
	global_load_lds_dwordx4 v[164:165], off
	s_add_i32 m0, s17, 0x2000
	s_nop 0
	global_load_lds_dwordx4 v[204:205], off
	s_barrier
	s_waitcnt lgkmcnt(3)
	v_mfma_f32_16x16x32_bf16 v[110:113], v[228:231], v[160:163], v[110:113]
	s_waitcnt lgkmcnt(1)
	v_mfma_f32_16x16x32_bf16 v[106:109], v[236:239], v[160:163], v[106:109]
	v_mfma_f32_16x16x32_bf16 v[94:97], v[228:231], v[192:195], v[94:97]
	v_mfma_f32_16x16x32_bf16 v[90:93], v[236:239], v[192:195], v[90:93]
	v_mfma_f32_16x16x32_bf16 v[78:81], v[228:231], v[200:203], v[78:81]
	v_mfma_f32_16x16x32_bf16 v[74:77], v[236:239], v[200:203], v[74:77]
	v_mfma_f32_16x16x32_bf16 v[70:73], v[228:231], v[220:223], v[70:73]
	v_mfma_f32_16x16x32_bf16 v[66:69], v[236:239], v[220:223], v[66:69]
	v_mfma_f32_16x16x32_bf16 v[110:113], v[232:235], v[188:191], v[110:113]
	s_waitcnt lgkmcnt(0)
	v_mfma_f32_16x16x32_bf16 v[106:109], v[240:243], v[188:191], v[106:109]
	v_mfma_f32_16x16x32_bf16 v[94:97], v[232:235], v[196:199], v[94:97]
	v_mfma_f32_16x16x32_bf16 v[90:93], v[240:243], v[196:199], v[90:93]
	v_mfma_f32_16x16x32_bf16 v[78:81], v[232:235], v[216:219], v[78:81]
	v_mfma_f32_16x16x32_bf16 v[74:77], v[240:243], v[216:219], v[74:77]
	v_mfma_f32_16x16x32_bf16 v[70:73], v[232:235], v[224:227], v[70:73]
	v_mfma_f32_16x16x32_bf16 v[66:69], v[240:243], v[224:227], v[66:69]
	s_mov_b32 m0, s58
	v_lshl_add_u64 v[244:245], s[72:73], 0, v[134:135]
	s_barrier
	ds_read_b128 v[160:163], v143 offset:16384
	ds_read_b128 v[188:191], v143 offset:17408
	ds_read_b128 v[192:195], v143 offset:18432
	ds_read_b128 v[196:199], v143 offset:19456
	ds_read_b128 v[200:203], v143 offset:20480
	ds_read_b128 v[216:219], v143 offset:21504
	ds_read_b128 v[220:223], v143 offset:22528
	ds_read_b128 v[224:227], v143 offset:23552
	global_load_lds_dwordx4 v[244:245], off
	v_lshl_add_u64 v[246:247], s[72:73], 0, v[132:133]
	s_mov_b32 m0, s74
	s_nop 0
	global_load_lds_dwordx4 v[246:247], off
	s_barrier
	s_waitcnt lgkmcnt(7)
	v_mfma_f32_16x16x32_bf16 v[62:65], v[144:147], v[160:163], v[62:65]
	v_mfma_f32_16x16x32_bf16 v[58:61], v[152:155], v[160:163], v[58:61]
	s_waitcnt lgkmcnt(5)
	v_mfma_f32_16x16x32_bf16 v[54:57], v[144:147], v[192:195], v[54:57]
	v_mfma_f32_16x16x32_bf16 v[50:53], v[152:155], v[192:195], v[50:53]
	s_waitcnt lgkmcnt(3)
	v_mfma_f32_16x16x32_bf16 v[38:41], v[144:147], v[200:203], v[38:41]
	v_mfma_f32_16x16x32_bf16 v[34:37], v[152:155], v[200:203], v[34:37]
	s_waitcnt lgkmcnt(1)
	v_mfma_f32_16x16x32_bf16 v[22:25], v[144:147], v[220:223], v[22:25]
	v_mfma_f32_16x16x32_bf16 v[18:21], v[152:155], v[220:223], v[18:21]
	v_mfma_f32_16x16x32_bf16 v[62:65], v[148:151], v[188:191], v[62:65]
	v_mfma_f32_16x16x32_bf16 v[58:61], v[156:159], v[188:191], v[58:61]
	v_mfma_f32_16x16x32_bf16 v[54:57], v[148:151], v[196:199], v[54:57]
	v_mfma_f32_16x16x32_bf16 v[50:53], v[156:159], v[196:199], v[50:53]
	v_mfma_f32_16x16x32_bf16 v[38:41], v[148:151], v[216:219], v[38:41]
	v_mfma_f32_16x16x32_bf16 v[34:37], v[156:159], v[216:219], v[34:37]
	s_waitcnt lgkmcnt(0)
	v_mfma_f32_16x16x32_bf16 v[22:25], v[148:151], v[224:227], v[22:25]
	v_mfma_f32_16x16x32_bf16 v[18:21], v[156:159], v[224:227], v[18:21]
	s_barrier
	s_add_u32 s26, s70, 0x80000
	s_addc_u32 s27, s71, 0
	s_add_i32 s2, s2, s3
	v_lshl_add_u64 v[144:145], s[26:27], 0, v[0:1]
	s_mov_b32 m0, s2
	s_nop 0
	global_load_lds_dwordx4 v[144:145], off
	v_lshl_add_u64 v[144:145], s[26:27], 0, v[130:131]
	s_add_i32 m0, s2, 0x2000
	s_nop 0
	global_load_lds_dwordx4 v[144:145], off
	s_waitcnt vmcnt(6)
	s_barrier
	v_mfma_f32_16x16x32_bf16 v[46:49], v[228:231], v[160:163], v[46:49]
	v_mfma_f32_16x16x32_bf16 v[42:45], v[236:239], v[160:163], v[42:45]
	v_mfma_f32_16x16x32_bf16 v[30:33], v[228:231], v[192:195], v[30:33]
	v_mfma_f32_16x16x32_bf16 v[26:29], v[236:239], v[192:195], v[26:29]
	v_mfma_f32_16x16x32_bf16 v[14:17], v[228:231], v[200:203], v[14:17]
	v_mfma_f32_16x16x32_bf16 v[10:13], v[236:239], v[200:203], v[10:13]
	v_mfma_f32_16x16x32_bf16 v[6:9], v[228:231], v[220:223], v[6:9]
	v_mfma_f32_16x16x32_bf16 v[2:5], v[236:239], v[220:223], v[2:5]
	v_mfma_f32_16x16x32_bf16 v[46:49], v[232:235], v[188:191], v[46:49]
	v_mfma_f32_16x16x32_bf16 v[42:45], v[240:243], v[188:191], v[42:45]
	v_mfma_f32_16x16x32_bf16 v[30:33], v[232:235], v[196:199], v[30:33]
	v_mfma_f32_16x16x32_bf16 v[26:29], v[240:243], v[196:199], v[26:29]
	v_mfma_f32_16x16x32_bf16 v[14:17], v[232:235], v[216:219], v[14:17]
	v_mfma_f32_16x16x32_bf16 v[10:13], v[240:243], v[216:219], v[10:13]
	v_mfma_f32_16x16x32_bf16 v[6:9], v[232:235], v[224:227], v[6:9]
	v_mfma_f32_16x16x32_bf16 v[2:5], v[240:243], v[224:227], v[2:5]
	s_add_i32 s2, 0, 0x18000
	v_add_u32_e32 v156, s2, v141
	s_barrier
	ds_read_b128 v[144:147], v156
	ds_read_b128 v[148:151], v156 offset:1024
	ds_read_b128 v[152:155], v156 offset:2048
	ds_read_b128 v[156:159], v156 offset:3072
	s_add_u32 s26, s72, 0x80000
	s_addc_u32 s27, s73, 0
	s_mov_b32 m0, s75
	v_lshl_add_u64 v[228:229], s[26:27], 0, v[134:135]
	ds_read_b128 v[160:163], v143 offset:32768
	ds_read_b128 v[188:191], v143 offset:33792
	ds_read_b128 v[192:195], v143 offset:34816
	ds_read_b128 v[196:199], v143 offset:35840
	ds_read_b128 v[200:203], v143 offset:36864
	ds_read_b128 v[216:219], v143 offset:37888
	ds_read_b128 v[220:223], v143 offset:38912
	ds_read_b128 v[224:227], v143 offset:39936
	global_load_lds_dwordx4 v[228:229], off
	v_lshl_add_u64 v[228:229], s[26:27], 0, v[132:133]
	s_mov_b32 m0, s79
	s_nop 0
	global_load_lds_dwordx4 v[228:229], off
	s_waitcnt lgkmcnt(8)
	s_barrier
	s_waitcnt lgkmcnt(7)
	v_mfma_f32_16x16x32_bf16 v[126:129], v[144:147], v[160:163], v[126:129]
	v_mfma_f32_16x16x32_bf16 v[122:125], v[152:155], v[160:163], v[122:125]
	s_waitcnt lgkmcnt(5)
	v_mfma_f32_16x16x32_bf16 v[118:121], v[144:147], v[192:195], v[118:121]
	v_mfma_f32_16x16x32_bf16 v[114:117], v[152:155], v[192:195], v[114:117]
	s_waitcnt lgkmcnt(3)
	v_mfma_f32_16x16x32_bf16 v[102:105], v[144:147], v[200:203], v[102:105]
	v_mfma_f32_16x16x32_bf16 v[98:101], v[152:155], v[200:203], v[98:101]
	s_waitcnt lgkmcnt(1)
	v_mfma_f32_16x16x32_bf16 v[86:89], v[144:147], v[220:223], v[86:89]
	v_mfma_f32_16x16x32_bf16 v[82:85], v[152:155], v[220:223], v[82:85]
	s_add_i32 s17, 0, 0x1c000
	v_add_u32_e32 v206, s17, v141
	ds_read_b128 v[228:231], v206
	ds_read_b128 v[232:235], v206 offset:1024
	ds_read_b128 v[236:239], v206 offset:2048
	ds_read_b128 v[240:243], v206 offset:3072
	v_mfma_f32_16x16x32_bf16 v[126:129], v[148:151], v[188:191], v[126:129]
	v_mfma_f32_16x16x32_bf16 v[122:125], v[156:159], v[188:191], v[122:125]
	v_mfma_f32_16x16x32_bf16 v[118:121], v[148:151], v[196:199], v[118:121]
	v_mfma_f32_16x16x32_bf16 v[114:117], v[156:159], v[196:199], v[114:117]
	v_mfma_f32_16x16x32_bf16 v[102:105], v[148:151], v[216:219], v[102:105]
	v_mfma_f32_16x16x32_bf16 v[98:101], v[156:159], v[216:219], v[98:101]
	s_waitcnt lgkmcnt(4)
	v_mfma_f32_16x16x32_bf16 v[86:89], v[148:151], v[224:227], v[86:89]
	v_mfma_f32_16x16x32_bf16 v[82:85], v[156:159], v[224:227], v[82:85]
	s_barrier
	s_add_i32 s2, s2, s3
	v_lshl_add_u64 v[164:165], v[164:165], 0, s[28:29]
	s_mov_b32 m0, s2
	global_load_lds_dwordx4 v[164:165], off
	v_lshl_add_u64 v[164:165], v[204:205], 0, s[28:29]
	s_add_i32 m0, s2, 0x2000
	s_nop 0
	global_load_lds_dwordx4 v[164:165], off
	s_barrier
	s_waitcnt lgkmcnt(3)
	v_mfma_f32_16x16x32_bf16 v[110:113], v[228:231], v[160:163], v[110:113]
	s_waitcnt lgkmcnt(1)
	v_mfma_f32_16x16x32_bf16 v[106:109], v[236:239], v[160:163], v[106:109]
	v_mfma_f32_16x16x32_bf16 v[94:97], v[228:231], v[192:195], v[94:97]
	v_mfma_f32_16x16x32_bf16 v[90:93], v[236:239], v[192:195], v[90:93]
	v_mfma_f32_16x16x32_bf16 v[78:81], v[228:231], v[200:203], v[78:81]
	v_mfma_f32_16x16x32_bf16 v[74:77], v[236:239], v[200:203], v[74:77]
	v_mfma_f32_16x16x32_bf16 v[70:73], v[228:231], v[220:223], v[70:73]
	v_mfma_f32_16x16x32_bf16 v[66:69], v[236:239], v[220:223], v[66:69]
	v_mfma_f32_16x16x32_bf16 v[110:113], v[232:235], v[188:191], v[110:113]
	s_waitcnt lgkmcnt(0)
	v_mfma_f32_16x16x32_bf16 v[106:109], v[240:243], v[188:191], v[106:109]
	v_mfma_f32_16x16x32_bf16 v[94:97], v[232:235], v[196:199], v[94:97]
	v_mfma_f32_16x16x32_bf16 v[90:93], v[240:243], v[196:199], v[90:93]
	v_mfma_f32_16x16x32_bf16 v[78:81], v[232:235], v[216:219], v[78:81]
	v_mfma_f32_16x16x32_bf16 v[74:77], v[240:243], v[216:219], v[74:77]
	v_mfma_f32_16x16x32_bf16 v[70:73], v[232:235], v[224:227], v[70:73]
	v_mfma_f32_16x16x32_bf16 v[66:69], v[240:243], v[224:227], v[66:69]
	s_mov_b32 m0, s80
	v_lshl_add_u64 v[164:165], v[244:245], 0, s[28:29]
	s_barrier
	ds_read_b128 v[160:163], v143 offset:49152
	ds_read_b128 v[188:191], v143 offset:50176
	ds_read_b128 v[192:195], v143 offset:51200
	ds_read_b128 v[196:199], v143 offset:52224
	ds_read_b128 v[200:203], v143 offset:53248
	ds_read_b128 v[216:219], v143 offset:54272
	ds_read_b128 v[220:223], v143 offset:55296
	ds_read_b128 v[224:227], v143 offset:56320
	global_load_lds_dwordx4 v[164:165], off
	v_lshl_add_u64 v[164:165], v[246:247], 0, s[28:29]
	s_mov_b32 m0, s81
	s_nop 0
	global_load_lds_dwordx4 v[164:165], off
	s_barrier
	s_waitcnt lgkmcnt(7)
	v_mfma_f32_16x16x32_bf16 v[62:65], v[144:147], v[160:163], v[62:65]
	v_mfma_f32_16x16x32_bf16 v[58:61], v[152:155], v[160:163], v[58:61]
	s_waitcnt lgkmcnt(5)
	v_mfma_f32_16x16x32_bf16 v[54:57], v[144:147], v[192:195], v[54:57]
	v_mfma_f32_16x16x32_bf16 v[50:53], v[152:155], v[192:195], v[50:53]
	s_waitcnt lgkmcnt(3)
	v_mfma_f32_16x16x32_bf16 v[38:41], v[144:147], v[200:203], v[38:41]
	v_mfma_f32_16x16x32_bf16 v[34:37], v[152:155], v[200:203], v[34:37]
	s_waitcnt lgkmcnt(1)
	v_mfma_f32_16x16x32_bf16 v[22:25], v[144:147], v[220:223], v[22:25]
	v_mfma_f32_16x16x32_bf16 v[18:21], v[152:155], v[220:223], v[18:21]
	v_mfma_f32_16x16x32_bf16 v[62:65], v[148:151], v[188:191], v[62:65]
	v_mfma_f32_16x16x32_bf16 v[58:61], v[156:159], v[188:191], v[58:61]
	v_mfma_f32_16x16x32_bf16 v[54:57], v[148:151], v[196:199], v[54:57]
	v_mfma_f32_16x16x32_bf16 v[50:53], v[156:159], v[196:199], v[50:53]
	v_mfma_f32_16x16x32_bf16 v[38:41], v[148:151], v[216:219], v[38:41]
	v_mfma_f32_16x16x32_bf16 v[34:37], v[156:159], v[216:219], v[34:37]
	s_waitcnt lgkmcnt(0)
	v_mfma_f32_16x16x32_bf16 v[22:25], v[148:151], v[224:227], v[22:25]
	v_mfma_f32_16x16x32_bf16 v[18:21], v[156:159], v[224:227], v[18:21]
	s_barrier
	s_add_u32 s26, s70, 0x80080
	s_addc_u32 s27, s71, 0
	s_add_i32 s2, s17, s3
	v_lshl_add_u64 v[144:145], s[26:27], 0, v[0:1]
	s_mov_b32 m0, s2
	s_nop 0
	global_load_lds_dwordx4 v[144:145], off
	v_lshl_add_u64 v[144:145], s[26:27], 0, v[130:131]
	s_add_i32 m0, s2, 0x2000
	s_nop 0
	global_load_lds_dwordx4 v[144:145], off
	s_waitcnt vmcnt(6)
	s_barrier
	v_mfma_f32_16x16x32_bf16 v[46:49], v[228:231], v[160:163], v[46:49]
	v_mfma_f32_16x16x32_bf16 v[42:45], v[236:239], v[160:163], v[42:45]
	v_mfma_f32_16x16x32_bf16 v[30:33], v[228:231], v[192:195], v[30:33]
	v_mfma_f32_16x16x32_bf16 v[26:29], v[236:239], v[192:195], v[26:29]
	v_mfma_f32_16x16x32_bf16 v[14:17], v[228:231], v[200:203], v[14:17]
	v_mfma_f32_16x16x32_bf16 v[10:13], v[236:239], v[200:203], v[10:13]
	v_mfma_f32_16x16x32_bf16 v[6:9], v[228:231], v[220:223], v[6:9]
	v_mfma_f32_16x16x32_bf16 v[2:5], v[236:239], v[220:223], v[2:5]
	v_mfma_f32_16x16x32_bf16 v[46:49], v[232:235], v[188:191], v[46:49]
	v_mfma_f32_16x16x32_bf16 v[42:45], v[240:243], v[188:191], v[42:45]
	v_mfma_f32_16x16x32_bf16 v[30:33], v[232:235], v[196:199], v[30:33]
	v_mfma_f32_16x16x32_bf16 v[26:29], v[240:243], v[196:199], v[26:29]
	v_mfma_f32_16x16x32_bf16 v[14:17], v[232:235], v[216:219], v[14:17]
	v_mfma_f32_16x16x32_bf16 v[10:13], v[240:243], v[216:219], v[10:13]
	v_mfma_f32_16x16x32_bf16 v[6:9], v[232:235], v[224:227], v[6:9]
	v_mfma_f32_16x16x32_bf16 v[2:5], v[240:243], v[224:227], v[2:5]
	s_add_i32 s44, s44, 2
	s_add_u32 s68, s68, 0x100
	s_addc_u32 s69, s69, 0
	s_add_u32 s43, s43, 0x100
	s_addc_u32 s92, s92, 0
	s_cmp_gt_u32 s44, 29
	s_barrier
	s_cbranch_scc0 .LBB0_304
	v_lshl_add_u32 v146, s47, 8, v140
	v_lshl_or_b32 v144, s46, 8, v142
	v_cvt_pk_bf16_f32 v126, v126, v127
	v_cvt_pk_bf16_f32 v127, v128, v129
	v_cvt_pk_bf16_f32 v128, v122, v123
	v_mov_b64_e32 v[122:123], s[22:23]
	v_ashrrev_i32_e32 v145, 31, v144
	v_cvt_pk_bf16_f32 v70, v70, v71
	v_cvt_pk_bf16_f32 v71, v72, v73
	v_cvt_pk_bf16_f32 v72, v66, v67
	v_add_u32_e32 v66, 0x80, v146
	v_cvt_pk_bf16_f32 v129, v124, v125
	v_mad_i64_i32 v[124:125], s[24:25], v146, s97, v[122:123]
	v_lshlrev_b64 v[144:145], 1, v[144:145]
	v_cvt_pk_bf16_f32 v62, v62, v63
	v_cvt_pk_bf16_f32 v63, v64, v65
	v_cvt_pk_bf16_f32 v64, v58, v59
	v_mad_i64_i32 v[58:59], s[24:25], v66, s97, v[122:123]
	v_lshl_add_u64 v[124:125], v[124:125], 0, v[144:145]
	v_cvt_pk_bf16_f32 v110, v110, v111
	v_cvt_pk_bf16_f32 v111, v112, v113
	v_cvt_pk_bf16_f32 v112, v106, v107
	v_cvt_pk_bf16_f32 v113, v108, v109
	v_lshl_add_u64 v[58:59], v[58:59], 0, v[144:145]
	v_cvt_pk_bf16_f32 v46, v46, v47
	v_cvt_pk_bf16_f32 v47, v48, v49
	v_cvt_pk_bf16_f32 v48, v42, v43
	v_cvt_pk_bf16_f32 v49, v44, v45
	global_store_dwordx4 v[124:125], v[110:113], off offset:256
	global_store_dwordx4 v[58:59], v[46:49], off offset:256
	v_cvt_pk_bf16_f32 v94, v94, v95
	v_or_b32_e32 v110, 16, v146
	v_add_u32_e32 v46, 0x90, v146
	v_mad_i64_i32 v[110:111], s[24:25], v110, s97, v[122:123]
	v_mad_i64_i32 v[46:47], s[24:25], v46, s97, v[122:123]
	v_lshl_add_u64 v[110:111], v[110:111], 0, v[144:145]
	v_cvt_pk_bf16_f32 v95, v96, v97
	v_cvt_pk_bf16_f32 v96, v90, v91
	v_cvt_pk_bf16_f32 v97, v92, v93
	v_lshl_add_u64 v[46:47], v[46:47], 0, v[144:145]
	v_cvt_pk_bf16_f32 v30, v30, v31
	v_cvt_pk_bf16_f32 v31, v32, v33
	v_cvt_pk_bf16_f32 v32, v26, v27
	v_cvt_pk_bf16_f32 v33, v28, v29
	global_store_dwordx4 v[110:111], v[94:97], off offset:256
	global_store_dwordx4 v[46:47], v[30:33], off offset:256
	v_cvt_pk_bf16_f32 v78, v78, v79
	v_or_b32_e32 v94, 32, v146
	v_add_u32_e32 v30, 0xa0, v146
	v_mad_i64_i32 v[94:95], s[24:25], v94, s97, v[122:123]
	v_mad_i64_i32 v[30:31], s[24:25], v30, s97, v[122:123]
	v_lshl_add_u64 v[94:95], v[94:95], 0, v[144:145]
	v_cvt_pk_bf16_f32 v79, v80, v81
	v_cvt_pk_bf16_f32 v80, v74, v75
	v_cvt_pk_bf16_f32 v81, v76, v77
	v_lshl_add_u64 v[30:31], v[30:31], 0, v[144:145]
	v_cvt_pk_bf16_f32 v14, v14, v15
	v_cvt_pk_bf16_f32 v15, v16, v17
	v_cvt_pk_bf16_f32 v16, v10, v11
	v_cvt_pk_bf16_f32 v17, v12, v13
	global_store_dwordx4 v[94:95], v[78:81], off offset:256
	global_store_dwordx4 v[30:31], v[14:17], off offset:256
	v_cvt_pk_bf16_f32 v106, v118, v119
	v_or_b32_e32 v78, 48, v146
	v_add_u32_e32 v14, 0xb0, v146
	v_mad_i64_i32 v[78:79], s[24:25], v78, s97, v[122:123]
	v_mad_i64_i32 v[14:15], s[24:25], v14, s97, v[122:123]
	v_cvt_pk_bf16_f32 v107, v120, v121
	v_cvt_pk_bf16_f32 v108, v114, v115
	v_cvt_pk_bf16_f32 v109, v116, v117
	v_cvt_pk_bf16_f32 v90, v102, v103
	v_cvt_pk_bf16_f32 v91, v104, v105
	v_cvt_pk_bf16_f32 v92, v98, v99
	v_cvt_pk_bf16_f32 v93, v100, v101
	v_cvt_pk_bf16_f32 v74, v86, v87
	v_cvt_pk_bf16_f32 v75, v88, v89
	v_cvt_pk_bf16_f32 v76, v82, v83
	v_cvt_pk_bf16_f32 v77, v84, v85
	v_lshl_add_u64 v[78:79], v[78:79], 0, v[144:145]
	v_cvt_pk_bf16_f32 v73, v68, v69
	v_cvt_pk_bf16_f32 v65, v60, v61
	v_cvt_pk_bf16_f32 v42, v54, v55
	v_cvt_pk_bf16_f32 v43, v56, v57
	v_cvt_pk_bf16_f32 v44, v50, v51
	v_cvt_pk_bf16_f32 v45, v52, v53
	v_cvt_pk_bf16_f32 v26, v38, v39
	v_cvt_pk_bf16_f32 v27, v40, v41
	v_cvt_pk_bf16_f32 v28, v34, v35
	v_cvt_pk_bf16_f32 v29, v36, v37
	v_cvt_pk_bf16_f32 v10, v22, v23
	v_cvt_pk_bf16_f32 v11, v24, v25
	v_cvt_pk_bf16_f32 v12, v18, v19
	v_cvt_pk_bf16_f32 v13, v20, v21
	v_lshl_add_u64 v[14:15], v[14:15], 0, v[144:145]
	v_cvt_pk_bf16_f32 v6, v6, v7
	v_cvt_pk_bf16_f32 v7, v8, v9
	v_cvt_pk_bf16_f32 v8, v2, v3
	v_cvt_pk_bf16_f32 v9, v4, v5
	s_and_b64 vcc, exec, s[0:1]
	s_mov_b32 s46, s42
	s_mov_b32 s47, s54
	s_mov_b64 s[70:71], s[64:65]
	s_mov_b64 s[68:69], s[62:63]
	global_store_dwordx4 v[124:125], v[126:129], off
	global_store_dwordx4 v[110:111], v[106:109], off
	global_store_dwordx4 v[94:95], v[90:93], off
	global_store_dwordx4 v[78:79], v[74:77], off
	global_store_dwordx4 v[78:79], v[70:73], off offset:256
	global_store_dwordx4 v[58:59], v[62:65], off
	global_store_dwordx4 v[46:47], v[42:45], off
	global_store_dwordx4 v[30:31], v[26:29], off
	global_store_dwordx4 v[14:15], v[10:13], off
	global_store_dwordx4 v[14:15], v[6:9], off offset:256
	s_cbranch_vccz .LBB0_301
	v_readlane_b32 s0, v254, 12
	s_waitcnt vmcnt(0)
	v_readlane_b32 s1, v254, 13
	v_readlane_b32 s84, v251, 38
	v_readlane_b32 s18, v253, 0
	s_andn2_b64 vcc, exec, s[0:1]
	v_readlane_b32 s85, v251, 39
	v_readlane_b32 s86, v251, 40
	v_readlane_b32 s87, v251, 41
	v_readlane_b32 s14, v250, 63
	v_readlane_b32 s19, v253, 1
	s_cbranch_vccnz .LBB0_308
	s_barrier

.LBB0_433:
	s_add_u32 s6, s78, 0x100
	s_addc_u32 s7, s79, 0
	s_add_i32 s2, 0, 0x10000
	v_add_u32_e32 v0, s2, v153
	ds_read_b128 v[142:145], v0
	ds_read_b128 v[146:149], v0 offset:1024
	ds_read_b128 v[156:159], v0 offset:2048
	ds_read_b128 v[160:163], v0 offset:3072
	s_cmp_eq_u32 s44, 4
	s_cselect_b32 s83, s75, s7
	s_cselect_b32 s82, s74, s6
	s_cselect_b32 s81, s11, s46
	s_cselect_b32 s80, s24, s25
	v_lshl_add_u64 v[150:151], s[78:79], 0, v[138:139]
	s_add_i32 m0, s58, 0xc000
	ds_read_b128 v[188:191], v155
	ds_read_b128 v[192:195], v155 offset:1024
	ds_read_b128 v[196:199], v155 offset:2048
	ds_read_b128 v[200:203], v155 offset:3072
	ds_read_b128 v[216:219], v155 offset:4096
	ds_read_b128 v[220:223], v155 offset:5120
	ds_read_b128 v[224:227], v155 offset:6144
	ds_read_b128 v[228:231], v155 offset:7168
	global_load_lds_dwordx4 v[150:151], off
	v_lshl_add_u64 v[150:151], s[78:79], 0, v[140:141]
	s_add_i32 m0, s58, 0xe000
	s_nop 0
	global_load_lds_dwordx4 v[150:151], off
	s_waitcnt lgkmcnt(8)
	s_barrier
	s_waitcnt lgkmcnt(7)
	v_mfma_f32_16x16x32_bf16 v[126:129], v[142:145], v[188:191], v[126:129]
	v_mfma_f32_16x16x32_bf16 v[122:125], v[156:159], v[188:191], v[122:125]
	s_waitcnt lgkmcnt(5)
	v_mfma_f32_16x16x32_bf16 v[110:113], v[142:145], v[196:199], v[110:113]
	v_mfma_f32_16x16x32_bf16 v[106:109], v[156:159], v[196:199], v[106:109]
	s_waitcnt lgkmcnt(3)
	v_mfma_f32_16x16x32_bf16 v[94:97], v[142:145], v[216:219], v[94:97]
	v_mfma_f32_16x16x32_bf16 v[90:93], v[156:159], v[216:219], v[90:93]
	s_waitcnt lgkmcnt(1)
	v_mfma_f32_16x16x32_bf16 v[78:81], v[142:145], v[224:227], v[78:81]
	v_mfma_f32_16x16x32_bf16 v[74:77], v[156:159], v[224:227], v[74:77]
	s_add_i32 s17, 0, 0x14000
	v_add_u32_e32 v0, s17, v153
	ds_read_b128 v[232:235], v0
	ds_read_b128 v[236:239], v0 offset:1024
	ds_read_b128 v[240:243], v0 offset:2048
	ds_read_b128 v[244:247], v0 offset:3072
	v_mfma_f32_16x16x32_bf16 v[126:129], v[146:149], v[192:195], v[126:129]
	v_mfma_f32_16x16x32_bf16 v[122:125], v[160:163], v[192:195], v[122:125]
	v_mfma_f32_16x16x32_bf16 v[110:113], v[146:149], v[200:203], v[110:113]
	v_mfma_f32_16x16x32_bf16 v[106:109], v[160:163], v[200:203], v[106:109]
	v_mfma_f32_16x16x32_bf16 v[94:97], v[146:149], v[220:223], v[94:97]
	v_mfma_f32_16x16x32_bf16 v[90:93], v[160:163], v[220:223], v[90:93]
	s_waitcnt lgkmcnt(4)
	v_mfma_f32_16x16x32_bf16 v[78:81], v[146:149], v[228:231], v[78:81]
	v_mfma_f32_16x16x32_bf16 v[74:77], v[160:163], v[228:231], v[74:77]
	s_barrier
	s_add_i32 s2, s2, s3
	v_lshl_add_u64 v[150:151], s[80:81], 0, v[134:135]
	s_mov_b32 m0, s2
	global_load_lds_dwordx4 v[150:151], off
	v_lshl_add_u64 v[164:165], s[80:81], 0, v[130:131]
	s_add_i32 m0, s2, 0x2000
	s_nop 0
	global_load_lds_dwordx4 v[164:165], off
	s_barrier
	s_waitcnt lgkmcnt(3)
	v_mfma_f32_16x16x32_bf16 v[118:121], v[232:235], v[188:191], v[118:121]
	s_waitcnt lgkmcnt(1)
	v_mfma_f32_16x16x32_bf16 v[114:117], v[240:243], v[188:191], v[114:117]
	v_mfma_f32_16x16x32_bf16 v[102:105], v[232:235], v[196:199], v[102:105]
	v_mfma_f32_16x16x32_bf16 v[98:101], v[240:243], v[196:199], v[98:101]
	v_mfma_f32_16x16x32_bf16 v[86:89], v[232:235], v[216:219], v[86:89]
	v_mfma_f32_16x16x32_bf16 v[82:85], v[240:243], v[216:219], v[82:85]
	v_mfma_f32_16x16x32_bf16 v[70:73], v[232:235], v[224:227], v[70:73]
	v_mfma_f32_16x16x32_bf16 v[66:69], v[240:243], v[224:227], v[66:69]
	v_mfma_f32_16x16x32_bf16 v[118:121], v[236:239], v[192:195], v[118:121]
	s_waitcnt lgkmcnt(0)
	v_mfma_f32_16x16x32_bf16 v[114:117], v[244:247], v[192:195], v[114:117]
	v_mfma_f32_16x16x32_bf16 v[102:105], v[236:239], v[200:203], v[102:105]
	v_mfma_f32_16x16x32_bf16 v[98:101], v[244:247], v[200:203], v[98:101]
	v_mfma_f32_16x16x32_bf16 v[86:89], v[236:239], v[220:223], v[86:89]
	v_mfma_f32_16x16x32_bf16 v[82:85], v[244:247], v[220:223], v[82:85]
	v_mfma_f32_16x16x32_bf16 v[70:73], v[236:239], v[228:231], v[70:73]
	v_mfma_f32_16x16x32_bf16 v[66:69], v[244:247], v[228:231], v[66:69]
	s_mov_b32 m0, s58
	v_lshl_add_u64 v[204:205], s[82:83], 0, v[136:137]
	s_barrier
	ds_read_b128 v[188:191], v155 offset:16384
	ds_read_b128 v[192:195], v155 offset:17408
	ds_read_b128 v[196:199], v155 offset:18432
	ds_read_b128 v[200:203], v155 offset:19456
	ds_read_b128 v[216:219], v155 offset:20480
	ds_read_b128 v[220:223], v155 offset:21504
	ds_read_b128 v[224:227], v155 offset:22528
	ds_read_b128 v[228:231], v155 offset:23552
	global_load_lds_dwordx4 v[204:205], off
	v_lshl_add_u64 v[248:249], s[82:83], 0, v[132:133]
	s_mov_b32 m0, s69
	s_nop 0
	global_load_lds_dwordx4 v[248:249], off
	s_barrier
	s_waitcnt lgkmcnt(7)
	v_mfma_f32_16x16x32_bf16 v[62:65], v[142:145], v[188:191], v[62:65]
	v_mfma_f32_16x16x32_bf16 v[58:61], v[156:159], v[188:191], v[58:61]
	s_waitcnt lgkmcnt(5)
	v_mfma_f32_16x16x32_bf16 v[46:49], v[142:145], v[196:199], v[46:49]
	v_mfma_f32_16x16x32_bf16 v[42:45], v[156:159], v[196:199], v[42:45]
	s_waitcnt lgkmcnt(3)
	v_mfma_f32_16x16x32_bf16 v[30:33], v[142:145], v[216:219], v[30:33]
	v_mfma_f32_16x16x32_bf16 v[26:29], v[156:159], v[216:219], v[26:29]
	s_waitcnt lgkmcnt(1)
	v_mfma_f32_16x16x32_bf16 v[14:17], v[142:145], v[224:227], v[14:17]
	v_mfma_f32_16x16x32_bf16 v[10:13], v[156:159], v[224:227], v[10:13]
	v_mfma_f32_16x16x32_bf16 v[62:65], v[146:149], v[192:195], v[62:65]
	v_mfma_f32_16x16x32_bf16 v[58:61], v[160:163], v[192:195], v[58:61]
	v_mfma_f32_16x16x32_bf16 v[46:49], v[146:149], v[200:203], v[46:49]
	v_mfma_f32_16x16x32_bf16 v[42:45], v[160:163], v[200:203], v[42:45]
	v_mfma_f32_16x16x32_bf16 v[30:33], v[146:149], v[220:223], v[30:33]
	v_mfma_f32_16x16x32_bf16 v[26:29], v[160:163], v[220:223], v[26:29]
	s_waitcnt lgkmcnt(0)
	v_mfma_f32_16x16x32_bf16 v[14:17], v[146:149], v[228:231], v[14:17]
	v_mfma_f32_16x16x32_bf16 v[10:13], v[160:163], v[228:231], v[10:13]
	s_barrier
	s_add_u32 s26, s80, 0x20000
	s_addc_u32 s27, s81, 0
	s_add_i32 s2, s17, s3
	v_lshl_add_u64 v[142:143], s[26:27], 0, v[134:135]
	s_mov_b32 m0, s2
	s_nop 0
	global_load_lds_dwordx4 v[142:143], off
	v_lshl_add_u64 v[142:143], s[26:27], 0, v[130:131]
	s_add_i32 m0, s2, 0x2000
	s_nop 0
	global_load_lds_dwordx4 v[142:143], off
	s_waitcnt vmcnt(6)
	s_barrier
	v_mfma_f32_16x16x32_bf16 v[54:57], v[232:235], v[188:191], v[54:57]
	v_mfma_f32_16x16x32_bf16 v[50:53], v[240:243], v[188:191], v[50:53]
	v_mfma_f32_16x16x32_bf16 v[38:41], v[232:235], v[196:199], v[38:41]
	v_mfma_f32_16x16x32_bf16 v[34:37], v[240:243], v[196:199], v[34:37]
	v_mfma_f32_16x16x32_bf16 v[22:25], v[232:235], v[216:219], v[22:25]
	v_mfma_f32_16x16x32_bf16 v[18:21], v[240:243], v[216:219], v[18:21]
	v_mfma_f32_16x16x32_bf16 v[6:9], v[232:235], v[224:227], v[6:9]
	v_mfma_f32_16x16x32_bf16 v[2:5], v[240:243], v[224:227], v[2:5]
	v_mfma_f32_16x16x32_bf16 v[54:57], v[236:239], v[192:195], v[54:57]
	v_mfma_f32_16x16x32_bf16 v[50:53], v[244:247], v[192:195], v[50:53]
	v_mfma_f32_16x16x32_bf16 v[38:41], v[236:239], v[200:203], v[38:41]
	v_mfma_f32_16x16x32_bf16 v[34:37], v[244:247], v[200:203], v[34:37]
	v_mfma_f32_16x16x32_bf16 v[22:25], v[236:239], v[220:223], v[22:25]
	v_mfma_f32_16x16x32_bf16 v[18:21], v[244:247], v[220:223], v[18:21]
	v_mfma_f32_16x16x32_bf16 v[6:9], v[236:239], v[228:231], v[6:9]
	v_mfma_f32_16x16x32_bf16 v[2:5], v[244:247], v[228:231], v[2:5]
	s_add_i32 s2, 0, 0x18000
	v_add_u32_e32 v0, s2, v153
	s_barrier
	ds_read_b128 v[142:145], v0
	ds_read_b128 v[146:149], v0 offset:1024
	ds_read_b128 v[156:159], v0 offset:2048
	ds_read_b128 v[160:163], v0 offset:3072
	s_add_u32 s26, s82, 0xd0000
	s_addc_u32 s27, s83, 0
	s_mov_b32 m0, s92
	v_lshl_add_u64 v[232:233], s[26:27], 0, v[136:137]
	ds_read_b128 v[188:191], v155 offset:32768
	ds_read_b128 v[192:195], v155 offset:33792
	ds_read_b128 v[196:199], v155 offset:34816
	ds_read_b128 v[200:203], v155 offset:35840
	ds_read_b128 v[216:219], v155 offset:36864
	ds_read_b128 v[220:223], v155 offset:37888
	ds_read_b128 v[224:227], v155 offset:38912
	ds_read_b128 v[228:231], v155 offset:39936
	global_load_lds_dwordx4 v[232:233], off
	v_lshl_add_u64 v[232:233], s[26:27], 0, v[132:133]
	s_mov_b32 m0, s93
	s_nop 0
	global_load_lds_dwordx4 v[232:233], off
	s_waitcnt lgkmcnt(8)
	s_barrier
	s_waitcnt lgkmcnt(7)
	v_mfma_f32_16x16x32_bf16 v[126:129], v[142:145], v[188:191], v[126:129]
	v_mfma_f32_16x16x32_bf16 v[122:125], v[156:159], v[188:191], v[122:125]
	s_waitcnt lgkmcnt(5)
	v_mfma_f32_16x16x32_bf16 v[110:113], v[142:145], v[196:199], v[110:113]
	v_mfma_f32_16x16x32_bf16 v[106:109], v[156:159], v[196:199], v[106:109]
	s_waitcnt lgkmcnt(3)
	v_mfma_f32_16x16x32_bf16 v[94:97], v[142:145], v[216:219], v[94:97]
	v_mfma_f32_16x16x32_bf16 v[90:93], v[156:159], v[216:219], v[90:93]
	s_waitcnt lgkmcnt(1)
	v_mfma_f32_16x16x32_bf16 v[78:81], v[142:145], v[224:227], v[78:81]
	v_mfma_f32_16x16x32_bf16 v[74:77], v[156:159], v[224:227], v[74:77]
	s_add_i32 s17, 0, 0x1c000
	v_add_u32_e32 v0, s17, v153
	ds_read_b128 v[232:235], v0
	ds_read_b128 v[236:239], v0 offset:1024
	ds_read_b128 v[240:243], v0 offset:2048
	ds_read_b128 v[244:247], v0 offset:3072
	v_mfma_f32_16x16x32_bf16 v[126:129], v[146:149], v[192:195], v[126:129]
	v_mfma_f32_16x16x32_bf16 v[122:125], v[160:163], v[192:195], v[122:125]
	v_mfma_f32_16x16x32_bf16 v[110:113], v[146:149], v[200:203], v[110:113]
	v_mfma_f32_16x16x32_bf16 v[106:109], v[160:163], v[200:203], v[106:109]
	v_mfma_f32_16x16x32_bf16 v[94:97], v[146:149], v[220:223], v[94:97]
	v_mfma_f32_16x16x32_bf16 v[90:93], v[160:163], v[220:223], v[90:93]
	s_waitcnt lgkmcnt(4)
	v_mfma_f32_16x16x32_bf16 v[78:81], v[146:149], v[228:231], v[78:81]
	v_mfma_f32_16x16x32_bf16 v[74:77], v[160:163], v[228:231], v[74:77]
	s_barrier
	s_add_i32 s2, s2, s3
	v_lshl_add_u64 v[150:151], v[150:151], 0, s[28:29]
	s_mov_b32 m0, s2
	global_load_lds_dwordx4 v[150:151], off
	v_lshl_add_u64 v[150:151], v[164:165], 0, s[28:29]
	s_add_i32 m0, s2, 0x2000
	s_nop 0
	global_load_lds_dwordx4 v[150:151], off
	s_barrier
	s_waitcnt lgkmcnt(3)
	v_mfma_f32_16x16x32_bf16 v[118:121], v[232:235], v[188:191], v[118:121]
	s_waitcnt lgkmcnt(1)
	v_mfma_f32_16x16x32_bf16 v[114:117], v[240:243], v[188:191], v[114:117]
	v_mfma_f32_16x16x32_bf16 v[102:105], v[232:235], v[196:199], v[102:105]
	v_mfma_f32_16x16x32_bf16 v[98:101], v[240:243], v[196:199], v[98:101]
	v_mfma_f32_16x16x32_bf16 v[86:89], v[232:235], v[216:219], v[86:89]
	v_mfma_f32_16x16x32_bf16 v[82:85], v[240:243], v[216:219], v[82:85]
	v_mfma_f32_16x16x32_bf16 v[70:73], v[232:235], v[224:227], v[70:73]
	v_mfma_f32_16x16x32_bf16 v[66:69], v[240:243], v[224:227], v[66:69]
	v_mfma_f32_16x16x32_bf16 v[118:121], v[236:239], v[192:195], v[118:121]
	s_waitcnt lgkmcnt(0)
	v_mfma_f32_16x16x32_bf16 v[114:117], v[244:247], v[192:195], v[114:117]
	v_mfma_f32_16x16x32_bf16 v[102:105], v[236:239], v[200:203], v[102:105]
	v_mfma_f32_16x16x32_bf16 v[98:101], v[244:247], v[200:203], v[98:101]
	v_mfma_f32_16x16x32_bf16 v[86:89], v[236:239], v[220:223], v[86:89]
	v_mfma_f32_16x16x32_bf16 v[82:85], v[244:247], v[220:223], v[82:85]
	v_mfma_f32_16x16x32_bf16 v[70:73], v[236:239], v[228:231], v[70:73]
	v_mfma_f32_16x16x32_bf16 v[66:69], v[244:247], v[228:231], v[66:69]
	s_mov_b32 m0, s72
	v_lshl_add_u64 v[150:151], v[204:205], 0, s[28:29]
	s_barrier
	ds_read_b128 v[188:191], v155 offset:49152
	ds_read_b128 v[192:195], v155 offset:50176
	ds_read_b128 v[196:199], v155 offset:51200
	ds_read_b128 v[200:203], v155 offset:52224
	ds_read_b128 v[216:219], v155 offset:53248
	ds_read_b128 v[220:223], v155 offset:54272
	ds_read_b128 v[224:227], v155 offset:55296
	ds_read_b128 v[228:231], v155 offset:56320
	global_load_lds_dwordx4 v[150:151], off
	v_lshl_add_u64 v[150:151], v[248:249], 0, s[28:29]
	s_mov_b32 m0, s73
	s_nop 0
	global_load_lds_dwordx4 v[150:151], off
	s_barrier
	s_waitcnt lgkmcnt(7)
	v_mfma_f32_16x16x32_bf16 v[62:65], v[142:145], v[188:191], v[62:65]
	v_mfma_f32_16x16x32_bf16 v[58:61], v[156:159], v[188:191], v[58:61]
	s_waitcnt lgkmcnt(5)
	v_mfma_f32_16x16x32_bf16 v[46:49], v[142:145], v[196:199], v[46:49]
	v_mfma_f32_16x16x32_bf16 v[42:45], v[156:159], v[196:199], v[42:45]
	s_waitcnt lgkmcnt(3)
	v_mfma_f32_16x16x32_bf16 v[30:33], v[142:145], v[216:219], v[30:33]
	v_mfma_f32_16x16x32_bf16 v[26:29], v[156:159], v[216:219], v[26:29]
	s_waitcnt lgkmcnt(1)
	v_mfma_f32_16x16x32_bf16 v[14:17], v[142:145], v[224:227], v[14:17]
	v_mfma_f32_16x16x32_bf16 v[10:13], v[156:159], v[224:227], v[10:13]
	v_mfma_f32_16x16x32_bf16 v[62:65], v[146:149], v[192:195], v[62:65]
	v_mfma_f32_16x16x32_bf16 v[58:61], v[160:163], v[192:195], v[58:61]
	v_mfma_f32_16x16x32_bf16 v[46:49], v[146:149], v[200:203], v[46:49]
	v_mfma_f32_16x16x32_bf16 v[42:45], v[160:163], v[200:203], v[42:45]
	v_mfma_f32_16x16x32_bf16 v[30:33], v[146:149], v[220:223], v[30:33]
	v_mfma_f32_16x16x32_bf16 v[26:29], v[160:163], v[220:223], v[26:29]
	s_waitcnt lgkmcnt(0)
	v_mfma_f32_16x16x32_bf16 v[14:17], v[146:149], v[228:231], v[14:17]
	v_mfma_f32_16x16x32_bf16 v[10:13], v[160:163], v[228:231], v[10:13]
	s_barrier
	s_add_u32 s26, s80, 0x20080
	s_addc_u32 s27, s81, 0
	s_add_i32 s2, s17, s3
	v_lshl_add_u64 v[142:143], s[26:27], 0, v[134:135]
	s_mov_b32 m0, s2
	s_nop 0
	global_load_lds_dwordx4 v[142:143], off
	v_lshl_add_u64 v[142:143], s[26:27], 0, v[130:131]
	s_add_i32 m0, s2, 0x2000
	s_nop 0
	global_load_lds_dwordx4 v[142:143], off
	s_waitcnt vmcnt(6)
	s_barrier
	v_mfma_f32_16x16x32_bf16 v[54:57], v[232:235], v[188:191], v[54:57]
	v_mfma_f32_16x16x32_bf16 v[50:53], v[240:243], v[188:191], v[50:53]
	v_mfma_f32_16x16x32_bf16 v[38:41], v[232:235], v[196:199], v[38:41]
	v_mfma_f32_16x16x32_bf16 v[34:37], v[240:243], v[196:199], v[34:37]
	v_mfma_f32_16x16x32_bf16 v[22:25], v[232:235], v[216:219], v[22:25]
	v_mfma_f32_16x16x32_bf16 v[18:21], v[240:243], v[216:219], v[18:21]
	v_mfma_f32_16x16x32_bf16 v[6:9], v[232:235], v[224:227], v[6:9]
	v_mfma_f32_16x16x32_bf16 v[2:5], v[240:243], v[224:227], v[2:5]
	v_mfma_f32_16x16x32_bf16 v[54:57], v[236:239], v[192:195], v[54:57]
	v_mfma_f32_16x16x32_bf16 v[50:53], v[244:247], v[192:195], v[50:53]
	v_mfma_f32_16x16x32_bf16 v[38:41], v[236:239], v[200:203], v[38:41]
	v_mfma_f32_16x16x32_bf16 v[34:37], v[244:247], v[200:203], v[34:37]
	v_mfma_f32_16x16x32_bf16 v[22:25], v[236:239], v[220:223], v[22:25]
	v_mfma_f32_16x16x32_bf16 v[18:21], v[244:247], v[220:223], v[18:21]
	v_mfma_f32_16x16x32_bf16 v[6:9], v[236:239], v[228:231], v[6:9]
	v_mfma_f32_16x16x32_bf16 v[2:5], v[244:247], v[228:231], v[2:5]
	s_add_i32 s44, s44, 2
	s_add_u32 s25, s25, 0x100
	s_addc_u32 s46, s46, 0
	s_cmp_gt_u32 s44, 5
	s_mov_b64 s[78:79], s[6:7]
	s_barrier
	s_cbranch_scc0 .LBB0_433
	v_lshl_add_u32 v144, s41, 8, v152
	v_ashrrev_i32_e32 v145, 31, v144
	v_lshl_add_u64 v[146:147], v[144:145], 2, s[50:51]
	global_load_dword v216, v[146:147], off
	global_load_dword v217, v[146:147], off offset:64
	global_load_dword v218, v[146:147], off offset:128
	global_load_dword v219, v[146:147], off offset:192
	global_load_dword v220, v[146:147], off offset:512
	global_load_dword v221, v[146:147], off offset:576
	global_load_dword v222, v[146:147], off offset:640
	global_load_dword v223, v[146:147], off offset:704
	v_lshl_or_b32 v142, s40, 8, v154
	s_mov_b32 s2, 0x2aaaaaab
	v_mul_hi_i32 v143, v142, s2
	v_lshlrev_b64 v[148:149], 8, v[144:145]
	v_lshrrev_b32_e32 v145, 31, v143
	v_lshrrev_b32_e32 v143, 5, v143
	v_add_u32_e32 v143, v143, v145
	s_movk_i32 s2, 0xc0
	v_mul_lo_u32 v143, v143, s2
	v_sub_u32_e32 v143, v142, v143
	s_movk_i32 s2, 0x7f
	v_cmp_lt_i32_e32 vcc, s2, v143
	v_add_u32_e32 v143, 0xffffff80, v143
	v_lshl_add_u64 v[148:149], s[20:21], 0, v[148:149]
	s_waitcnt vmcnt(0)
	v_mov_b32_e32 v0, v216
	v_mul_f32_e32 v150, 0x3dd53b94, v0
	v_pk_mul_f32 v[128:129], v[128:129], v[150:151] op_sel_hi:[1,0]
	v_pk_mul_f32 v[126:127], v[126:127], v[150:151] op_sel_hi:[1,0]
	v_pk_mul_f32 v[124:125], v[124:125], v[150:151] op_sel_hi:[1,0]
	v_pk_mul_f32 v[122:123], v[122:123], v[150:151] op_sel_hi:[1,0]
	v_lshrrev_b32_e32 v0, 1, v143
	s_and_saveexec_b64 s[6:7], vcc
	s_cbranch_execz .LBB0_436
	v_lshl_add_u64 v[160:161], v[0:1], 3, v[148:149]
	global_load_dwordx4 v[156:159], v[160:161], off offset:16
	s_nop 0
	global_load_dwordx4 v[160:163], v[160:161], off
	s_waitcnt vmcnt(0)
	v_pk_mul_f32 v[190:191], v[122:123], v[156:157] op_sel:[1,1] op_sel_hi:[0,1]
	v_pk_mul_f32 v[188:189], v[126:127], v[160:161] op_sel:[1,1] op_sel_hi:[0,1]
	v_pk_mul_f32 v[164:165], v[126:127], v[160:161]
	v_pk_fma_f32 v[126:127], v[126:127], v[160:161], v[188:189] op_sel_hi:[1,0,1]
	s_nop 0
	v_mul_f32_e32 v126, v129, v163
	v_pk_fma_f32 v[160:161], v[128:129], v[162:163], v[126:127] op_sel_hi:[1,1,0] neg_lo:[0,0,1] neg_hi:[0,0,1]
	v_mul_f32_e32 v126, v128, v163
	v_pk_fma_f32 v[162:163], v[128:129], v[162:163], v[126:127] op_sel:[1,0,0] op_sel_hi:[0,1,0]
	v_pk_mul_f32 v[128:129], v[122:123], v[156:157]
	v_pk_fma_f32 v[122:123], v[122:123], v[156:157], v[190:191] op_sel_hi:[1,0,1]
	v_sub_f32_e32 v126, v164, v188
	v_mul_f32_e32 v122, v125, v159
	v_pk_fma_f32 v[156:157], v[124:125], v[158:159], v[122:123] op_sel_hi:[1,1,0] neg_lo:[0,0,1] neg_hi:[0,0,1]
	v_mul_f32_e32 v122, v124, v159
	v_pk_fma_f32 v[158:159], v[124:125], v[158:159], v[122:123] op_sel:[1,0,0] op_sel_hi:[0,1,0]
	v_sub_f32_e32 v122, v128, v190
	v_mov_b32_e32 v128, v160
	v_mov_b32_e32 v129, v162
	v_mov_b32_e32 v124, v156
	v_mov_b32_e32 v125, v158

.LBB0_482:
	s_add_u32 s10, s80, 0x100
	s_addc_u32 s11, s81, 0
	s_add_i32 s2, 0, 0x10000
	v_add_u32_e32 v156, s2, v145
	ds_read_b128 v[140:143], v156
	ds_read_b128 v[148:151], v156 offset:1024
	ds_read_b128 v[152:155], v156 offset:2048
	ds_read_b128 v[156:159], v156 offset:3072
	s_cmp_eq_u32 s44, 4
	s_cselect_b32 s93, s77, s11
	s_cselect_b32 s92, s76, s10
	s_cselect_b32 s83, s24, s47
	s_cselect_b32 s82, s25, s46
	v_lshl_add_u64 v[164:165], s[80:81], 0, v[136:137]
	s_add_i32 m0, s58, 0xc000
	ds_read_b128 v[160:163], v147
	ds_read_b128 v[188:191], v147 offset:1024
	ds_read_b128 v[192:195], v147 offset:2048
	ds_read_b128 v[196:199], v147 offset:3072
	ds_read_b128 v[200:203], v147 offset:4096
	ds_read_b128 v[216:219], v147 offset:5120
	ds_read_b128 v[220:223], v147 offset:6144
	ds_read_b128 v[224:227], v147 offset:7168
	global_load_lds_dwordx4 v[164:165], off
	v_lshl_add_u64 v[164:165], s[80:81], 0, v[138:139]
	s_add_i32 m0, s58, 0xe000
	s_nop 0
	global_load_lds_dwordx4 v[164:165], off
	s_waitcnt lgkmcnt(8)
	s_barrier
	s_waitcnt lgkmcnt(7)
	v_mfma_f32_16x16x32_bf16 v[126:129], v[140:143], v[160:163], v[126:129]
	v_mfma_f32_16x16x32_bf16 v[122:125], v[152:155], v[160:163], v[122:125]
	s_waitcnt lgkmcnt(5)
	v_mfma_f32_16x16x32_bf16 v[110:113], v[140:143], v[192:195], v[110:113]
	v_mfma_f32_16x16x32_bf16 v[106:109], v[152:155], v[192:195], v[106:109]
	s_waitcnt lgkmcnt(3)
	v_mfma_f32_16x16x32_bf16 v[94:97], v[140:143], v[200:203], v[94:97]
	v_mfma_f32_16x16x32_bf16 v[90:93], v[152:155], v[200:203], v[90:93]
	s_waitcnt lgkmcnt(1)
	v_mfma_f32_16x16x32_bf16 v[78:81], v[140:143], v[220:223], v[78:81]
	v_mfma_f32_16x16x32_bf16 v[74:77], v[152:155], v[220:223], v[74:77]
	s_add_i32 s17, 0, 0x14000
	v_add_u32_e32 v164, s17, v145
	ds_read_b128 v[228:231], v164
	ds_read_b128 v[232:235], v164 offset:1024
	ds_read_b128 v[236:239], v164 offset:2048
	ds_read_b128 v[240:243], v164 offset:3072
	v_mfma_f32_16x16x32_bf16 v[126:129], v[148:151], v[188:191], v[126:129]
	v_mfma_f32_16x16x32_bf16 v[122:125], v[156:159], v[188:191], v[122:125]
	v_mfma_f32_16x16x32_bf16 v[110:113], v[148:151], v[196:199], v[110:113]
	v_mfma_f32_16x16x32_bf16 v[106:109], v[156:159], v[196:199], v[106:109]
	v_mfma_f32_16x16x32_bf16 v[94:97], v[148:151], v[216:219], v[94:97]
	v_mfma_f32_16x16x32_bf16 v[90:93], v[156:159], v[216:219], v[90:93]
	s_waitcnt lgkmcnt(4)
	v_mfma_f32_16x16x32_bf16 v[78:81], v[148:151], v[224:227], v[78:81]
	v_mfma_f32_16x16x32_bf16 v[74:77], v[156:159], v[224:227], v[74:77]
	s_barrier
	s_add_i32 s2, s2, s3
	v_lshl_add_u64 v[164:165], s[82:83], 0, v[0:1]
	s_mov_b32 m0, s2
	v_lshl_add_u64 v[204:205], s[82:83], 0, v[130:131]
	global_load_lds_dwordx4 v[164:165], off
	s_add_i32 m0, s2, 0x2000
	s_nop 0
	global_load_lds_dwordx4 v[204:205], off
	s_barrier
	s_waitcnt lgkmcnt(3)
	v_mfma_f32_16x16x32_bf16 v[118:121], v[228:231], v[160:163], v[118:121]
	s_waitcnt lgkmcnt(1)
	v_mfma_f32_16x16x32_bf16 v[114:117], v[236:239], v[160:163], v[114:117]
	v_mfma_f32_16x16x32_bf16 v[102:105], v[228:231], v[192:195], v[102:105]
	v_mfma_f32_16x16x32_bf16 v[98:101], v[236:239], v[192:195], v[98:101]
	v_mfma_f32_16x16x32_bf16 v[86:89], v[228:231], v[200:203], v[86:89]
	v_mfma_f32_16x16x32_bf16 v[82:85], v[236:239], v[200:203], v[82:85]
	v_mfma_f32_16x16x32_bf16 v[70:73], v[228:231], v[220:223], v[70:73]
	v_mfma_f32_16x16x32_bf16 v[66:69], v[236:239], v[220:223], v[66:69]
	v_mfma_f32_16x16x32_bf16 v[118:121], v[232:235], v[188:191], v[118:121]
	s_waitcnt lgkmcnt(0)
	v_mfma_f32_16x16x32_bf16 v[114:117], v[240:243], v[188:191], v[114:117]
	v_mfma_f32_16x16x32_bf16 v[102:105], v[232:235], v[196:199], v[102:105]
	v_mfma_f32_16x16x32_bf16 v[98:101], v[240:243], v[196:199], v[98:101]
	v_mfma_f32_16x16x32_bf16 v[86:89], v[232:235], v[216:219], v[86:89]
	v_mfma_f32_16x16x32_bf16 v[82:85], v[240:243], v[216:219], v[82:85]
	v_mfma_f32_16x16x32_bf16 v[70:73], v[232:235], v[224:227], v[70:73]
	v_mfma_f32_16x16x32_bf16 v[66:69], v[240:243], v[224:227], v[66:69]
	s_mov_b32 m0, s58
	v_lshl_add_u64 v[244:245], s[92:93], 0, v[134:135]
	s_barrier
	ds_read_b128 v[160:163], v147 offset:16384
	ds_read_b128 v[188:191], v147 offset:17408
	ds_read_b128 v[192:195], v147 offset:18432
	ds_read_b128 v[196:199], v147 offset:19456
	ds_read_b128 v[200:203], v147 offset:20480
	ds_read_b128 v[216:219], v147 offset:21504
	ds_read_b128 v[220:223], v147 offset:22528
	ds_read_b128 v[224:227], v147 offset:23552
	global_load_lds_dwordx4 v[244:245], off
	v_lshl_add_u64 v[246:247], s[92:93], 0, v[132:133]
	s_mov_b32 m0, s69
	s_nop 0
	global_load_lds_dwordx4 v[246:247], off
	s_barrier
	s_waitcnt lgkmcnt(7)
	v_mfma_f32_16x16x32_bf16 v[62:65], v[140:143], v[160:163], v[62:65]
	v_mfma_f32_16x16x32_bf16 v[58:61], v[152:155], v[160:163], v[58:61]
	s_waitcnt lgkmcnt(5)
	v_mfma_f32_16x16x32_bf16 v[46:49], v[140:143], v[192:195], v[46:49]
	v_mfma_f32_16x16x32_bf16 v[42:45], v[152:155], v[192:195], v[42:45]
	s_waitcnt lgkmcnt(3)
	v_mfma_f32_16x16x32_bf16 v[30:33], v[140:143], v[200:203], v[30:33]
	v_mfma_f32_16x16x32_bf16 v[26:29], v[152:155], v[200:203], v[26:29]
	s_waitcnt lgkmcnt(1)
	v_mfma_f32_16x16x32_bf16 v[14:17], v[140:143], v[220:223], v[14:17]
	v_mfma_f32_16x16x32_bf16 v[10:13], v[152:155], v[220:223], v[10:13]
	v_mfma_f32_16x16x32_bf16 v[62:65], v[148:151], v[188:191], v[62:65]
	v_mfma_f32_16x16x32_bf16 v[58:61], v[156:159], v[188:191], v[58:61]
	v_mfma_f32_16x16x32_bf16 v[46:49], v[148:151], v[196:199], v[46:49]
	v_mfma_f32_16x16x32_bf16 v[42:45], v[156:159], v[196:199], v[42:45]
	v_mfma_f32_16x16x32_bf16 v[30:33], v[148:151], v[216:219], v[30:33]
	v_mfma_f32_16x16x32_bf16 v[26:29], v[156:159], v[216:219], v[26:29]
	s_waitcnt lgkmcnt(0)
	v_mfma_f32_16x16x32_bf16 v[14:17], v[148:151], v[224:227], v[14:17]
	v_mfma_f32_16x16x32_bf16 v[10:13], v[156:159], v[224:227], v[10:13]
	s_barrier
	s_add_u32 s26, s82, 0x20000
	s_addc_u32 s27, s83, 0
	s_add_i32 s2, s17, s3
	v_lshl_add_u64 v[140:141], s[26:27], 0, v[0:1]
	s_mov_b32 m0, s2
	s_nop 0
	global_load_lds_dwordx4 v[140:141], off
	v_lshl_add_u64 v[140:141], s[26:27], 0, v[130:131]
	s_add_i32 m0, s2, 0x2000
	s_nop 0
	global_load_lds_dwordx4 v[140:141], off
	s_waitcnt vmcnt(6)
	s_barrier
	v_mfma_f32_16x16x32_bf16 v[54:57], v[228:231], v[160:163], v[54:57]
	v_mfma_f32_16x16x32_bf16 v[50:53], v[236:239], v[160:163], v[50:53]
	v_mfma_f32_16x16x32_bf16 v[38:41], v[228:231], v[192:195], v[38:41]
	v_mfma_f32_16x16x32_bf16 v[34:37], v[236:239], v[192:195], v[34:37]
	v_mfma_f32_16x16x32_bf16 v[22:25], v[228:231], v[200:203], v[22:25]
	v_mfma_f32_16x16x32_bf16 v[18:21], v[236:239], v[200:203], v[18:21]
	v_mfma_f32_16x16x32_bf16 v[6:9], v[228:231], v[220:223], v[6:9]
	v_mfma_f32_16x16x32_bf16 v[2:5], v[236:239], v[220:223], v[2:5]
	v_mfma_f32_16x16x32_bf16 v[54:57], v[232:235], v[188:191], v[54:57]
	v_mfma_f32_16x16x32_bf16 v[50:53], v[240:243], v[188:191], v[50:53]
	v_mfma_f32_16x16x32_bf16 v[38:41], v[232:235], v[196:199], v[38:41]
	v_mfma_f32_16x16x32_bf16 v[34:37], v[240:243], v[196:199], v[34:37]
	v_mfma_f32_16x16x32_bf16 v[22:25], v[232:235], v[216:219], v[22:25]
	v_mfma_f32_16x16x32_bf16 v[18:21], v[240:243], v[216:219], v[18:21]
	v_mfma_f32_16x16x32_bf16 v[6:9], v[232:235], v[224:227], v[6:9]
	v_mfma_f32_16x16x32_bf16 v[2:5], v[240:243], v[224:227], v[2:5]
	s_add_i32 s2, 0, 0x18000
	v_add_u32_e32 v156, s2, v145
	s_barrier
	ds_read_b128 v[140:143], v156
	ds_read_b128 v[148:151], v156 offset:1024
	ds_read_b128 v[152:155], v156 offset:2048
	ds_read_b128 v[156:159], v156 offset:3072
	s_add_u32 s26, s92, 0xd0000
	s_addc_u32 s27, s93, 0
	s_mov_b32 m0, s70
	v_lshl_add_u64 v[228:229], s[26:27], 0, v[134:135]
	ds_read_b128 v[160:163], v147 offset:32768
	ds_read_b128 v[188:191], v147 offset:33792
	ds_read_b128 v[192:195], v147 offset:34816
	ds_read_b128 v[196:199], v147 offset:35840
	ds_read_b128 v[200:203], v147 offset:36864
	ds_read_b128 v[216:219], v147 offset:37888
	ds_read_b128 v[220:223], v147 offset:38912
	ds_read_b128 v[224:227], v147 offset:39936
	global_load_lds_dwordx4 v[228:229], off
	v_lshl_add_u64 v[228:229], s[26:27], 0, v[132:133]
	s_mov_b32 m0, s71
	s_nop 0
	global_load_lds_dwordx4 v[228:229], off
	s_waitcnt lgkmcnt(8)
	s_barrier
	s_waitcnt lgkmcnt(7)
	v_mfma_f32_16x16x32_bf16 v[126:129], v[140:143], v[160:163], v[126:129]
	v_mfma_f32_16x16x32_bf16 v[122:125], v[152:155], v[160:163], v[122:125]
	s_waitcnt lgkmcnt(5)
	v_mfma_f32_16x16x32_bf16 v[110:113], v[140:143], v[192:195], v[110:113]
	v_mfma_f32_16x16x32_bf16 v[106:109], v[152:155], v[192:195], v[106:109]
	s_waitcnt lgkmcnt(3)
	v_mfma_f32_16x16x32_bf16 v[94:97], v[140:143], v[200:203], v[94:97]
	v_mfma_f32_16x16x32_bf16 v[90:93], v[152:155], v[200:203], v[90:93]
	s_waitcnt lgkmcnt(1)
	v_mfma_f32_16x16x32_bf16 v[78:81], v[140:143], v[220:223], v[78:81]
	v_mfma_f32_16x16x32_bf16 v[74:77], v[152:155], v[220:223], v[74:77]
	s_add_i32 s17, 0, 0x1c000
	v_add_u32_e32 v206, s17, v145
	ds_read_b128 v[228:231], v206
	ds_read_b128 v[232:235], v206 offset:1024
	ds_read_b128 v[236:239], v206 offset:2048
	ds_read_b128 v[240:243], v206 offset:3072
	v_mfma_f32_16x16x32_bf16 v[126:129], v[148:151], v[188:191], v[126:129]
	v_mfma_f32_16x16x32_bf16 v[122:125], v[156:159], v[188:191], v[122:125]
	v_mfma_f32_16x16x32_bf16 v[110:113], v[148:151], v[196:199], v[110:113]
	v_mfma_f32_16x16x32_bf16 v[106:109], v[156:159], v[196:199], v[106:109]
	v_mfma_f32_16x16x32_bf16 v[94:97], v[148:151], v[216:219], v[94:97]
	v_mfma_f32_16x16x32_bf16 v[90:93], v[156:159], v[216:219], v[90:93]
	s_waitcnt lgkmcnt(4)
	v_mfma_f32_16x16x32_bf16 v[78:81], v[148:151], v[224:227], v[78:81]
	v_mfma_f32_16x16x32_bf16 v[74:77], v[156:159], v[224:227], v[74:77]
	s_barrier
	s_add_i32 s2, s2, s3
	v_lshl_add_u64 v[164:165], v[164:165], 0, s[28:29]
	s_mov_b32 m0, s2
	global_load_lds_dwordx4 v[164:165], off
	v_lshl_add_u64 v[164:165], v[204:205], 0, s[28:29]
	s_add_i32 m0, s2, 0x2000
	s_nop 0
	global_load_lds_dwordx4 v[164:165], off
	s_barrier
	s_waitcnt lgkmcnt(3)
	v_mfma_f32_16x16x32_bf16 v[118:121], v[228:231], v[160:163], v[118:121]
	s_waitcnt lgkmcnt(1)
	v_mfma_f32_16x16x32_bf16 v[114:117], v[236:239], v[160:163], v[114:117]
	v_mfma_f32_16x16x32_bf16 v[102:105], v[228:231], v[192:195], v[102:105]
	v_mfma_f32_16x16x32_bf16 v[98:101], v[236:239], v[192:195], v[98:101]
	v_mfma_f32_16x16x32_bf16 v[86:89], v[228:231], v[200:203], v[86:89]
	v_mfma_f32_16x16x32_bf16 v[82:85], v[236:239], v[200:203], v[82:85]
	v_mfma_f32_16x16x32_bf16 v[70:73], v[228:231], v[220:223], v[70:73]
	v_mfma_f32_16x16x32_bf16 v[66:69], v[236:239], v[220:223], v[66:69]
	v_mfma_f32_16x16x32_bf16 v[118:121], v[232:235], v[188:191], v[118:121]
	s_waitcnt lgkmcnt(0)
	v_mfma_f32_16x16x32_bf16 v[114:117], v[240:243], v[188:191], v[114:117]
	v_mfma_f32_16x16x32_bf16 v[102:105], v[232:235], v[196:199], v[102:105]
	v_mfma_f32_16x16x32_bf16 v[98:101], v[240:243], v[196:199], v[98:101]
	v_mfma_f32_16x16x32_bf16 v[86:89], v[232:235], v[216:219], v[86:89]
	v_mfma_f32_16x16x32_bf16 v[82:85], v[240:243], v[216:219], v[82:85]
	v_mfma_f32_16x16x32_bf16 v[70:73], v[232:235], v[224:227], v[70:73]
	v_mfma_f32_16x16x32_bf16 v[66:69], v[240:243], v[224:227], v[66:69]
	s_mov_b32 m0, s72
	v_lshl_add_u64 v[164:165], v[244:245], 0, s[28:29]
	s_barrier
	ds_read_b128 v[160:163], v147 offset:49152
	ds_read_b128 v[188:191], v147 offset:50176
	ds_read_b128 v[192:195], v147 offset:51200
	ds_read_b128 v[196:199], v147 offset:52224
	ds_read_b128 v[200:203], v147 offset:53248
	ds_read_b128 v[216:219], v147 offset:54272
	ds_read_b128 v[220:223], v147 offset:55296
	ds_read_b128 v[224:227], v147 offset:56320
	global_load_lds_dwordx4 v[164:165], off
	v_lshl_add_u64 v[164:165], v[246:247], 0, s[28:29]
	s_mov_b32 m0, s73
	s_nop 0
	global_load_lds_dwordx4 v[164:165], off
	s_barrier
	s_waitcnt lgkmcnt(7)
	v_mfma_f32_16x16x32_bf16 v[62:65], v[140:143], v[160:163], v[62:65]
	v_mfma_f32_16x16x32_bf16 v[58:61], v[152:155], v[160:163], v[58:61]
	s_waitcnt lgkmcnt(5)
	v_mfma_f32_16x16x32_bf16 v[46:49], v[140:143], v[192:195], v[46:49]
	v_mfma_f32_16x16x32_bf16 v[42:45], v[152:155], v[192:195], v[42:45]
	s_waitcnt lgkmcnt(3)
	v_mfma_f32_16x16x32_bf16 v[30:33], v[140:143], v[200:203], v[30:33]
	v_mfma_f32_16x16x32_bf16 v[26:29], v[152:155], v[200:203], v[26:29]
	s_waitcnt lgkmcnt(1)
	v_mfma_f32_16x16x32_bf16 v[14:17], v[140:143], v[220:223], v[14:17]
	v_mfma_f32_16x16x32_bf16 v[10:13], v[152:155], v[220:223], v[10:13]
	v_mfma_f32_16x16x32_bf16 v[62:65], v[148:151], v[188:191], v[62:65]
	v_mfma_f32_16x16x32_bf16 v[58:61], v[156:159], v[188:191], v[58:61]
	v_mfma_f32_16x16x32_bf16 v[46:49], v[148:151], v[196:199], v[46:49]
	v_mfma_f32_16x16x32_bf16 v[42:45], v[156:159], v[196:199], v[42:45]
	v_mfma_f32_16x16x32_bf16 v[30:33], v[148:151], v[216:219], v[30:33]
	v_mfma_f32_16x16x32_bf16 v[26:29], v[156:159], v[216:219], v[26:29]
	s_waitcnt lgkmcnt(0)
	v_mfma_f32_16x16x32_bf16 v[14:17], v[148:151], v[224:227], v[14:17]
	v_mfma_f32_16x16x32_bf16 v[10:13], v[156:159], v[224:227], v[10:13]
	s_barrier
	s_add_u32 s26, s82, 0x20080
	s_addc_u32 s27, s83, 0
	s_add_i32 s2, s17, s3
	v_lshl_add_u64 v[140:141], s[26:27], 0, v[0:1]
	s_mov_b32 m0, s2
	s_nop 0
	global_load_lds_dwordx4 v[140:141], off
	v_lshl_add_u64 v[140:141], s[26:27], 0, v[130:131]
	s_add_i32 m0, s2, 0x2000
	s_nop 0
	global_load_lds_dwordx4 v[140:141], off
	s_waitcnt vmcnt(6)
	s_barrier
	v_mfma_f32_16x16x32_bf16 v[54:57], v[228:231], v[160:163], v[54:57]
	v_mfma_f32_16x16x32_bf16 v[50:53], v[236:239], v[160:163], v[50:53]
	v_mfma_f32_16x16x32_bf16 v[38:41], v[228:231], v[192:195], v[38:41]
	v_mfma_f32_16x16x32_bf16 v[34:37], v[236:239], v[192:195], v[34:37]
	v_mfma_f32_16x16x32_bf16 v[22:25], v[228:231], v[200:203], v[22:25]
	v_mfma_f32_16x16x32_bf16 v[18:21], v[236:239], v[200:203], v[18:21]
	v_mfma_f32_16x16x32_bf16 v[6:9], v[228:231], v[220:223], v[6:9]
	v_mfma_f32_16x16x32_bf16 v[2:5], v[236:239], v[220:223], v[2:5]
	v_mfma_f32_16x16x32_bf16 v[54:57], v[232:235], v[188:191], v[54:57]
	v_mfma_f32_16x16x32_bf16 v[50:53], v[240:243], v[188:191], v[50:53]
	v_mfma_f32_16x16x32_bf16 v[38:41], v[232:235], v[196:199], v[38:41]
	v_mfma_f32_16x16x32_bf16 v[34:37], v[240:243], v[196:199], v[34:37]
	v_mfma_f32_16x16x32_bf16 v[22:25], v[232:235], v[216:219], v[22:25]
	v_mfma_f32_16x16x32_bf16 v[18:21], v[240:243], v[216:219], v[18:21]
	v_mfma_f32_16x16x32_bf16 v[6:9], v[232:235], v[224:227], v[6:9]
	v_mfma_f32_16x16x32_bf16 v[2:5], v[240:243], v[224:227], v[2:5]
	s_add_i32 s44, s44, 2
	s_add_u32 s46, s46, 0x100
	s_addc_u32 s47, s47, 0
	s_cmp_gt_u32 s44, 5
	s_mov_b64 s[80:81], s[10:11]
	s_barrier
	s_cbranch_scc0 .LBB0_482
	v_lshl_add_u32 v142, s63, 8, v144
	v_ashrrev_i32_e32 v143, 31, v142
	v_lshl_add_u64 v[140:141], v[142:143], 2, s[38:39]
	global_load_dword v216, v[140:141], off
	global_load_dword v218, v[140:141], off offset:64
	global_load_dword v220, v[140:141], off offset:128
	global_load_dword v222, v[140:141], off offset:192
	global_load_dword v224, v[140:141], off offset:512
	global_load_dword v226, v[140:141], off offset:576
	global_load_dword v228, v[140:141], off offset:640
	global_load_dword v230, v[140:141], off offset:704
	v_lshl_or_b32 v148, s62, 8, v146
	v_ashrrev_i32_e32 v149, 31, v148
	s_mov_b32 s2, 0x80000
	s_mov_b64 s[4:5], 0x80000
	s_mov_b32 s62, s74
	s_mov_b32 s63, s41
	s_mov_b64 s[82:83], s[78:79]
	s_mov_b64 s[80:81], s[76:77]
	v_readlane_b32 s93, v251, 60
	s_waitcnt vmcnt(7)
	v_mov_b32_e32 v150, v216
	v_pk_mul_f32 v[128:129], v[128:129], v[150:151] op_sel_hi:[1,0]
	v_pk_mul_f32 v[126:127], v[126:127], v[150:151] op_sel_hi:[1,0]
	v_pk_mul_f32 v[122:123], v[122:123], v[150:151] op_sel_hi:[1,0]
	v_pk_mul_f32 v[124:125], v[124:125], v[150:151] op_sel_hi:[1,0]
	v_cvt_pk_bf16_f32 v126, v126, v127
	v_cvt_pk_bf16_f32 v127, v128, v129
	v_cvt_pk_bf16_f32 v128, v122, v123
	v_lshlrev_b64 v[122:123], 12, v[142:143]
	v_cvt_pk_bf16_f32 v129, v124, v125
	v_lshl_add_u64 v[122:123], s[56:57], 0, v[122:123]
	v_lshlrev_b64 v[124:125], 1, v[148:149]
	v_lshl_add_u64 v[122:123], v[122:123], 0, v[124:125]
	global_store_dwordx4 v[122:123], v[126:129], off
	v_pk_mul_f32 v[120:121], v[120:121], v[150:151] op_sel_hi:[1,0]
	v_pk_mul_f32 v[118:119], v[118:119], v[150:151] op_sel_hi:[1,0]
	v_pk_mul_f32 v[126:127], v[116:117], v[150:151] op_sel_hi:[1,0]
	v_pk_mul_f32 v[116:117], v[114:115], v[150:151] op_sel_hi:[1,0]
	v_cvt_pk_bf16_f32 v114, v118, v119
	v_cvt_pk_bf16_f32 v115, v120, v121
	v_cvt_pk_bf16_f32 v116, v116, v117
	v_cvt_pk_bf16_f32 v117, v126, v127
	global_store_dwordx4 v[122:123], v[114:117], off offset:256
	s_nop 1
	v_or_b32_e32 v114, 16, v142
	v_ashrrev_i32_e32 v115, 31, v114
	v_lshl_add_u64 v[116:117], v[114:115], 2, s[38:39]
	s_waitcnt vmcnt(8)
	v_mov_b32_e32 v116, v218
	v_pk_mul_f32 v[110:111], v[110:111], v[116:117] op_sel_hi:[1,0]
	v_pk_mul_f32 v[118:119], v[108:109], v[116:117] op_sel_hi:[1,0]
	v_pk_mul_f32 v[108:109], v[106:107], v[116:117] op_sel_hi:[1,0]
	v_cvt_pk_bf16_f32 v106, v110, v111
	v_lshlrev_b64 v[110:111], 12, v[114:115]
	v_pk_mul_f32 v[112:113], v[112:113], v[116:117] op_sel_hi:[1,0]
	v_lshl_add_u64 v[110:111], s[56:57], 0, v[110:111]
	v_cvt_pk_bf16_f32 v107, v112, v113
	v_cvt_pk_bf16_f32 v108, v108, v109
	v_cvt_pk_bf16_f32 v109, v118, v119
	v_lshl_add_u64 v[110:111], v[110:111], 0, v[124:125]
	global_store_dwordx4 v[110:111], v[106:109], off
	v_pk_mul_f32 v[104:105], v[104:105], v[116:117] op_sel_hi:[1,0]
	v_pk_mul_f32 v[102:103], v[102:103], v[116:117] op_sel_hi:[1,0]
	v_pk_mul_f32 v[106:107], v[100:101], v[116:117] op_sel_hi:[1,0]
	v_pk_mul_f32 v[100:101], v[98:99], v[116:117] op_sel_hi:[1,0]
	v_cvt_pk_bf16_f32 v98, v102, v103
	v_cvt_pk_bf16_f32 v99, v104, v105
	v_cvt_pk_bf16_f32 v100, v100, v101
	v_cvt_pk_bf16_f32 v101, v106, v107
	global_store_dwordx4 v[110:111], v[98:101], off offset:256
	s_nop 1
	v_or_b32_e32 v98, 32, v142
	v_ashrrev_i32_e32 v99, 31, v98
	v_lshl_add_u64 v[100:101], v[98:99], 2, s[38:39]
	s_waitcnt vmcnt(9)
	v_mov_b32_e32 v100, v220
	v_pk_mul_f32 v[94:95], v[94:95], v[100:101] op_sel_hi:[1,0]
	v_pk_mul_f32 v[102:103], v[92:93], v[100:101] op_sel_hi:[1,0]
	v_pk_mul_f32 v[92:93], v[90:91], v[100:101] op_sel_hi:[1,0]
	v_cvt_pk_bf16_f32 v90, v94, v95
	v_lshlrev_b64 v[94:95], 12, v[98:99]
	v_pk_mul_f32 v[96:97], v[96:97], v[100:101] op_sel_hi:[1,0]
	v_lshl_add_u64 v[94:95], s[56:57], 0, v[94:95]
	v_cvt_pk_bf16_f32 v91, v96, v97
	v_cvt_pk_bf16_f32 v92, v92, v93
	v_cvt_pk_bf16_f32 v93, v102, v103
	v_lshl_add_u64 v[94:95], v[94:95], 0, v[124:125]
	global_store_dwordx4 v[94:95], v[90:93], off
	v_pk_mul_f32 v[88:89], v[88:89], v[100:101] op_sel_hi:[1,0]
	v_pk_mul_f32 v[86:87], v[86:87], v[100:101] op_sel_hi:[1,0]
	v_pk_mul_f32 v[90:91], v[84:85], v[100:101] op_sel_hi:[1,0]
	v_pk_mul_f32 v[84:85], v[82:83], v[100:101] op_sel_hi:[1,0]
	v_cvt_pk_bf16_f32 v82, v86, v87
	v_cvt_pk_bf16_f32 v83, v88, v89
	v_cvt_pk_bf16_f32 v84, v84, v85
	v_cvt_pk_bf16_f32 v85, v90, v91
	global_store_dwordx4 v[94:95], v[82:85], off offset:256
	s_nop 1
	v_or_b32_e32 v82, 48, v142
	v_ashrrev_i32_e32 v83, 31, v82
	v_lshl_add_u64 v[84:85], v[82:83], 2, s[38:39]
	s_waitcnt vmcnt(10)
	v_mov_b32_e32 v84, v222
	v_pk_mul_f32 v[78:79], v[78:79], v[84:85] op_sel_hi:[1,0]
	v_pk_mul_f32 v[86:87], v[76:77], v[84:85] op_sel_hi:[1,0]
	v_pk_mul_f32 v[76:77], v[74:75], v[84:85] op_sel_hi:[1,0]
	v_cvt_pk_bf16_f32 v74, v78, v79
	v_lshlrev_b64 v[78:79], 12, v[82:83]
	v_pk_mul_f32 v[80:81], v[80:81], v[84:85] op_sel_hi:[1,0]
	v_lshl_add_u64 v[78:79], s[56:57], 0, v[78:79]
	v_cvt_pk_bf16_f32 v75, v80, v81
	v_cvt_pk_bf16_f32 v76, v76, v77
	v_cvt_pk_bf16_f32 v77, v86, v87
	v_lshl_add_u64 v[78:79], v[78:79], 0, v[124:125]
	global_store_dwordx4 v[78:79], v[74:77], off
	v_pk_mul_f32 v[72:73], v[72:73], v[84:85] op_sel_hi:[1,0]
	v_pk_mul_f32 v[70:71], v[70:71], v[84:85] op_sel_hi:[1,0]
	v_pk_mul_f32 v[74:75], v[68:69], v[84:85] op_sel_hi:[1,0]
	v_pk_mul_f32 v[68:69], v[66:67], v[84:85] op_sel_hi:[1,0]
	v_cvt_pk_bf16_f32 v66, v70, v71
	v_cvt_pk_bf16_f32 v67, v72, v73
	v_cvt_pk_bf16_f32 v68, v68, v69
	v_cvt_pk_bf16_f32 v69, v74, v75
	global_store_dwordx4 v[78:79], v[66:69], off offset:256
	s_waitcnt vmcnt(11)
	v_mov_b32_e32 v66, v224
	v_pk_mul_f32 v[64:65], v[64:65], v[66:67] op_sel_hi:[1,0]
	v_pk_mul_f32 v[62:63], v[62:63], v[66:67] op_sel_hi:[1,0]
	v_pk_mul_f32 v[68:69], v[60:61], v[66:67] op_sel_hi:[1,0]
	v_pk_mul_f32 v[60:61], v[58:59], v[66:67] op_sel_hi:[1,0]
	v_cvt_pk_bf16_f32 v59, v64, v65
	v_add_co_u32_e32 v64, vcc, s2, v122
	v_cvt_pk_bf16_f32 v58, v62, v63
	v_cvt_pk_bf16_f32 v60, v60, v61
	v_cvt_pk_bf16_f32 v61, v68, v69
	v_addc_co_u32_e32 v65, vcc, 0, v123, vcc
	global_store_dwordx4 v[64:65], v[58:61], off
	v_pk_mul_f32 v[56:57], v[56:57], v[66:67] op_sel_hi:[1,0]
	v_pk_mul_f32 v[54:55], v[54:55], v[66:67] op_sel_hi:[1,0]
	v_pk_mul_f32 v[58:59], v[52:53], v[66:67] op_sel_hi:[1,0]
	v_pk_mul_f32 v[52:53], v[50:51], v[66:67] op_sel_hi:[1,0]
	v_lshl_add_u64 v[62:63], v[122:123], 0, s[4:5]
	v_cvt_pk_bf16_f32 v50, v54, v55
	v_cvt_pk_bf16_f32 v51, v56, v57
	v_cvt_pk_bf16_f32 v52, v52, v53
	v_cvt_pk_bf16_f32 v53, v58, v59
	global_store_dwordx4 v[62:63], v[50:53], off offset:256
	s_mov_b32 s2, 0x90000
	s_mov_b64 s[4:5], 0x90000
	s_waitcnt vmcnt(12)
	v_mov_b32_e32 v50, v226
	v_pk_mul_f32 v[48:49], v[48:49], v[50:51] op_sel_hi:[1,0]
	v_pk_mul_f32 v[46:47], v[46:47], v[50:51] op_sel_hi:[1,0]
	v_pk_mul_f32 v[52:53], v[44:45], v[50:51] op_sel_hi:[1,0]
	v_pk_mul_f32 v[44:45], v[42:43], v[50:51] op_sel_hi:[1,0]
	v_cvt_pk_bf16_f32 v43, v48, v49
	v_add_co_u32_e32 v48, vcc, s2, v122
	v_cvt_pk_bf16_f32 v42, v46, v47
	v_cvt_pk_bf16_f32 v44, v44, v45
	v_cvt_pk_bf16_f32 v45, v52, v53
	v_addc_co_u32_e32 v49, vcc, 0, v123, vcc
	global_store_dwordx4 v[48:49], v[42:45], off
	v_pk_mul_f32 v[40:41], v[40:41], v[50:51] op_sel_hi:[1,0]
	v_pk_mul_f32 v[38:39], v[38:39], v[50:51] op_sel_hi:[1,0]
	v_pk_mul_f32 v[42:43], v[36:37], v[50:51] op_sel_hi:[1,0]
	v_pk_mul_f32 v[36:37], v[34:35], v[50:51] op_sel_hi:[1,0]
	v_lshl_add_u64 v[46:47], v[122:123], 0, s[4:5]
	v_cvt_pk_bf16_f32 v34, v38, v39
	v_cvt_pk_bf16_f32 v35, v40, v41
	v_cvt_pk_bf16_f32 v36, v36, v37
	v_cvt_pk_bf16_f32 v37, v42, v43
	global_store_dwordx4 v[46:47], v[34:37], off offset:256
	s_mov_b32 s2, 0xa0000
	s_mov_b64 s[4:5], 0xa0000
	s_waitcnt vmcnt(13)
	v_mov_b32_e32 v34, v228
	v_pk_mul_f32 v[32:33], v[32:33], v[34:35] op_sel_hi:[1,0]
	v_pk_mul_f32 v[30:31], v[30:31], v[34:35] op_sel_hi:[1,0]
	v_pk_mul_f32 v[36:37], v[28:29], v[34:35] op_sel_hi:[1,0]
	v_pk_mul_f32 v[28:29], v[26:27], v[34:35] op_sel_hi:[1,0]
	v_cvt_pk_bf16_f32 v27, v32, v33
	v_add_co_u32_e32 v32, vcc, s2, v122
	v_cvt_pk_bf16_f32 v26, v30, v31
	v_cvt_pk_bf16_f32 v28, v28, v29
	v_cvt_pk_bf16_f32 v29, v36, v37
	v_addc_co_u32_e32 v33, vcc, 0, v123, vcc
	global_store_dwordx4 v[32:33], v[26:29], off
	v_pk_mul_f32 v[24:25], v[24:25], v[34:35] op_sel_hi:[1,0]
	v_pk_mul_f32 v[22:23], v[22:23], v[34:35] op_sel_hi:[1,0]
	v_pk_mul_f32 v[26:27], v[20:21], v[34:35] op_sel_hi:[1,0]
	v_pk_mul_f32 v[20:21], v[18:19], v[34:35] op_sel_hi:[1,0]
	v_lshl_add_u64 v[30:31], v[122:123], 0, s[4:5]
	v_cvt_pk_bf16_f32 v18, v22, v23
	v_cvt_pk_bf16_f32 v19, v24, v25
	v_cvt_pk_bf16_f32 v20, v20, v21
	v_cvt_pk_bf16_f32 v21, v26, v27
	global_store_dwordx4 v[30:31], v[18:21], off offset:256
	s_mov_b32 s2, 0xb0000
	s_mov_b64 s[4:5], 0xb0000
	s_waitcnt vmcnt(14)
	v_mov_b32_e32 v18, v230
	v_pk_mul_f32 v[16:17], v[16:17], v[18:19] op_sel_hi:[1,0]
	v_pk_mul_f32 v[14:15], v[14:15], v[18:19] op_sel_hi:[1,0]
	v_pk_mul_f32 v[20:21], v[12:13], v[18:19] op_sel_hi:[1,0]
	v_pk_mul_f32 v[12:13], v[10:11], v[18:19] op_sel_hi:[1,0]
	v_cvt_pk_bf16_f32 v11, v16, v17
	v_add_co_u32_e32 v16, vcc, s2, v122
	v_cvt_pk_bf16_f32 v10, v14, v15
	v_cvt_pk_bf16_f32 v12, v12, v13
	v_cvt_pk_bf16_f32 v13, v20, v21
	v_addc_co_u32_e32 v17, vcc, 0, v123, vcc
	global_store_dwordx4 v[16:17], v[10:13], off
	v_pk_mul_f32 v[8:9], v[8:9], v[18:19] op_sel_hi:[1,0]
	v_pk_mul_f32 v[6:7], v[6:7], v[18:19] op_sel_hi:[1,0]
	v_pk_mul_f32 v[10:11], v[4:5], v[18:19] op_sel_hi:[1,0]
	v_pk_mul_f32 v[4:5], v[2:3], v[18:19] op_sel_hi:[1,0]
	v_lshl_add_u64 v[14:15], v[122:123], 0, s[4:5]
	v_cvt_pk_bf16_f32 v2, v6, v7
	v_cvt_pk_bf16_f32 v3, v8, v9
	v_cvt_pk_bf16_f32 v4, v4, v5
	v_cvt_pk_bf16_f32 v5, v10, v11
	s_and_b64 vcc, exec, s[6:7]
	global_store_dwordx4 v[14:15], v[2:5], off offset:256
	s_cbranch_vccz .LBB0_473
	v_readlane_b32 s4, v254, 12
	s_waitcnt vmcnt(0)
	v_readlane_b32 s5, v254, 13
	v_readlane_b32 s84, v251, 38
	v_readlane_b32 s18, v253, 0
	s_andn2_b64 vcc, exec, s[4:5]
	v_readlane_b32 s85, v251, 39
	v_readlane_b32 s86, v251, 40
	v_readlane_b32 s87, v251, 41
	v_readlane_b32 s14, v250, 63
	v_readlane_b32 s19, v253, 1
	s_cbranch_vccnz .LBB0_486
	s_barrier

.LBB0_500:
	s_add_u32 s2, s6, 0xfffe0080
	s_addc_u32 s17, s7, -1
	s_add_i32 s26, 0, 0x10000
	v_add_u32_e32 v156, s26, v145
	ds_read_b128 v[140:143], v156
	ds_read_b128 v[148:151], v156 offset:1024
	ds_read_b128 v[152:155], v156 offset:2048
	ds_read_b128 v[156:159], v156 offset:3072
	s_cmp_eq_u32 s44, 4
	s_cselect_b32 s81, s11, s17
	s_cselect_b32 s80, s24, s2
	s_cselect_b32 s79, s75, s46
	s_cselect_b32 s78, s74, s25
	v_lshl_add_u64 v[164:165], s[6:7], 0, v[136:137]
	s_add_i32 m0, s58, 0xc000
	ds_read_b128 v[160:163], v147
	ds_read_b128 v[188:191], v147 offset:1024
	ds_read_b128 v[192:195], v147 offset:2048
	ds_read_b128 v[196:199], v147 offset:3072
	ds_read_b128 v[200:203], v147 offset:4096
	ds_read_b128 v[216:219], v147 offset:5120
	ds_read_b128 v[220:223], v147 offset:6144
	ds_read_b128 v[224:227], v147 offset:7168
	global_load_lds_dwordx4 v[164:165], off
	v_lshl_add_u64 v[164:165], s[6:7], 0, v[138:139]
	s_add_i32 m0, s58, 0xe000
	s_nop 0
	global_load_lds_dwordx4 v[164:165], off
	s_waitcnt lgkmcnt(8)
	s_barrier
	s_waitcnt lgkmcnt(7)
	v_mfma_f32_16x16x32_bf16 v[126:129], v[140:143], v[160:163], v[126:129]
	v_mfma_f32_16x16x32_bf16 v[122:125], v[152:155], v[160:163], v[122:125]
	s_waitcnt lgkmcnt(5)
	v_mfma_f32_16x16x32_bf16 v[110:113], v[140:143], v[192:195], v[110:113]
	v_mfma_f32_16x16x32_bf16 v[106:109], v[152:155], v[192:195], v[106:109]
	s_waitcnt lgkmcnt(3)
	v_mfma_f32_16x16x32_bf16 v[94:97], v[140:143], v[200:203], v[94:97]
	v_mfma_f32_16x16x32_bf16 v[90:93], v[152:155], v[200:203], v[90:93]
	s_waitcnt lgkmcnt(1)
	v_mfma_f32_16x16x32_bf16 v[78:81], v[140:143], v[220:223], v[78:81]
	v_mfma_f32_16x16x32_bf16 v[74:77], v[152:155], v[220:223], v[74:77]
	s_add_i32 s2, 0, 0x14000
	v_add_u32_e32 v164, s2, v145
	ds_read_b128 v[228:231], v164
	ds_read_b128 v[232:235], v164 offset:1024
	ds_read_b128 v[236:239], v164 offset:2048
	ds_read_b128 v[240:243], v164 offset:3072
	v_mfma_f32_16x16x32_bf16 v[126:129], v[148:151], v[188:191], v[126:129]
	v_mfma_f32_16x16x32_bf16 v[122:125], v[156:159], v[188:191], v[122:125]
	v_mfma_f32_16x16x32_bf16 v[110:113], v[148:151], v[196:199], v[110:113]
	v_mfma_f32_16x16x32_bf16 v[106:109], v[156:159], v[196:199], v[106:109]
	v_mfma_f32_16x16x32_bf16 v[94:97], v[148:151], v[216:219], v[94:97]
	v_mfma_f32_16x16x32_bf16 v[90:93], v[156:159], v[216:219], v[90:93]
	s_waitcnt lgkmcnt(4)
	v_mfma_f32_16x16x32_bf16 v[78:81], v[148:151], v[224:227], v[78:81]
	v_mfma_f32_16x16x32_bf16 v[74:77], v[156:159], v[224:227], v[74:77]
	s_barrier
	s_add_i32 s17, s26, s3
	v_lshl_add_u64 v[164:165], s[78:79], 0, v[0:1]
	s_mov_b32 m0, s17
	v_lshl_add_u64 v[204:205], s[78:79], 0, v[130:131]
	global_load_lds_dwordx4 v[164:165], off
	s_add_i32 m0, s17, 0x2000
	s_nop 0
	global_load_lds_dwordx4 v[204:205], off
	s_barrier
	s_waitcnt lgkmcnt(3)
	v_mfma_f32_16x16x32_bf16 v[118:121], v[228:231], v[160:163], v[118:121]
	s_waitcnt lgkmcnt(1)
	v_mfma_f32_16x16x32_bf16 v[114:117], v[236:239], v[160:163], v[114:117]
	v_mfma_f32_16x16x32_bf16 v[102:105], v[228:231], v[192:195], v[102:105]
	v_mfma_f32_16x16x32_bf16 v[98:101], v[236:239], v[192:195], v[98:101]
	v_mfma_f32_16x16x32_bf16 v[86:89], v[228:231], v[200:203], v[86:89]
	v_mfma_f32_16x16x32_bf16 v[82:85], v[236:239], v[200:203], v[82:85]
	v_mfma_f32_16x16x32_bf16 v[70:73], v[228:231], v[220:223], v[70:73]
	v_mfma_f32_16x16x32_bf16 v[66:69], v[236:239], v[220:223], v[66:69]
	v_mfma_f32_16x16x32_bf16 v[118:121], v[232:235], v[188:191], v[118:121]
	s_waitcnt lgkmcnt(0)
	v_mfma_f32_16x16x32_bf16 v[114:117], v[240:243], v[188:191], v[114:117]
	v_mfma_f32_16x16x32_bf16 v[102:105], v[232:235], v[196:199], v[102:105]
	v_mfma_f32_16x16x32_bf16 v[98:101], v[240:243], v[196:199], v[98:101]
	v_mfma_f32_16x16x32_bf16 v[86:89], v[232:235], v[216:219], v[86:89]
	v_mfma_f32_16x16x32_bf16 v[82:85], v[240:243], v[216:219], v[82:85]
	v_mfma_f32_16x16x32_bf16 v[70:73], v[232:235], v[224:227], v[70:73]
	v_mfma_f32_16x16x32_bf16 v[66:69], v[240:243], v[224:227], v[66:69]
	s_mov_b32 m0, s58
	v_lshl_add_u64 v[244:245], s[80:81], 0, v[134:135]
	s_barrier
	ds_read_b128 v[160:163], v147 offset:16384
	ds_read_b128 v[188:191], v147 offset:17408
	ds_read_b128 v[192:195], v147 offset:18432
	ds_read_b128 v[196:199], v147 offset:19456
	ds_read_b128 v[200:203], v147 offset:20480
	ds_read_b128 v[216:219], v147 offset:21504
	ds_read_b128 v[220:223], v147 offset:22528
	ds_read_b128 v[224:227], v147 offset:23552
	global_load_lds_dwordx4 v[244:245], off
	v_lshl_add_u64 v[246:247], s[80:81], 0, v[132:133]
	s_mov_b32 m0, s69
	s_nop 0
	global_load_lds_dwordx4 v[246:247], off
	s_barrier
	s_waitcnt lgkmcnt(7)
	v_mfma_f32_16x16x32_bf16 v[62:65], v[140:143], v[160:163], v[62:65]
	v_mfma_f32_16x16x32_bf16 v[58:61], v[152:155], v[160:163], v[58:61]
	s_waitcnt lgkmcnt(5)
	v_mfma_f32_16x16x32_bf16 v[54:57], v[140:143], v[192:195], v[54:57]
	v_mfma_f32_16x16x32_bf16 v[46:49], v[152:155], v[192:195], v[46:49]
	s_waitcnt lgkmcnt(3)
	v_mfma_f32_16x16x32_bf16 v[38:41], v[140:143], v[200:203], v[38:41]
	v_mfma_f32_16x16x32_bf16 v[30:33], v[152:155], v[200:203], v[30:33]
	s_waitcnt lgkmcnt(1)
	v_mfma_f32_16x16x32_bf16 v[22:25], v[140:143], v[220:223], v[22:25]
	v_mfma_f32_16x16x32_bf16 v[14:17], v[152:155], v[220:223], v[14:17]
	v_mfma_f32_16x16x32_bf16 v[62:65], v[148:151], v[188:191], v[62:65]
	v_mfma_f32_16x16x32_bf16 v[58:61], v[156:159], v[188:191], v[58:61]
	v_mfma_f32_16x16x32_bf16 v[54:57], v[148:151], v[196:199], v[54:57]
	v_mfma_f32_16x16x32_bf16 v[46:49], v[156:159], v[196:199], v[46:49]
	v_mfma_f32_16x16x32_bf16 v[38:41], v[148:151], v[216:219], v[38:41]
	v_mfma_f32_16x16x32_bf16 v[30:33], v[156:159], v[216:219], v[30:33]
	s_waitcnt lgkmcnt(0)
	v_mfma_f32_16x16x32_bf16 v[22:25], v[148:151], v[224:227], v[22:25]
	v_mfma_f32_16x16x32_bf16 v[14:17], v[156:159], v[224:227], v[14:17]
	s_barrier
	s_add_u32 s26, s78, 0xd0000
	s_addc_u32 s27, s79, 0
	s_add_i32 s2, s2, s3
	v_lshl_add_u64 v[140:141], s[26:27], 0, v[0:1]
	s_mov_b32 m0, s2
	s_nop 0
	global_load_lds_dwordx4 v[140:141], off
	v_lshl_add_u64 v[140:141], s[26:27], 0, v[130:131]
	s_add_i32 m0, s2, 0x2000
	s_nop 0
	global_load_lds_dwordx4 v[140:141], off
	s_waitcnt vmcnt(6)
	s_barrier
	v_mfma_f32_16x16x32_bf16 v[50:53], v[228:231], v[160:163], v[50:53]
	v_mfma_f32_16x16x32_bf16 v[42:45], v[236:239], v[160:163], v[42:45]
	v_mfma_f32_16x16x32_bf16 v[34:37], v[228:231], v[192:195], v[34:37]
	v_mfma_f32_16x16x32_bf16 v[26:29], v[236:239], v[192:195], v[26:29]
	v_mfma_f32_16x16x32_bf16 v[18:21], v[228:231], v[200:203], v[18:21]
	v_mfma_f32_16x16x32_bf16 v[10:13], v[236:239], v[200:203], v[10:13]
	v_mfma_f32_16x16x32_bf16 v[6:9], v[228:231], v[220:223], v[6:9]
	v_mfma_f32_16x16x32_bf16 v[2:5], v[236:239], v[220:223], v[2:5]
	v_mfma_f32_16x16x32_bf16 v[50:53], v[232:235], v[188:191], v[50:53]
	v_mfma_f32_16x16x32_bf16 v[42:45], v[240:243], v[188:191], v[42:45]
	v_mfma_f32_16x16x32_bf16 v[34:37], v[232:235], v[196:199], v[34:37]
	v_mfma_f32_16x16x32_bf16 v[26:29], v[240:243], v[196:199], v[26:29]
	v_mfma_f32_16x16x32_bf16 v[18:21], v[232:235], v[216:219], v[18:21]
	v_mfma_f32_16x16x32_bf16 v[10:13], v[240:243], v[216:219], v[10:13]
	v_mfma_f32_16x16x32_bf16 v[6:9], v[232:235], v[224:227], v[6:9]
	v_mfma_f32_16x16x32_bf16 v[2:5], v[240:243], v[224:227], v[2:5]
	s_add_i32 s2, 0, 0x18000
	v_add_u32_e32 v156, s2, v145
	s_barrier
	ds_read_b128 v[140:143], v156
	ds_read_b128 v[148:151], v156 offset:1024
	ds_read_b128 v[152:155], v156 offset:2048
	ds_read_b128 v[156:159], v156 offset:3072
	s_add_u32 s26, s80, 0x20000
	s_addc_u32 s27, s81, 0
	s_mov_b32 m0, s70
	v_lshl_add_u64 v[228:229], s[26:27], 0, v[134:135]
	ds_read_b128 v[160:163], v147 offset:32768
	ds_read_b128 v[188:191], v147 offset:33792
	ds_read_b128 v[192:195], v147 offset:34816
	ds_read_b128 v[196:199], v147 offset:35840
	ds_read_b128 v[200:203], v147 offset:36864
	ds_read_b128 v[216:219], v147 offset:37888
	ds_read_b128 v[220:223], v147 offset:38912
	ds_read_b128 v[224:227], v147 offset:39936
	global_load_lds_dwordx4 v[228:229], off
	v_lshl_add_u64 v[228:229], s[26:27], 0, v[132:133]
	s_mov_b32 m0, s71
	s_nop 0
	global_load_lds_dwordx4 v[228:229], off
	s_waitcnt lgkmcnt(8)
	s_barrier
	s_waitcnt lgkmcnt(7)
	v_mfma_f32_16x16x32_bf16 v[126:129], v[140:143], v[160:163], v[126:129]
	v_mfma_f32_16x16x32_bf16 v[122:125], v[152:155], v[160:163], v[122:125]
	s_waitcnt lgkmcnt(5)
	v_mfma_f32_16x16x32_bf16 v[110:113], v[140:143], v[192:195], v[110:113]
	v_mfma_f32_16x16x32_bf16 v[106:109], v[152:155], v[192:195], v[106:109]
	s_waitcnt lgkmcnt(3)
	v_mfma_f32_16x16x32_bf16 v[94:97], v[140:143], v[200:203], v[94:97]
	v_mfma_f32_16x16x32_bf16 v[90:93], v[152:155], v[200:203], v[90:93]
	s_waitcnt lgkmcnt(1)
	v_mfma_f32_16x16x32_bf16 v[78:81], v[140:143], v[220:223], v[78:81]
	v_mfma_f32_16x16x32_bf16 v[74:77], v[152:155], v[220:223], v[74:77]
	s_add_i32 s17, 0, 0x1c000
	v_add_u32_e32 v206, s17, v145
	ds_read_b128 v[228:231], v206
	ds_read_b128 v[232:235], v206 offset:1024
	ds_read_b128 v[236:239], v206 offset:2048
	ds_read_b128 v[240:243], v206 offset:3072
	v_mfma_f32_16x16x32_bf16 v[126:129], v[148:151], v[188:191], v[126:129]
	v_mfma_f32_16x16x32_bf16 v[122:125], v[156:159], v[188:191], v[122:125]
	v_mfma_f32_16x16x32_bf16 v[110:113], v[148:151], v[196:199], v[110:113]
	v_mfma_f32_16x16x32_bf16 v[106:109], v[156:159], v[196:199], v[106:109]
	v_mfma_f32_16x16x32_bf16 v[94:97], v[148:151], v[216:219], v[94:97]
	v_mfma_f32_16x16x32_bf16 v[90:93], v[156:159], v[216:219], v[90:93]
	s_waitcnt lgkmcnt(4)
	v_mfma_f32_16x16x32_bf16 v[78:81], v[148:151], v[224:227], v[78:81]
	v_mfma_f32_16x16x32_bf16 v[74:77], v[156:159], v[224:227], v[74:77]
	s_barrier
	s_add_i32 s2, s2, s3
	v_lshl_add_u64 v[164:165], v[164:165], 0, s[28:29]
	s_mov_b32 m0, s2
	global_load_lds_dwordx4 v[164:165], off
	v_lshl_add_u64 v[164:165], v[204:205], 0, s[28:29]
	s_add_i32 m0, s2, 0x2000
	s_nop 0
	global_load_lds_dwordx4 v[164:165], off
	s_barrier
	s_waitcnt lgkmcnt(3)
	v_mfma_f32_16x16x32_bf16 v[118:121], v[228:231], v[160:163], v[118:121]
	s_waitcnt lgkmcnt(1)
	v_mfma_f32_16x16x32_bf16 v[114:117], v[236:239], v[160:163], v[114:117]
	v_mfma_f32_16x16x32_bf16 v[102:105], v[228:231], v[192:195], v[102:105]
	v_mfma_f32_16x16x32_bf16 v[98:101], v[236:239], v[192:195], v[98:101]
	v_mfma_f32_16x16x32_bf16 v[86:89], v[228:231], v[200:203], v[86:89]
	v_mfma_f32_16x16x32_bf16 v[82:85], v[236:239], v[200:203], v[82:85]
	v_mfma_f32_16x16x32_bf16 v[70:73], v[228:231], v[220:223], v[70:73]
	v_mfma_f32_16x16x32_bf16 v[66:69], v[236:239], v[220:223], v[66:69]
	v_mfma_f32_16x16x32_bf16 v[118:121], v[232:235], v[188:191], v[118:121]
	s_waitcnt lgkmcnt(0)
	v_mfma_f32_16x16x32_bf16 v[114:117], v[240:243], v[188:191], v[114:117]
	v_mfma_f32_16x16x32_bf16 v[102:105], v[232:235], v[196:199], v[102:105]
	v_mfma_f32_16x16x32_bf16 v[98:101], v[240:243], v[196:199], v[98:101]
	v_mfma_f32_16x16x32_bf16 v[86:89], v[232:235], v[216:219], v[86:89]
	v_mfma_f32_16x16x32_bf16 v[82:85], v[240:243], v[216:219], v[82:85]
	v_mfma_f32_16x16x32_bf16 v[70:73], v[232:235], v[224:227], v[70:73]
	v_mfma_f32_16x16x32_bf16 v[66:69], v[240:243], v[224:227], v[66:69]
	s_mov_b32 m0, s72
	v_lshl_add_u64 v[164:165], v[244:245], 0, s[28:29]
	s_barrier
	ds_read_b128 v[160:163], v147 offset:49152
	ds_read_b128 v[188:191], v147 offset:50176
	ds_read_b128 v[192:195], v147 offset:51200
	ds_read_b128 v[196:199], v147 offset:52224
	ds_read_b128 v[200:203], v147 offset:53248
	ds_read_b128 v[216:219], v147 offset:54272
	ds_read_b128 v[220:223], v147 offset:55296
	ds_read_b128 v[224:227], v147 offset:56320
	global_load_lds_dwordx4 v[164:165], off
	v_lshl_add_u64 v[164:165], v[246:247], 0, s[28:29]
	s_mov_b32 m0, s73
	s_nop 0
	global_load_lds_dwordx4 v[164:165], off
	s_barrier
	s_waitcnt lgkmcnt(7)
	v_mfma_f32_16x16x32_bf16 v[62:65], v[140:143], v[160:163], v[62:65]
	v_mfma_f32_16x16x32_bf16 v[58:61], v[152:155], v[160:163], v[58:61]
	s_waitcnt lgkmcnt(5)
	v_mfma_f32_16x16x32_bf16 v[54:57], v[140:143], v[192:195], v[54:57]
	v_mfma_f32_16x16x32_bf16 v[46:49], v[152:155], v[192:195], v[46:49]
	s_waitcnt lgkmcnt(3)
	v_mfma_f32_16x16x32_bf16 v[38:41], v[140:143], v[200:203], v[38:41]
	v_mfma_f32_16x16x32_bf16 v[30:33], v[152:155], v[200:203], v[30:33]
	s_waitcnt lgkmcnt(1)
	v_mfma_f32_16x16x32_bf16 v[22:25], v[140:143], v[220:223], v[22:25]
	v_mfma_f32_16x16x32_bf16 v[14:17], v[152:155], v[220:223], v[14:17]
	v_mfma_f32_16x16x32_bf16 v[62:65], v[148:151], v[188:191], v[62:65]
	v_mfma_f32_16x16x32_bf16 v[58:61], v[156:159], v[188:191], v[58:61]
	v_mfma_f32_16x16x32_bf16 v[54:57], v[148:151], v[196:199], v[54:57]
	v_mfma_f32_16x16x32_bf16 v[46:49], v[156:159], v[196:199], v[46:49]
	v_mfma_f32_16x16x32_bf16 v[38:41], v[148:151], v[216:219], v[38:41]
	v_mfma_f32_16x16x32_bf16 v[30:33], v[156:159], v[216:219], v[30:33]
	s_waitcnt lgkmcnt(0)
	v_mfma_f32_16x16x32_bf16 v[22:25], v[148:151], v[224:227], v[22:25]
	v_mfma_f32_16x16x32_bf16 v[14:17], v[156:159], v[224:227], v[14:17]
	s_barrier
	s_add_u32 s26, s78, 0xd0080
	s_addc_u32 s27, s79, 0
	s_add_i32 s2, s17, s3
	v_lshl_add_u64 v[140:141], s[26:27], 0, v[0:1]
	s_mov_b32 m0, s2
	s_nop 0
	global_load_lds_dwordx4 v[140:141], off
	v_lshl_add_u64 v[140:141], s[26:27], 0, v[130:131]
	s_add_i32 m0, s2, 0x2000
	s_nop 0
	global_load_lds_dwordx4 v[140:141], off
	s_waitcnt vmcnt(6)
	s_barrier
	v_mfma_f32_16x16x32_bf16 v[50:53], v[228:231], v[160:163], v[50:53]
	v_mfma_f32_16x16x32_bf16 v[42:45], v[236:239], v[160:163], v[42:45]
	v_mfma_f32_16x16x32_bf16 v[34:37], v[228:231], v[192:195], v[34:37]
	v_mfma_f32_16x16x32_bf16 v[26:29], v[236:239], v[192:195], v[26:29]
	v_mfma_f32_16x16x32_bf16 v[18:21], v[228:231], v[200:203], v[18:21]
	v_mfma_f32_16x16x32_bf16 v[10:13], v[236:239], v[200:203], v[10:13]
	v_mfma_f32_16x16x32_bf16 v[6:9], v[228:231], v[220:223], v[6:9]
	v_mfma_f32_16x16x32_bf16 v[2:5], v[236:239], v[220:223], v[2:5]
	v_mfma_f32_16x16x32_bf16 v[50:53], v[232:235], v[188:191], v[50:53]
	v_mfma_f32_16x16x32_bf16 v[42:45], v[240:243], v[188:191], v[42:45]
	v_mfma_f32_16x16x32_bf16 v[34:37], v[232:235], v[196:199], v[34:37]
	v_mfma_f32_16x16x32_bf16 v[26:29], v[240:243], v[196:199], v[26:29]
	v_mfma_f32_16x16x32_bf16 v[18:21], v[232:235], v[216:219], v[18:21]
	v_mfma_f32_16x16x32_bf16 v[10:13], v[240:243], v[216:219], v[10:13]
	v_mfma_f32_16x16x32_bf16 v[6:9], v[232:235], v[224:227], v[6:9]
	v_mfma_f32_16x16x32_bf16 v[2:5], v[240:243], v[224:227], v[2:5]
	s_add_i32 s44, s44, 2
	s_add_u32 s6, s6, 0x100
	s_addc_u32 s7, s7, 0
	s_add_u32 s25, s25, 0x100
	s_addc_u32 s46, s46, 0
	s_cmp_gt_u32 s44, 5
	s_barrier
	s_cbranch_scc0 .LBB0_500
	v_lshl_or_b32 v156, s62, 8, v146
	v_ashrrev_i32_e32 v157, 31, v156
	v_lshl_add_u64 v[140:141], v[156:157], 2, s[38:39]
	global_load_dwordx4 v[200:203], v[140:141], off offset:16
	global_load_dwordx4 v[220:223], v[140:141], off
	global_load_dwordx4 v[228:231], v[140:141], off offset:528
	global_load_dwordx4 v[236:239], v[140:141], off offset:512
	v_lshl_add_u32 v142, s63, 8, v144
	v_ashrrev_i32_e32 v143, 31, v142
	s_mov_b32 s2, 0x400000
	s_mov_b64 s[6:7], 0x400000
	s_mov_b32 s62, s41
	s_mov_b32 s63, s10
	s_mov_b64 s[78:79], s[74:75]
	s_mov_b64 s[80:81], s[76:77]
	s_waitcnt vmcnt(0)
	v_mov_b32_e32 v148, v200
	v_mov_b32_e32 v149, v201
	v_mov_b32_e32 v150, v202
	v_mov_b32_e32 v151, v203
	v_mov_b32_e32 v152, v220
	v_mov_b32_e32 v153, v221
	v_mov_b32_e32 v154, v222
	v_mov_b32_e32 v155, v223
	v_pk_mul_f32 v[122:123], v[122:123], v[148:149]
	v_pk_mul_f32 v[126:127], v[126:127], v[152:153]
	v_pk_mul_f32 v[124:125], v[124:125], v[150:151]
	v_cvt_pk_bf16_f32 v150, v122, v123
	v_lshlrev_b64 v[122:123], 15, v[142:143]
	v_pk_mul_f32 v[128:129], v[128:129], v[154:155]
	v_cvt_pk_bf16_f32 v148, v126, v127
	v_cvt_pk_bf16_f32 v151, v124, v125
	v_lshl_add_u64 v[122:123], s[60:61], 0, v[122:123]
	v_lshlrev_b64 v[126:127], 1, v[156:157]
	v_or_b32_e32 v124, 0x80, v156
	v_cvt_pk_bf16_f32 v149, v128, v129
	v_lshl_add_u64 v[122:123], v[122:123], 0, v[126:127]
	v_ashrrev_i32_e32 v125, 31, v124
	global_store_dwordx4 v[122:123], v[148:151], off
	v_lshl_add_u64 v[124:125], v[124:125], 2, s[38:39]
	s_nop 1
	v_mov_b32_e32 v148, v228
	v_mov_b32_e32 v149, v229
	v_mov_b32_e32 v150, v230
	v_mov_b32_e32 v151, v231
	s_nop 1
	v_mov_b32_e32 v152, v236
	v_mov_b32_e32 v153, v237
	v_mov_b32_e32 v154, v238
	v_mov_b32_e32 v155, v239
	s_nop 0
	v_pk_mul_f32 v[128:129], v[116:117], v[150:151]
	v_pk_mul_f32 v[120:121], v[120:121], v[154:155]
	v_pk_mul_f32 v[118:119], v[118:119], v[152:153]
	v_pk_mul_f32 v[116:117], v[114:115], v[148:149]
	v_cvt_pk_bf16_f32 v114, v118, v119
	v_cvt_pk_bf16_f32 v115, v120, v121
	v_cvt_pk_bf16_f32 v116, v116, v117
	v_cvt_pk_bf16_f32 v117, v128, v129
	global_store_dwordx4 v[122:123], v[114:117], off offset:256
	s_nop 1
	v_mov_b32_e32 v114, v200
	v_mov_b32_e32 v115, v201
	v_mov_b32_e32 v116, v202
	v_mov_b32_e32 v117, v203
	s_nop 0
	s_nop 1
	v_mov_b32_e32 v118, v220
	v_mov_b32_e32 v119, v221
	v_mov_b32_e32 v120, v222
	v_mov_b32_e32 v121, v223
	v_or_b32_e32 v128, 16, v142
	v_ashrrev_i32_e32 v129, 31, v128
	s_nop 0
	v_pk_mul_f32 v[116:117], v[108:109], v[116:117]
	v_pk_mul_f32 v[110:111], v[110:111], v[118:119]
	v_pk_mul_f32 v[108:109], v[106:107], v[114:115]
	v_cvt_pk_bf16_f32 v106, v110, v111
	v_lshlrev_b64 v[110:111], 15, v[128:129]
	v_pk_mul_f32 v[112:113], v[112:113], v[120:121]
	v_lshl_add_u64 v[110:111], s[60:61], 0, v[110:111]
	v_cvt_pk_bf16_f32 v107, v112, v113
	v_cvt_pk_bf16_f32 v108, v108, v109
	v_cvt_pk_bf16_f32 v109, v116, v117
	v_lshl_add_u64 v[114:115], v[110:111], 0, v[126:127]
	global_store_dwordx4 v[114:115], v[106:109], off
	s_nop 1
	v_mov_b32_e32 v106, v228
	v_mov_b32_e32 v107, v229
	v_mov_b32_e32 v108, v230
	v_mov_b32_e32 v109, v231
	s_nop 0
	s_nop 1
	v_mov_b32_e32 v110, v236
	v_mov_b32_e32 v111, v237
	v_mov_b32_e32 v112, v238
	v_mov_b32_e32 v113, v239
	s_nop 0
	v_pk_mul_f32 v[108:109], v[100:101], v[108:109]
	v_pk_mul_f32 v[104:105], v[104:105], v[112:113]
	v_pk_mul_f32 v[102:103], v[102:103], v[110:111]
	v_pk_mul_f32 v[100:101], v[98:99], v[106:107]
	v_cvt_pk_bf16_f32 v98, v102, v103
	v_cvt_pk_bf16_f32 v99, v104, v105
	v_cvt_pk_bf16_f32 v100, v100, v101
	v_cvt_pk_bf16_f32 v101, v108, v109
	global_store_dwordx4 v[114:115], v[98:101], off offset:256
	s_nop 1
	v_mov_b32_e32 v98, v200
	v_mov_b32_e32 v99, v201
	v_mov_b32_e32 v100, v202
	v_mov_b32_e32 v101, v203
	s_nop 0
	s_nop 1
	v_mov_b32_e32 v102, v220
	v_mov_b32_e32 v103, v221
	v_mov_b32_e32 v104, v222
	v_mov_b32_e32 v105, v223
	v_or_b32_e32 v106, 32, v142
	v_ashrrev_i32_e32 v107, 31, v106
	s_nop 0
	v_pk_mul_f32 v[100:101], v[92:93], v[100:101]
	v_pk_mul_f32 v[94:95], v[94:95], v[102:103]
	v_pk_mul_f32 v[92:93], v[90:91], v[98:99]
	v_cvt_pk_bf16_f32 v90, v94, v95
	v_lshlrev_b64 v[94:95], 15, v[106:107]
	v_pk_mul_f32 v[96:97], v[96:97], v[104:105]
	v_lshl_add_u64 v[94:95], s[60:61], 0, v[94:95]
	v_cvt_pk_bf16_f32 v91, v96, v97
	v_cvt_pk_bf16_f32 v92, v92, v93
	v_cvt_pk_bf16_f32 v93, v100, v101
	v_lshl_add_u64 v[98:99], v[94:95], 0, v[126:127]
	global_store_dwordx4 v[98:99], v[90:93], off
	s_nop 1
	v_mov_b32_e32 v90, v228
	v_mov_b32_e32 v91, v229
	v_mov_b32_e32 v92, v230
	v_mov_b32_e32 v93, v231
	s_nop 0
	s_nop 1
	v_mov_b32_e32 v94, v236
	v_mov_b32_e32 v95, v237
	v_mov_b32_e32 v96, v238
	v_mov_b32_e32 v97, v239
	s_nop 0
	v_pk_mul_f32 v[92:93], v[84:85], v[92:93]
	v_pk_mul_f32 v[88:89], v[88:89], v[96:97]
	v_pk_mul_f32 v[86:87], v[86:87], v[94:95]
	v_pk_mul_f32 v[84:85], v[82:83], v[90:91]
	v_cvt_pk_bf16_f32 v82, v86, v87
	v_cvt_pk_bf16_f32 v83, v88, v89
	v_cvt_pk_bf16_f32 v84, v84, v85
	v_cvt_pk_bf16_f32 v85, v92, v93
	global_store_dwordx4 v[98:99], v[82:85], off offset:256
	s_nop 1
	v_mov_b32_e32 v82, v200
	v_mov_b32_e32 v83, v201
	v_mov_b32_e32 v84, v202
	v_mov_b32_e32 v85, v203
	s_nop 0
	s_nop 1
	v_mov_b32_e32 v86, v220
	v_mov_b32_e32 v87, v221
	v_mov_b32_e32 v88, v222
	v_mov_b32_e32 v89, v223
	v_or_b32_e32 v90, 48, v142
	v_ashrrev_i32_e32 v91, 31, v90
	s_nop 0
	v_pk_mul_f32 v[84:85], v[76:77], v[84:85]
	v_pk_mul_f32 v[78:79], v[78:79], v[86:87]
	v_pk_mul_f32 v[76:77], v[74:75], v[82:83]
	v_cvt_pk_bf16_f32 v74, v78, v79
	v_lshlrev_b64 v[78:79], 15, v[90:91]
	v_pk_mul_f32 v[80:81], v[80:81], v[88:89]
	v_lshl_add_u64 v[78:79], s[60:61], 0, v[78:79]
	v_cvt_pk_bf16_f32 v75, v80, v81
	v_cvt_pk_bf16_f32 v76, v76, v77
	v_cvt_pk_bf16_f32 v77, v84, v85
	v_lshl_add_u64 v[82:83], v[78:79], 0, v[126:127]
	global_store_dwordx4 v[82:83], v[74:77], off
	s_nop 1
	v_mov_b32_e32 v74, v228
	v_mov_b32_e32 v75, v229
	v_mov_b32_e32 v76, v230
	v_mov_b32_e32 v77, v231
	s_nop 0
	s_nop 1
	v_mov_b32_e32 v78, v236
	v_mov_b32_e32 v79, v237
	v_mov_b32_e32 v80, v238
	v_mov_b32_e32 v81, v239
	s_nop 0
	v_pk_mul_f32 v[76:77], v[68:69], v[76:77]
	v_pk_mul_f32 v[72:73], v[72:73], v[80:81]
	v_pk_mul_f32 v[70:71], v[70:71], v[78:79]
	v_pk_mul_f32 v[68:69], v[66:67], v[74:75]
	v_cvt_pk_bf16_f32 v66, v70, v71
	v_cvt_pk_bf16_f32 v67, v72, v73
	v_cvt_pk_bf16_f32 v68, v68, v69
	v_cvt_pk_bf16_f32 v69, v76, v77
	global_store_dwordx4 v[82:83], v[66:69], off offset:256
	s_nop 1
	v_mov_b32_e32 v66, v200
	v_mov_b32_e32 v67, v201
	v_mov_b32_e32 v68, v202
	v_mov_b32_e32 v69, v203
	s_nop 0
	s_nop 1
	v_mov_b32_e32 v70, v220
	v_mov_b32_e32 v71, v221
	v_mov_b32_e32 v72, v222
	v_mov_b32_e32 v73, v223
	s_nop 0
	v_pk_mul_f32 v[68:69], v[60:61], v[68:69]
	v_pk_mul_f32 v[62:63], v[62:63], v[70:71]
	v_pk_mul_f32 v[64:65], v[64:65], v[72:73]
	v_pk_mul_f32 v[60:61], v[58:59], v[66:67]
	v_cvt_pk_bf16_f32 v58, v62, v63
	v_add_co_u32_e32 v62, vcc, s2, v122
	v_cvt_pk_bf16_f32 v59, v64, v65
	v_cvt_pk_bf16_f32 v60, v60, v61
	v_cvt_pk_bf16_f32 v61, v68, v69
	v_addc_co_u32_e32 v63, vcc, 0, v123, vcc
	global_store_dwordx4 v[62:63], v[58:61], off
	s_nop 1
	v_mov_b32_e32 v58, v228
	v_mov_b32_e32 v59, v229
	v_mov_b32_e32 v60, v230
	v_mov_b32_e32 v61, v231
	s_nop 0
	s_nop 1
	v_mov_b32_e32 v62, v236
	v_mov_b32_e32 v63, v237
	v_mov_b32_e32 v64, v238
	v_mov_b32_e32 v65, v239
	v_lshl_add_u64 v[66:67], v[122:123], 0, s[6:7]
	s_mov_b32 s2, 0x480000
	s_mov_b64 s[6:7], 0x480000
	s_nop 0
	v_pk_mul_f32 v[60:61], v[44:45], v[60:61]
	v_pk_mul_f32 v[52:53], v[52:53], v[64:65]
	v_pk_mul_f32 v[50:51], v[50:51], v[62:63]
	v_pk_mul_f32 v[44:45], v[42:43], v[58:59]
	v_cvt_pk_bf16_f32 v42, v50, v51
	v_cvt_pk_bf16_f32 v43, v52, v53
	v_cvt_pk_bf16_f32 v44, v44, v45
	v_cvt_pk_bf16_f32 v45, v60, v61
	global_store_dwordx4 v[66:67], v[42:45], off offset:256
	s_nop 1
	v_mov_b32_e32 v42, v200
	v_mov_b32_e32 v43, v201
	v_mov_b32_e32 v44, v202
	v_mov_b32_e32 v45, v203
	s_nop 0
	s_nop 1
	v_mov_b32_e32 v50, v220
	v_mov_b32_e32 v51, v221
	v_mov_b32_e32 v52, v222
	v_mov_b32_e32 v53, v223
	s_nop 0
	v_pk_mul_f32 v[48:49], v[48:49], v[44:45]
	v_pk_mul_f32 v[52:53], v[56:57], v[52:53]
	v_pk_mul_f32 v[50:51], v[54:55], v[50:51]
	v_pk_mul_f32 v[44:45], v[46:47], v[42:43]
	v_add_co_u32_e32 v46, vcc, s2, v122
	v_cvt_pk_bf16_f32 v42, v50, v51
	v_cvt_pk_bf16_f32 v43, v52, v53
	v_cvt_pk_bf16_f32 v44, v44, v45
	v_cvt_pk_bf16_f32 v45, v48, v49
	v_addc_co_u32_e32 v47, vcc, 0, v123, vcc
	global_store_dwordx4 v[46:47], v[42:45], off
	s_nop 1
	v_mov_b32_e32 v42, v228
	v_mov_b32_e32 v43, v229
	v_mov_b32_e32 v44, v230
	v_mov_b32_e32 v45, v231
	s_nop 0
	s_nop 1
	v_mov_b32_e32 v46, v236
	v_mov_b32_e32 v47, v237
	v_mov_b32_e32 v48, v238
	v_mov_b32_e32 v49, v239
	v_lshl_add_u64 v[50:51], v[122:123], 0, s[6:7]
	s_mov_b32 s2, 0x500000
	s_mov_b64 s[6:7], 0x500000
	s_nop 0
	v_pk_mul_f32 v[44:45], v[28:29], v[44:45]
	v_pk_mul_f32 v[36:37], v[36:37], v[48:49]
	v_pk_mul_f32 v[34:35], v[34:35], v[46:47]
	v_pk_mul_f32 v[28:29], v[26:27], v[42:43]
	v_cvt_pk_bf16_f32 v26, v34, v35
	v_cvt_pk_bf16_f32 v27, v36, v37
	v_cvt_pk_bf16_f32 v28, v28, v29
	v_cvt_pk_bf16_f32 v29, v44, v45
	global_store_dwordx4 v[50:51], v[26:29], off offset:256
	s_nop 1
	v_mov_b32_e32 v26, v200
	v_mov_b32_e32 v27, v201
	v_mov_b32_e32 v28, v202
	v_mov_b32_e32 v29, v203
	s_nop 0
	s_nop 1
	v_mov_b32_e32 v34, v220
	v_mov_b32_e32 v35, v221
	v_mov_b32_e32 v36, v222
	v_mov_b32_e32 v37, v223
	s_nop 0
	v_pk_mul_f32 v[32:33], v[32:33], v[28:29]
	v_pk_mul_f32 v[36:37], v[40:41], v[36:37]
	v_pk_mul_f32 v[34:35], v[38:39], v[34:35]
	v_pk_mul_f32 v[28:29], v[30:31], v[26:27]
	v_add_co_u32_e32 v30, vcc, s2, v122
	v_cvt_pk_bf16_f32 v26, v34, v35
	v_cvt_pk_bf16_f32 v27, v36, v37
	v_cvt_pk_bf16_f32 v28, v28, v29
	v_cvt_pk_bf16_f32 v29, v32, v33
	v_addc_co_u32_e32 v31, vcc, 0, v123, vcc
	global_store_dwordx4 v[30:31], v[26:29], off
	s_nop 1
	v_mov_b32_e32 v26, v228
	v_mov_b32_e32 v27, v229
	v_mov_b32_e32 v28, v230
	v_mov_b32_e32 v29, v231
	s_nop 0
	s_nop 1
	v_mov_b32_e32 v30, v236
	v_mov_b32_e32 v31, v237
	v_mov_b32_e32 v32, v238
	v_mov_b32_e32 v33, v239
	v_lshl_add_u64 v[34:35], v[122:123], 0, s[6:7]
	s_mov_b32 s2, 0x580000
	s_mov_b64 s[6:7], 0x580000
	s_nop 0
	v_pk_mul_f32 v[28:29], v[12:13], v[28:29]
	v_pk_mul_f32 v[20:21], v[20:21], v[32:33]
	v_pk_mul_f32 v[18:19], v[18:19], v[30:31]
	v_pk_mul_f32 v[12:13], v[10:11], v[26:27]
	v_cvt_pk_bf16_f32 v10, v18, v19
	v_cvt_pk_bf16_f32 v11, v20, v21
	v_cvt_pk_bf16_f32 v12, v12, v13
	v_cvt_pk_bf16_f32 v13, v28, v29
	global_store_dwordx4 v[34:35], v[10:13], off offset:256
	s_nop 1
	v_mov_b32_e32 v10, v200
	v_mov_b32_e32 v11, v201
	v_mov_b32_e32 v12, v202
	v_mov_b32_e32 v13, v203
	s_nop 0
	s_nop 1
	v_mov_b32_e32 v18, v220
	v_mov_b32_e32 v19, v221
	v_mov_b32_e32 v20, v222
	v_mov_b32_e32 v21, v223
	s_nop 0
	v_pk_mul_f32 v[16:17], v[16:17], v[12:13]
	v_pk_mul_f32 v[20:21], v[24:25], v[20:21]
	v_pk_mul_f32 v[18:19], v[22:23], v[18:19]
	v_pk_mul_f32 v[12:13], v[14:15], v[10:11]
	v_add_co_u32_e32 v14, vcc, s2, v122
	v_cvt_pk_bf16_f32 v10, v18, v19
	v_cvt_pk_bf16_f32 v11, v20, v21
	v_cvt_pk_bf16_f32 v12, v12, v13
	v_cvt_pk_bf16_f32 v13, v16, v17
	v_addc_co_u32_e32 v15, vcc, 0, v123, vcc
	global_store_dwordx4 v[14:15], v[10:13], off
	s_nop 1
	v_mov_b32_e32 v10, v228
	v_mov_b32_e32 v11, v229
	v_mov_b32_e32 v12, v230
	v_mov_b32_e32 v13, v231
	s_nop 0
	s_nop 1
	v_mov_b32_e32 v14, v236
	v_mov_b32_e32 v15, v237
	v_mov_b32_e32 v16, v238
	v_mov_b32_e32 v17, v239
	v_lshl_add_u64 v[18:19], v[122:123], 0, s[6:7]
	s_and_b64 vcc, exec, s[0:1]
	s_nop 0
	v_pk_mul_f32 v[12:13], v[4:5], v[12:13]
	v_pk_mul_f32 v[8:9], v[8:9], v[16:17]
	v_pk_mul_f32 v[6:7], v[6:7], v[14:15]
	v_pk_mul_f32 v[4:5], v[2:3], v[10:11]
	v_cvt_pk_bf16_f32 v2, v6, v7
	v_cvt_pk_bf16_f32 v3, v8, v9
	v_cvt_pk_bf16_f32 v4, v4, v5
	v_cvt_pk_bf16_f32 v5, v12, v13
	global_store_dwordx4 v[18:19], v[2:5], off offset:256
	s_cbranch_vccz .LBB0_491
	v_readlane_b32 s0, v254, 12
	s_waitcnt vmcnt(0)
	v_readlane_b32 s1, v254, 13
	v_readlane_b32 s84, v251, 38
	v_readlane_b32 s18, v253, 0
	s_andn2_b64 vcc, exec, s[0:1]
	v_readlane_b32 s85, v251, 39
	v_readlane_b32 s86, v251, 40
	v_readlane_b32 s87, v251, 41
	v_readlane_b32 s14, v250, 63
	v_readlane_b32 s19, v253, 1
	s_cbranch_vccnz .LBB0_504
	s_barrier

.LBB0_655:
	s_add_u32 s2, s68, 0xfff80080
	s_addc_u32 s17, s69, -1
	s_add_i32 s26, 0, 0x10000
	v_add_u32_e32 v156, s26, v141
	ds_read_b128 v[144:147], v156
	ds_read_b128 v[148:151], v156 offset:1024
	ds_read_b128 v[152:155], v156 offset:2048
	ds_read_b128 v[156:159], v156 offset:3072
	s_cmp_eq_u32 s44, 28
	s_cselect_b32 s73, s55, s17
	s_cselect_b32 s72, s83, s2
	s_cselect_b32 s71, s24, s92
	s_cselect_b32 s70, s25, s43
	v_lshl_add_u64 v[164:165], s[68:69], 0, v[136:137]
	s_add_i32 m0, s58, 0xc000
	ds_read_b128 v[160:163], v143
	ds_read_b128 v[188:191], v143 offset:1024
	ds_read_b128 v[192:195], v143 offset:2048
	ds_read_b128 v[196:199], v143 offset:3072
	ds_read_b128 v[200:203], v143 offset:4096
	ds_read_b128 v[216:219], v143 offset:5120
	ds_read_b128 v[220:223], v143 offset:6144
	ds_read_b128 v[224:227], v143 offset:7168
	global_load_lds_dwordx4 v[164:165], off
	v_lshl_add_u64 v[164:165], s[68:69], 0, v[138:139]
	s_add_i32 m0, s58, 0xe000
	s_nop 0
	global_load_lds_dwordx4 v[164:165], off
	s_waitcnt lgkmcnt(8)
	s_barrier
	s_waitcnt lgkmcnt(7)
	v_mfma_f32_16x16x32_bf16 v[126:129], v[144:147], v[160:163], v[126:129]
	v_mfma_f32_16x16x32_bf16 v[122:125], v[152:155], v[160:163], v[122:125]
	s_waitcnt lgkmcnt(5)
	v_mfma_f32_16x16x32_bf16 v[118:121], v[144:147], v[192:195], v[118:121]
	v_mfma_f32_16x16x32_bf16 v[114:117], v[152:155], v[192:195], v[114:117]
	s_waitcnt lgkmcnt(3)
	v_mfma_f32_16x16x32_bf16 v[102:105], v[144:147], v[200:203], v[102:105]
	v_mfma_f32_16x16x32_bf16 v[98:101], v[152:155], v[200:203], v[98:101]
	s_waitcnt lgkmcnt(1)
	v_mfma_f32_16x16x32_bf16 v[86:89], v[144:147], v[220:223], v[86:89]
	v_mfma_f32_16x16x32_bf16 v[82:85], v[152:155], v[220:223], v[82:85]
	s_add_i32 s2, 0, 0x14000
	v_add_u32_e32 v164, s2, v141
	ds_read_b128 v[228:231], v164
	ds_read_b128 v[232:235], v164 offset:1024
	ds_read_b128 v[236:239], v164 offset:2048
	ds_read_b128 v[240:243], v164 offset:3072
	v_mfma_f32_16x16x32_bf16 v[126:129], v[148:151], v[188:191], v[126:129]
	v_mfma_f32_16x16x32_bf16 v[122:125], v[156:159], v[188:191], v[122:125]
	v_mfma_f32_16x16x32_bf16 v[118:121], v[148:151], v[196:199], v[118:121]
	v_mfma_f32_16x16x32_bf16 v[114:117], v[156:159], v[196:199], v[114:117]
	v_mfma_f32_16x16x32_bf16 v[102:105], v[148:151], v[216:219], v[102:105]
	v_mfma_f32_16x16x32_bf16 v[98:101], v[156:159], v[216:219], v[98:101]
	s_waitcnt lgkmcnt(4)
	v_mfma_f32_16x16x32_bf16 v[86:89], v[148:151], v[224:227], v[86:89]
	v_mfma_f32_16x16x32_bf16 v[82:85], v[156:159], v[224:227], v[82:85]
	s_barrier
	s_add_i32 s17, s26, s3
	v_lshl_add_u64 v[164:165], s[70:71], 0, v[0:1]
	s_mov_b32 m0, s17
	v_lshl_add_u64 v[204:205], s[70:71], 0, v[130:131]
	global_load_lds_dwordx4 v[164:165], off
	s_add_i32 m0, s17, 0x2000
	s_nop 0
	global_load_lds_dwordx4 v[204:205], off
	s_barrier
	s_waitcnt lgkmcnt(3)
	v_mfma_f32_16x16x32_bf16 v[110:113], v[228:231], v[160:163], v[110:113]
	s_waitcnt lgkmcnt(1)
	v_mfma_f32_16x16x32_bf16 v[106:109], v[236:239], v[160:163], v[106:109]
	v_mfma_f32_16x16x32_bf16 v[94:97], v[228:231], v[192:195], v[94:97]
	v_mfma_f32_16x16x32_bf16 v[90:93], v[236:239], v[192:195], v[90:93]
	v_mfma_f32_16x16x32_bf16 v[78:81], v[228:231], v[200:203], v[78:81]
	v_mfma_f32_16x16x32_bf16 v[74:77], v[236:239], v[200:203], v[74:77]
	v_mfma_f32_16x16x32_bf16 v[70:73], v[228:231], v[220:223], v[70:73]
	v_mfma_f32_16x16x32_bf16 v[66:69], v[236:239], v[220:223], v[66:69]
	v_mfma_f32_16x16x32_bf16 v[110:113], v[232:235], v[188:191], v[110:113]
	s_waitcnt lgkmcnt(0)
	v_mfma_f32_16x16x32_bf16 v[106:109], v[240:243], v[188:191], v[106:109]
	v_mfma_f32_16x16x32_bf16 v[94:97], v[232:235], v[196:199], v[94:97]
	v_mfma_f32_16x16x32_bf16 v[90:93], v[240:243], v[196:199], v[90:93]
	v_mfma_f32_16x16x32_bf16 v[78:81], v[232:235], v[216:219], v[78:81]
	v_mfma_f32_16x16x32_bf16 v[74:77], v[240:243], v[216:219], v[74:77]
	v_mfma_f32_16x16x32_bf16 v[70:73], v[232:235], v[224:227], v[70:73]
	v_mfma_f32_16x16x32_bf16 v[66:69], v[240:243], v[224:227], v[66:69]
	s_mov_b32 m0, s58
	v_lshl_add_u64 v[244:245], s[72:73], 0, v[134:135]
	s_barrier
	ds_read_b128 v[160:163], v143 offset:16384
	ds_read_b128 v[188:191], v143 offset:17408
	ds_read_b128 v[192:195], v143 offset:18432
	ds_read_b128 v[196:199], v143 offset:19456
	ds_read_b128 v[200:203], v143 offset:20480
	ds_read_b128 v[216:219], v143 offset:21504
	ds_read_b128 v[220:223], v143 offset:22528
	ds_read_b128 v[224:227], v143 offset:23552
	global_load_lds_dwordx4 v[244:245], off
	v_lshl_add_u64 v[246:247], s[72:73], 0, v[132:133]
	s_mov_b32 m0, s74
	s_nop 0
	global_load_lds_dwordx4 v[246:247], off
	s_barrier
	s_waitcnt lgkmcnt(7)
	v_mfma_f32_16x16x32_bf16 v[62:65], v[144:147], v[160:163], v[62:65]
	v_mfma_f32_16x16x32_bf16 v[58:61], v[152:155], v[160:163], v[58:61]
	s_waitcnt lgkmcnt(5)
	v_mfma_f32_16x16x32_bf16 v[54:57], v[144:147], v[192:195], v[54:57]
	v_mfma_f32_16x16x32_bf16 v[50:53], v[152:155], v[192:195], v[50:53]
	s_waitcnt lgkmcnt(3)
	v_mfma_f32_16x16x32_bf16 v[38:41], v[144:147], v[200:203], v[38:41]
	v_mfma_f32_16x16x32_bf16 v[34:37], v[152:155], v[200:203], v[34:37]
	s_waitcnt lgkmcnt(1)
	v_mfma_f32_16x16x32_bf16 v[22:25], v[144:147], v[220:223], v[22:25]
	v_mfma_f32_16x16x32_bf16 v[18:21], v[152:155], v[220:223], v[18:21]
	v_mfma_f32_16x16x32_bf16 v[62:65], v[148:151], v[188:191], v[62:65]
	v_mfma_f32_16x16x32_bf16 v[58:61], v[156:159], v[188:191], v[58:61]
	v_mfma_f32_16x16x32_bf16 v[54:57], v[148:151], v[196:199], v[54:57]
	v_mfma_f32_16x16x32_bf16 v[50:53], v[156:159], v[196:199], v[50:53]
	v_mfma_f32_16x16x32_bf16 v[38:41], v[148:151], v[216:219], v[38:41]
	v_mfma_f32_16x16x32_bf16 v[34:37], v[156:159], v[216:219], v[34:37]
	s_waitcnt lgkmcnt(0)
	v_mfma_f32_16x16x32_bf16 v[22:25], v[148:151], v[224:227], v[22:25]
	v_mfma_f32_16x16x32_bf16 v[18:21], v[156:159], v[224:227], v[18:21]
	s_barrier
	s_add_u32 s26, s70, 0x80000
	s_addc_u32 s27, s71, 0
	s_add_i32 s2, s2, s3
	v_lshl_add_u64 v[144:145], s[26:27], 0, v[0:1]
	s_mov_b32 m0, s2
	s_nop 0
	global_load_lds_dwordx4 v[144:145], off
	v_lshl_add_u64 v[144:145], s[26:27], 0, v[130:131]
	s_add_i32 m0, s2, 0x2000
	s_nop 0
	global_load_lds_dwordx4 v[144:145], off
	s_waitcnt vmcnt(6)
	s_barrier
	v_mfma_f32_16x16x32_bf16 v[46:49], v[228:231], v[160:163], v[46:49]
	v_mfma_f32_16x16x32_bf16 v[42:45], v[236:239], v[160:163], v[42:45]
	v_mfma_f32_16x16x32_bf16 v[30:33], v[228:231], v[192:195], v[30:33]
	v_mfma_f32_16x16x32_bf16 v[26:29], v[236:239], v[192:195], v[26:29]
	v_mfma_f32_16x16x32_bf16 v[14:17], v[228:231], v[200:203], v[14:17]
	v_mfma_f32_16x16x32_bf16 v[10:13], v[236:239], v[200:203], v[10:13]
	v_mfma_f32_16x16x32_bf16 v[6:9], v[228:231], v[220:223], v[6:9]
	v_mfma_f32_16x16x32_bf16 v[2:5], v[236:239], v[220:223], v[2:5]
	v_mfma_f32_16x16x32_bf16 v[46:49], v[232:235], v[188:191], v[46:49]
	v_mfma_f32_16x16x32_bf16 v[42:45], v[240:243], v[188:191], v[42:45]
	v_mfma_f32_16x16x32_bf16 v[30:33], v[232:235], v[196:199], v[30:33]
	v_mfma_f32_16x16x32_bf16 v[26:29], v[240:243], v[196:199], v[26:29]
	v_mfma_f32_16x16x32_bf16 v[14:17], v[232:235], v[216:219], v[14:17]
	v_mfma_f32_16x16x32_bf16 v[10:13], v[240:243], v[216:219], v[10:13]
	v_mfma_f32_16x16x32_bf16 v[6:9], v[232:235], v[224:227], v[6:9]
	v_mfma_f32_16x16x32_bf16 v[2:5], v[240:243], v[224:227], v[2:5]
	s_add_i32 s2, 0, 0x18000
	v_add_u32_e32 v156, s2, v141
	s_barrier
	ds_read_b128 v[144:147], v156
	ds_read_b128 v[148:151], v156 offset:1024
	ds_read_b128 v[152:155], v156 offset:2048
	ds_read_b128 v[156:159], v156 offset:3072
	s_add_u32 s26, s72, 0x80000
	s_addc_u32 s27, s73, 0
	s_mov_b32 m0, s75
	v_lshl_add_u64 v[228:229], s[26:27], 0, v[134:135]
	ds_read_b128 v[160:163], v143 offset:32768
	ds_read_b128 v[188:191], v143 offset:33792
	ds_read_b128 v[192:195], v143 offset:34816
	ds_read_b128 v[196:199], v143 offset:35840
	ds_read_b128 v[200:203], v143 offset:36864
	ds_read_b128 v[216:219], v143 offset:37888
	ds_read_b128 v[220:223], v143 offset:38912
	ds_read_b128 v[224:227], v143 offset:39936
	global_load_lds_dwordx4 v[228:229], off
	v_lshl_add_u64 v[228:229], s[26:27], 0, v[132:133]
	s_mov_b32 m0, s79
	s_nop 0
	global_load_lds_dwordx4 v[228:229], off
	s_waitcnt lgkmcnt(8)
	s_barrier
	s_waitcnt lgkmcnt(7)
	v_mfma_f32_16x16x32_bf16 v[126:129], v[144:147], v[160:163], v[126:129]
	v_mfma_f32_16x16x32_bf16 v[122:125], v[152:155], v[160:163], v[122:125]
	s_waitcnt lgkmcnt(5)
	v_mfma_f32_16x16x32_bf16 v[118:121], v[144:147], v[192:195], v[118:121]
	v_mfma_f32_16x16x32_bf16 v[114:117], v[152:155], v[192:195], v[114:117]
	s_waitcnt lgkmcnt(3)
	v_mfma_f32_16x16x32_bf16 v[102:105], v[144:147], v[200:203], v[102:105]
	v_mfma_f32_16x16x32_bf16 v[98:101], v[152:155], v[200:203], v[98:101]
	s_waitcnt lgkmcnt(1)
	v_mfma_f32_16x16x32_bf16 v[86:89], v[144:147], v[220:223], v[86:89]
	v_mfma_f32_16x16x32_bf16 v[82:85], v[152:155], v[220:223], v[82:85]
	s_add_i32 s17, 0, 0x1c000
	v_add_u32_e32 v206, s17, v141
	ds_read_b128 v[228:231], v206
	ds_read_b128 v[232:235], v206 offset:1024
	ds_read_b128 v[236:239], v206 offset:2048
	ds_read_b128 v[240:243], v206 offset:3072
	v_mfma_f32_16x16x32_bf16 v[126:129], v[148:151], v[188:191], v[126:129]
	v_mfma_f32_16x16x32_bf16 v[122:125], v[156:159], v[188:191], v[122:125]
	v_mfma_f32_16x16x32_bf16 v[118:121], v[148:151], v[196:199], v[118:121]
	v_mfma_f32_16x16x32_bf16 v[114:117], v[156:159], v[196:199], v[114:117]
	v_mfma_f32_16x16x32_bf16 v[102:105], v[148:151], v[216:219], v[102:105]
	v_mfma_f32_16x16x32_bf16 v[98:101], v[156:159], v[216:219], v[98:101]
	s_waitcnt lgkmcnt(4)
	v_mfma_f32_16x16x32_bf16 v[86:89], v[148:151], v[224:227], v[86:89]
	v_mfma_f32_16x16x32_bf16 v[82:85], v[156:159], v[224:227], v[82:85]
	s_barrier
	s_add_i32 s2, s2, s3
	v_lshl_add_u64 v[164:165], v[164:165], 0, s[28:29]
	s_mov_b32 m0, s2
	global_load_lds_dwordx4 v[164:165], off
	v_lshl_add_u64 v[164:165], v[204:205], 0, s[28:29]
	s_add_i32 m0, s2, 0x2000
	s_nop 0
	global_load_lds_dwordx4 v[164:165], off
	s_barrier
	s_waitcnt lgkmcnt(3)
	v_mfma_f32_16x16x32_bf16 v[110:113], v[228:231], v[160:163], v[110:113]
	s_waitcnt lgkmcnt(1)
	v_mfma_f32_16x16x32_bf16 v[106:109], v[236:239], v[160:163], v[106:109]
	v_mfma_f32_16x16x32_bf16 v[94:97], v[228:231], v[192:195], v[94:97]
	v_mfma_f32_16x16x32_bf16 v[90:93], v[236:239], v[192:195], v[90:93]
	v_mfma_f32_16x16x32_bf16 v[78:81], v[228:231], v[200:203], v[78:81]
	v_mfma_f32_16x16x32_bf16 v[74:77], v[236:239], v[200:203], v[74:77]
	v_mfma_f32_16x16x32_bf16 v[70:73], v[228:231], v[220:223], v[70:73]
	v_mfma_f32_16x16x32_bf16 v[66:69], v[236:239], v[220:223], v[66:69]
	v_mfma_f32_16x16x32_bf16 v[110:113], v[232:235], v[188:191], v[110:113]
	s_waitcnt lgkmcnt(0)
	v_mfma_f32_16x16x32_bf16 v[106:109], v[240:243], v[188:191], v[106:109]
	v_mfma_f32_16x16x32_bf16 v[94:97], v[232:235], v[196:199], v[94:97]
	v_mfma_f32_16x16x32_bf16 v[90:93], v[240:243], v[196:199], v[90:93]
	v_mfma_f32_16x16x32_bf16 v[78:81], v[232:235], v[216:219], v[78:81]
	v_mfma_f32_16x16x32_bf16 v[74:77], v[240:243], v[216:219], v[74:77]
	v_mfma_f32_16x16x32_bf16 v[70:73], v[232:235], v[224:227], v[70:73]
	v_mfma_f32_16x16x32_bf16 v[66:69], v[240:243], v[224:227], v[66:69]
	s_mov_b32 m0, s80
	v_lshl_add_u64 v[164:165], v[244:245], 0, s[28:29]
	s_barrier
	ds_read_b128 v[160:163], v143 offset:49152
	ds_read_b128 v[188:191], v143 offset:50176
	ds_read_b128 v[192:195], v143 offset:51200
	ds_read_b128 v[196:199], v143 offset:52224
	ds_read_b128 v[200:203], v143 offset:53248
	ds_read_b128 v[216:219], v143 offset:54272
	ds_read_b128 v[220:223], v143 offset:55296
	ds_read_b128 v[224:227], v143 offset:56320
	global_load_lds_dwordx4 v[164:165], off
	v_lshl_add_u64 v[164:165], v[246:247], 0, s[28:29]
	s_mov_b32 m0, s81
	s_nop 0
	global_load_lds_dwordx4 v[164:165], off
	s_barrier
	s_waitcnt lgkmcnt(7)
	v_mfma_f32_16x16x32_bf16 v[62:65], v[144:147], v[160:163], v[62:65]
	v_mfma_f32_16x16x32_bf16 v[58:61], v[152:155], v[160:163], v[58:61]
	s_waitcnt lgkmcnt(5)
	v_mfma_f32_16x16x32_bf16 v[54:57], v[144:147], v[192:195], v[54:57]
	v_mfma_f32_16x16x32_bf16 v[50:53], v[152:155], v[192:195], v[50:53]
	s_waitcnt lgkmcnt(3)
	v_mfma_f32_16x16x32_bf16 v[38:41], v[144:147], v[200:203], v[38:41]
	v_mfma_f32_16x16x32_bf16 v[34:37], v[152:155], v[200:203], v[34:37]
	s_waitcnt lgkmcnt(1)
	v_mfma_f32_16x16x32_bf16 v[22:25], v[144:147], v[220:223], v[22:25]
	v_mfma_f32_16x16x32_bf16 v[18:21], v[152:155], v[220:223], v[18:21]
	v_mfma_f32_16x16x32_bf16 v[62:65], v[148:151], v[188:191], v[62:65]
	v_mfma_f32_16x16x32_bf16 v[58:61], v[156:159], v[188:191], v[58:61]
	v_mfma_f32_16x16x32_bf16 v[54:57], v[148:151], v[196:199], v[54:57]
	v_mfma_f32_16x16x32_bf16 v[50:53], v[156:159], v[196:199], v[50:53]
	v_mfma_f32_16x16x32_bf16 v[38:41], v[148:151], v[216:219], v[38:41]
	v_mfma_f32_16x16x32_bf16 v[34:37], v[156:159], v[216:219], v[34:37]
	s_waitcnt lgkmcnt(0)
	v_mfma_f32_16x16x32_bf16 v[22:25], v[148:151], v[224:227], v[22:25]
	v_mfma_f32_16x16x32_bf16 v[18:21], v[156:159], v[224:227], v[18:21]
	s_barrier
	s_add_u32 s26, s70, 0x80080
	s_addc_u32 s27, s71, 0
	s_add_i32 s2, s17, s3
	v_lshl_add_u64 v[144:145], s[26:27], 0, v[0:1]
	s_mov_b32 m0, s2
	s_nop 0
	global_load_lds_dwordx4 v[144:145], off
	v_lshl_add_u64 v[144:145], s[26:27], 0, v[130:131]
	s_add_i32 m0, s2, 0x2000
	s_nop 0
	global_load_lds_dwordx4 v[144:145], off
	s_waitcnt vmcnt(6)
	s_barrier
	v_mfma_f32_16x16x32_bf16 v[46:49], v[228:231], v[160:163], v[46:49]
	v_mfma_f32_16x16x32_bf16 v[42:45], v[236:239], v[160:163], v[42:45]
	v_mfma_f32_16x16x32_bf16 v[30:33], v[228:231], v[192:195], v[30:33]
	v_mfma_f32_16x16x32_bf16 v[26:29], v[236:239], v[192:195], v[26:29]
	v_mfma_f32_16x16x32_bf16 v[14:17], v[228:231], v[200:203], v[14:17]
	v_mfma_f32_16x16x32_bf16 v[10:13], v[236:239], v[200:203], v[10:13]
	v_mfma_f32_16x16x32_bf16 v[6:9], v[228:231], v[220:223], v[6:9]
	v_mfma_f32_16x16x32_bf16 v[2:5], v[236:239], v[220:223], v[2:5]
	v_mfma_f32_16x16x32_bf16 v[46:49], v[232:235], v[188:191], v[46:49]
	v_mfma_f32_16x16x32_bf16 v[42:45], v[240:243], v[188:191], v[42:45]
	v_mfma_f32_16x16x32_bf16 v[30:33], v[232:235], v[196:199], v[30:33]
	v_mfma_f32_16x16x32_bf16 v[26:29], v[240:243], v[196:199], v[26:29]
	v_mfma_f32_16x16x32_bf16 v[14:17], v[232:235], v[216:219], v[14:17]
	v_mfma_f32_16x16x32_bf16 v[10:13], v[240:243], v[216:219], v[10:13]
	v_mfma_f32_16x16x32_bf16 v[6:9], v[232:235], v[224:227], v[6:9]
	v_mfma_f32_16x16x32_bf16 v[2:5], v[240:243], v[224:227], v[2:5]
	s_add_i32 s44, s44, 2
	s_add_u32 s68, s68, 0x100
	s_addc_u32 s69, s69, 0
	s_add_u32 s43, s43, 0x100
	s_addc_u32 s92, s92, 0
	s_cmp_gt_u32 s44, 29
	s_barrier
	s_cbranch_scc0 .LBB0_655
	v_lshl_add_u32 v144, s47, 8, v140
	v_lshl_or_b32 v146, s46, 8, v142
	v_ashrrev_i32_e32 v145, 31, v144
	v_cvt_pk_bf16_f32 v126, v126, v127
	v_cvt_pk_bf16_f32 v127, v128, v129
	v_cvt_pk_bf16_f32 v128, v122, v123
	v_lshlrev_b64 v[122:123], 12, v[144:145]
	v_ashrrev_i32_e32 v147, 31, v146
	v_cvt_pk_bf16_f32 v129, v124, v125
	v_lshl_add_u64 v[122:123], s[22:23], 0, v[122:123]
	v_lshlrev_b64 v[124:125], 1, v[146:147]
	v_lshl_add_u64 v[122:123], v[122:123], 0, v[124:125]
	v_cvt_pk_bf16_f32 v110, v110, v111
	v_cvt_pk_bf16_f32 v111, v112, v113
	v_cvt_pk_bf16_f32 v112, v106, v107
	v_cvt_pk_bf16_f32 v113, v108, v109
	global_store_dwordx4 v[122:123], v[110:113], off offset:256
	v_cvt_pk_bf16_f32 v94, v94, v95
	v_cvt_pk_bf16_f32 v95, v96, v97
	v_or_b32_e32 v110, 16, v144
	v_ashrrev_i32_e32 v111, 31, v110
	v_lshlrev_b64 v[110:111], 12, v[110:111]
	v_lshl_add_u64 v[110:111], s[22:23], 0, v[110:111]
	v_lshl_add_u64 v[110:111], v[110:111], 0, v[124:125]
	v_cvt_pk_bf16_f32 v96, v90, v91
	v_cvt_pk_bf16_f32 v97, v92, v93
	global_store_dwordx4 v[110:111], v[94:97], off offset:256
	s_mov_b32 s2, 0x80000
	v_cvt_pk_bf16_f32 v62, v62, v63
	v_or_b32_e32 v94, 32, v144
	v_ashrrev_i32_e32 v95, 31, v94
	v_cvt_pk_bf16_f32 v63, v64, v65
	v_cvt_pk_bf16_f32 v65, v60, v61
	s_mov_b64 s[4:5], 0x80000
	v_add_co_u32_e32 v60, vcc, s2, v122
	v_lshlrev_b64 v[94:95], 12, v[94:95]
	v_cvt_pk_bf16_f32 v64, v58, v59
	v_lshl_add_u64 v[58:59], v[122:123], 0, s[4:5]
	v_addc_co_u32_e32 v61, vcc, 0, v123, vcc
	v_cvt_pk_bf16_f32 v46, v46, v47
	v_cvt_pk_bf16_f32 v47, v48, v49
	v_cvt_pk_bf16_f32 v48, v42, v43
	v_cvt_pk_bf16_f32 v49, v44, v45
	s_mov_b32 s2, 0x90000
	v_lshl_add_u64 v[94:95], s[22:23], 0, v[94:95]
	global_store_dwordx4 v[58:59], v[46:49], off offset:256
	s_mov_b64 s[4:5], 0x90000
	v_lshl_add_u64 v[94:95], v[94:95], 0, v[124:125]
	v_add_co_u32_e32 v48, vcc, s2, v122
	v_cvt_pk_bf16_f32 v78, v78, v79
	v_cvt_pk_bf16_f32 v79, v80, v81
	v_cvt_pk_bf16_f32 v80, v74, v75
	v_cvt_pk_bf16_f32 v81, v76, v77
	v_lshl_add_u64 v[46:47], v[122:123], 0, s[4:5]
	v_addc_co_u32_e32 v49, vcc, 0, v123, vcc
	v_cvt_pk_bf16_f32 v30, v30, v31
	v_cvt_pk_bf16_f32 v31, v32, v33
	v_cvt_pk_bf16_f32 v32, v26, v27
	v_cvt_pk_bf16_f32 v33, v28, v29
	s_mov_b32 s2, 0xa0000
	global_store_dwordx4 v[94:95], v[78:81], off offset:256
	global_store_dwordx4 v[46:47], v[30:33], off offset:256
	s_mov_b64 s[4:5], 0xa0000
	v_or_b32_e32 v78, 48, v144
	v_add_co_u32_e32 v32, vcc, s2, v122
	v_ashrrev_i32_e32 v79, 31, v78
	v_lshl_add_u64 v[30:31], v[122:123], 0, s[4:5]
	v_addc_co_u32_e32 v33, vcc, 0, v123, vcc
	v_cvt_pk_bf16_f32 v14, v14, v15
	v_cvt_pk_bf16_f32 v15, v16, v17
	v_cvt_pk_bf16_f32 v16, v10, v11
	v_cvt_pk_bf16_f32 v17, v12, v13
	s_mov_b32 s2, 0xb0000
	v_lshlrev_b64 v[78:79], 12, v[78:79]
	global_store_dwordx4 v[30:31], v[14:17], off offset:256
	v_lshl_add_u64 v[78:79], s[22:23], 0, v[78:79]
	s_mov_b64 s[4:5], 0xb0000
	v_add_co_u32_e32 v16, vcc, s2, v122
	v_cvt_pk_bf16_f32 v106, v118, v119
	s_nop 0
	v_addc_co_u32_e32 v17, vcc, 0, v123, vcc
	v_cvt_pk_bf16_f32 v107, v120, v121
	v_cvt_pk_bf16_f32 v108, v114, v115
	v_cvt_pk_bf16_f32 v109, v116, v117
	v_cvt_pk_bf16_f32 v90, v102, v103
	v_cvt_pk_bf16_f32 v91, v104, v105
	v_cvt_pk_bf16_f32 v92, v98, v99
	v_cvt_pk_bf16_f32 v93, v100, v101
	v_cvt_pk_bf16_f32 v74, v86, v87
	v_cvt_pk_bf16_f32 v75, v88, v89
	v_cvt_pk_bf16_f32 v76, v82, v83
	v_cvt_pk_bf16_f32 v77, v84, v85
	v_lshl_add_u64 v[78:79], v[78:79], 0, v[124:125]
	v_cvt_pk_bf16_f32 v70, v70, v71
	v_cvt_pk_bf16_f32 v71, v72, v73
	v_cvt_pk_bf16_f32 v72, v66, v67
	v_cvt_pk_bf16_f32 v73, v68, v69
	v_cvt_pk_bf16_f32 v42, v54, v55
	v_cvt_pk_bf16_f32 v43, v56, v57
	v_cvt_pk_bf16_f32 v44, v50, v51
	v_cvt_pk_bf16_f32 v45, v52, v53
	v_cvt_pk_bf16_f32 v26, v38, v39
	v_cvt_pk_bf16_f32 v27, v40, v41
	v_cvt_pk_bf16_f32 v28, v34, v35
	v_cvt_pk_bf16_f32 v29, v36, v37
	v_cvt_pk_bf16_f32 v10, v22, v23
	v_cvt_pk_bf16_f32 v11, v24, v25
	v_cvt_pk_bf16_f32 v12, v18, v19
	v_cvt_pk_bf16_f32 v13, v20, v21
	v_lshl_add_u64 v[14:15], v[122:123], 0, s[4:5]
	v_cvt_pk_bf16_f32 v6, v6, v7
	v_cvt_pk_bf16_f32 v7, v8, v9
	v_cvt_pk_bf16_f32 v8, v2, v3
	v_cvt_pk_bf16_f32 v9, v4, v5
	s_and_b64 vcc, exec, s[0:1]
	s_mov_b32 s46, s42
	s_mov_b32 s47, s54
	s_mov_b64 s[70:71], s[64:65]
	s_mov_b64 s[68:69], s[62:63]
	global_store_dwordx4 v[122:123], v[126:129], off
	global_store_dwordx4 v[110:111], v[106:109], off
	global_store_dwordx4 v[94:95], v[90:93], off
	global_store_dwordx4 v[78:79], v[74:77], off
	global_store_dwordx4 v[78:79], v[70:73], off offset:256
	global_store_dwordx4 v[60:61], v[62:65], off
	global_store_dwordx4 v[48:49], v[42:45], off
	global_store_dwordx4 v[32:33], v[26:29], off
	global_store_dwordx4 v[16:17], v[10:13], off
	global_store_dwordx4 v[14:15], v[6:9], off offset:256
	s_cbranch_vccz .LBB0_652
	v_readlane_b32 s0, v254, 12
	s_waitcnt vmcnt(0)
	v_readlane_b32 s1, v254, 13
	v_readlane_b32 s84, v251, 38
	s_andn2_b64 vcc, exec, s[0:1]
	v_readlane_b32 s85, v251, 39
	v_readlane_b32 s86, v251, 40
	v_readlane_b32 s87, v251, 41
	s_cbranch_vccnz .LBB0_659
	s_barrier

.LBB0_724:
	s_add_u32 s2, s68, 0xfff80080
	s_addc_u32 s17, s69, -1
	s_add_i32 s26, 0, 0x10000
	v_add_u32_e32 v156, s26, v141
	ds_read_b128 v[144:147], v156
	ds_read_b128 v[148:151], v156 offset:1024
	ds_read_b128 v[152:155], v156 offset:2048
	ds_read_b128 v[156:159], v156 offset:3072
	s_cmp_eq_u32 s83, 28
	s_cselect_b32 s73, s55, s17
	s_cselect_b32 s72, s81, s2
	s_cselect_b32 s71, s24, s82
	s_cselect_b32 s70, s25, s43
	v_lshl_add_u64 v[164:165], s[68:69], 0, v[136:137]
	s_add_i32 m0, s58, 0xc000
	ds_read_b128 v[160:163], v143
	ds_read_b128 v[188:191], v143 offset:1024
	ds_read_b128 v[192:195], v143 offset:2048
	ds_read_b128 v[196:199], v143 offset:3072
	ds_read_b128 v[200:203], v143 offset:4096
	ds_read_b128 v[216:219], v143 offset:5120
	ds_read_b128 v[220:223], v143 offset:6144
	ds_read_b128 v[224:227], v143 offset:7168
	global_load_lds_dwordx4 v[164:165], off
	v_lshl_add_u64 v[164:165], s[68:69], 0, v[138:139]
	s_add_i32 m0, s58, 0xe000
	s_nop 0
	global_load_lds_dwordx4 v[164:165], off
	s_waitcnt lgkmcnt(8)
	s_barrier
	s_waitcnt lgkmcnt(7)
	v_mfma_f32_16x16x32_bf16 v[126:129], v[144:147], v[160:163], v[126:129]
	v_mfma_f32_16x16x32_bf16 v[122:125], v[152:155], v[160:163], v[122:125]
	s_waitcnt lgkmcnt(5)
	v_mfma_f32_16x16x32_bf16 v[118:121], v[144:147], v[192:195], v[118:121]
	v_mfma_f32_16x16x32_bf16 v[114:117], v[152:155], v[192:195], v[114:117]
	s_waitcnt lgkmcnt(3)
	v_mfma_f32_16x16x32_bf16 v[102:105], v[144:147], v[200:203], v[102:105]
	v_mfma_f32_16x16x32_bf16 v[98:101], v[152:155], v[200:203], v[98:101]
	s_waitcnt lgkmcnt(1)
	v_mfma_f32_16x16x32_bf16 v[86:89], v[144:147], v[220:223], v[86:89]
	v_mfma_f32_16x16x32_bf16 v[82:85], v[152:155], v[220:223], v[82:85]
	s_add_i32 s2, 0, 0x14000
	v_add_u32_e32 v164, s2, v141
	ds_read_b128 v[228:231], v164
	ds_read_b128 v[232:235], v164 offset:1024
	ds_read_b128 v[236:239], v164 offset:2048
	ds_read_b128 v[240:243], v164 offset:3072
	v_mfma_f32_16x16x32_bf16 v[126:129], v[148:151], v[188:191], v[126:129]
	v_mfma_f32_16x16x32_bf16 v[122:125], v[156:159], v[188:191], v[122:125]
	v_mfma_f32_16x16x32_bf16 v[118:121], v[148:151], v[196:199], v[118:121]
	v_mfma_f32_16x16x32_bf16 v[114:117], v[156:159], v[196:199], v[114:117]
	v_mfma_f32_16x16x32_bf16 v[102:105], v[148:151], v[216:219], v[102:105]
	v_mfma_f32_16x16x32_bf16 v[98:101], v[156:159], v[216:219], v[98:101]
	s_waitcnt lgkmcnt(4)
	v_mfma_f32_16x16x32_bf16 v[86:89], v[148:151], v[224:227], v[86:89]
	v_mfma_f32_16x16x32_bf16 v[82:85], v[156:159], v[224:227], v[82:85]
	s_barrier
	s_add_i32 s17, s26, s3
	v_lshl_add_u64 v[164:165], s[70:71], 0, v[0:1]
	s_mov_b32 m0, s17
	v_lshl_add_u64 v[204:205], s[70:71], 0, v[130:131]
	global_load_lds_dwordx4 v[164:165], off
	s_add_i32 m0, s17, 0x2000
	s_nop 0
	global_load_lds_dwordx4 v[204:205], off
	s_barrier
	s_waitcnt lgkmcnt(3)
	v_mfma_f32_16x16x32_bf16 v[110:113], v[228:231], v[160:163], v[110:113]
	s_waitcnt lgkmcnt(1)
	v_mfma_f32_16x16x32_bf16 v[106:109], v[236:239], v[160:163], v[106:109]
	v_mfma_f32_16x16x32_bf16 v[94:97], v[228:231], v[192:195], v[94:97]
	v_mfma_f32_16x16x32_bf16 v[90:93], v[236:239], v[192:195], v[90:93]
	v_mfma_f32_16x16x32_bf16 v[78:81], v[228:231], v[200:203], v[78:81]
	v_mfma_f32_16x16x32_bf16 v[74:77], v[236:239], v[200:203], v[74:77]
	v_mfma_f32_16x16x32_bf16 v[70:73], v[228:231], v[220:223], v[70:73]
	v_mfma_f32_16x16x32_bf16 v[66:69], v[236:239], v[220:223], v[66:69]
	v_mfma_f32_16x16x32_bf16 v[110:113], v[232:235], v[188:191], v[110:113]
	s_waitcnt lgkmcnt(0)
	v_mfma_f32_16x16x32_bf16 v[106:109], v[240:243], v[188:191], v[106:109]
	v_mfma_f32_16x16x32_bf16 v[94:97], v[232:235], v[196:199], v[94:97]
	v_mfma_f32_16x16x32_bf16 v[90:93], v[240:243], v[196:199], v[90:93]
	v_mfma_f32_16x16x32_bf16 v[78:81], v[232:235], v[216:219], v[78:81]
	v_mfma_f32_16x16x32_bf16 v[74:77], v[240:243], v[216:219], v[74:77]
	v_mfma_f32_16x16x32_bf16 v[70:73], v[232:235], v[224:227], v[70:73]
	v_mfma_f32_16x16x32_bf16 v[66:69], v[240:243], v[224:227], v[66:69]
	s_mov_b32 m0, s58
	v_lshl_add_u64 v[244:245], s[72:73], 0, v[134:135]
	s_barrier
	ds_read_b128 v[160:163], v143 offset:16384
	ds_read_b128 v[188:191], v143 offset:17408
	ds_read_b128 v[192:195], v143 offset:18432
	ds_read_b128 v[196:199], v143 offset:19456
	ds_read_b128 v[200:203], v143 offset:20480
	ds_read_b128 v[216:219], v143 offset:21504
	ds_read_b128 v[220:223], v143 offset:22528
	ds_read_b128 v[224:227], v143 offset:23552
	global_load_lds_dwordx4 v[244:245], off
	v_lshl_add_u64 v[246:247], s[72:73], 0, v[132:133]
	s_mov_b32 m0, s74
	s_nop 0
	global_load_lds_dwordx4 v[246:247], off
	s_barrier
	s_waitcnt lgkmcnt(7)
	v_mfma_f32_16x16x32_bf16 v[62:65], v[144:147], v[160:163], v[62:65]
	v_mfma_f32_16x16x32_bf16 v[58:61], v[152:155], v[160:163], v[58:61]
	s_waitcnt lgkmcnt(5)
	v_mfma_f32_16x16x32_bf16 v[54:57], v[144:147], v[192:195], v[54:57]
	v_mfma_f32_16x16x32_bf16 v[50:53], v[152:155], v[192:195], v[50:53]
	s_waitcnt lgkmcnt(3)
	v_mfma_f32_16x16x32_bf16 v[38:41], v[144:147], v[200:203], v[38:41]
	v_mfma_f32_16x16x32_bf16 v[34:37], v[152:155], v[200:203], v[34:37]
	s_waitcnt lgkmcnt(1)
	v_mfma_f32_16x16x32_bf16 v[22:25], v[144:147], v[220:223], v[22:25]
	v_mfma_f32_16x16x32_bf16 v[18:21], v[152:155], v[220:223], v[18:21]
	v_mfma_f32_16x16x32_bf16 v[62:65], v[148:151], v[188:191], v[62:65]
	v_mfma_f32_16x16x32_bf16 v[58:61], v[156:159], v[188:191], v[58:61]
	v_mfma_f32_16x16x32_bf16 v[54:57], v[148:151], v[196:199], v[54:57]
	v_mfma_f32_16x16x32_bf16 v[50:53], v[156:159], v[196:199], v[50:53]
	v_mfma_f32_16x16x32_bf16 v[38:41], v[148:151], v[216:219], v[38:41]
	v_mfma_f32_16x16x32_bf16 v[34:37], v[156:159], v[216:219], v[34:37]
	s_waitcnt lgkmcnt(0)
	v_mfma_f32_16x16x32_bf16 v[22:25], v[148:151], v[224:227], v[22:25]
	v_mfma_f32_16x16x32_bf16 v[18:21], v[156:159], v[224:227], v[18:21]
	s_barrier
	s_add_u32 s44, s70, 0x80000
	s_addc_u32 s45, s71, 0
	s_add_i32 s2, s2, s3
	v_lshl_add_u64 v[144:145], s[44:45], 0, v[0:1]
	s_mov_b32 m0, s2
	s_nop 0
	global_load_lds_dwordx4 v[144:145], off
	v_lshl_add_u64 v[144:145], s[44:45], 0, v[130:131]
	s_add_i32 m0, s2, 0x2000
	s_nop 0
	global_load_lds_dwordx4 v[144:145], off
	s_waitcnt vmcnt(6)
	s_barrier
	v_mfma_f32_16x16x32_bf16 v[46:49], v[228:231], v[160:163], v[46:49]
	v_mfma_f32_16x16x32_bf16 v[42:45], v[236:239], v[160:163], v[42:45]
	v_mfma_f32_16x16x32_bf16 v[30:33], v[228:231], v[192:195], v[30:33]
	v_mfma_f32_16x16x32_bf16 v[26:29], v[236:239], v[192:195], v[26:29]
	v_mfma_f32_16x16x32_bf16 v[14:17], v[228:231], v[200:203], v[14:17]
	v_mfma_f32_16x16x32_bf16 v[10:13], v[236:239], v[200:203], v[10:13]
	v_mfma_f32_16x16x32_bf16 v[6:9], v[228:231], v[220:223], v[6:9]
	v_mfma_f32_16x16x32_bf16 v[2:5], v[236:239], v[220:223], v[2:5]
	v_mfma_f32_16x16x32_bf16 v[46:49], v[232:235], v[188:191], v[46:49]
	v_mfma_f32_16x16x32_bf16 v[42:45], v[240:243], v[188:191], v[42:45]
	v_mfma_f32_16x16x32_bf16 v[30:33], v[232:235], v[196:199], v[30:33]
	v_mfma_f32_16x16x32_bf16 v[26:29], v[240:243], v[196:199], v[26:29]
	v_mfma_f32_16x16x32_bf16 v[14:17], v[232:235], v[216:219], v[14:17]
	v_mfma_f32_16x16x32_bf16 v[10:13], v[240:243], v[216:219], v[10:13]
	v_mfma_f32_16x16x32_bf16 v[6:9], v[232:235], v[224:227], v[6:9]
	v_mfma_f32_16x16x32_bf16 v[2:5], v[240:243], v[224:227], v[2:5]
	s_add_i32 s2, 0, 0x18000
	v_add_u32_e32 v156, s2, v141
	s_barrier
	ds_read_b128 v[144:147], v156
	ds_read_b128 v[148:151], v156 offset:1024
	ds_read_b128 v[152:155], v156 offset:2048
	ds_read_b128 v[156:159], v156 offset:3072
	s_add_u32 s44, s72, 0x80000
	s_addc_u32 s45, s73, 0
	s_mov_b32 m0, s75
	v_lshl_add_u64 v[228:229], s[44:45], 0, v[134:135]
	ds_read_b128 v[160:163], v143 offset:32768
	ds_read_b128 v[188:191], v143 offset:33792
	ds_read_b128 v[192:195], v143 offset:34816
	ds_read_b128 v[196:199], v143 offset:35840
	ds_read_b128 v[200:203], v143 offset:36864
	ds_read_b128 v[216:219], v143 offset:37888
	ds_read_b128 v[220:223], v143 offset:38912
	ds_read_b128 v[224:227], v143 offset:39936
	global_load_lds_dwordx4 v[228:229], off
	v_lshl_add_u64 v[228:229], s[44:45], 0, v[132:133]
	s_mov_b32 m0, s77
	s_nop 0
	global_load_lds_dwordx4 v[228:229], off
	s_waitcnt lgkmcnt(8)
	s_barrier
	s_waitcnt lgkmcnt(7)
	v_mfma_f32_16x16x32_bf16 v[126:129], v[144:147], v[160:163], v[126:129]
	v_mfma_f32_16x16x32_bf16 v[122:125], v[152:155], v[160:163], v[122:125]
	s_waitcnt lgkmcnt(5)
	v_mfma_f32_16x16x32_bf16 v[118:121], v[144:147], v[192:195], v[118:121]
	v_mfma_f32_16x16x32_bf16 v[114:117], v[152:155], v[192:195], v[114:117]
	s_waitcnt lgkmcnt(3)
	v_mfma_f32_16x16x32_bf16 v[102:105], v[144:147], v[200:203], v[102:105]
	v_mfma_f32_16x16x32_bf16 v[98:101], v[152:155], v[200:203], v[98:101]
	s_waitcnt lgkmcnt(1)
	v_mfma_f32_16x16x32_bf16 v[86:89], v[144:147], v[220:223], v[86:89]
	v_mfma_f32_16x16x32_bf16 v[82:85], v[152:155], v[220:223], v[82:85]
	s_add_i32 s17, 0, 0x1c000
	v_add_u32_e32 v206, s17, v141
	ds_read_b128 v[228:231], v206
	ds_read_b128 v[232:235], v206 offset:1024
	ds_read_b128 v[236:239], v206 offset:2048
	ds_read_b128 v[240:243], v206 offset:3072
	v_mfma_f32_16x16x32_bf16 v[126:129], v[148:151], v[188:191], v[126:129]
	v_mfma_f32_16x16x32_bf16 v[122:125], v[156:159], v[188:191], v[122:125]
	v_mfma_f32_16x16x32_bf16 v[118:121], v[148:151], v[196:199], v[118:121]
	v_mfma_f32_16x16x32_bf16 v[114:117], v[156:159], v[196:199], v[114:117]
	v_mfma_f32_16x16x32_bf16 v[102:105], v[148:151], v[216:219], v[102:105]
	v_mfma_f32_16x16x32_bf16 v[98:101], v[156:159], v[216:219], v[98:101]
	s_waitcnt lgkmcnt(4)
	v_mfma_f32_16x16x32_bf16 v[86:89], v[148:151], v[224:227], v[86:89]
	v_mfma_f32_16x16x32_bf16 v[82:85], v[156:159], v[224:227], v[82:85]
	s_barrier
	s_add_i32 s2, s2, s3
	v_lshl_add_u64 v[164:165], v[164:165], 0, s[28:29]
	s_mov_b32 m0, s2
	global_load_lds_dwordx4 v[164:165], off
	v_lshl_add_u64 v[164:165], v[204:205], 0, s[28:29]
	s_add_i32 m0, s2, 0x2000
	s_nop 0
	global_load_lds_dwordx4 v[164:165], off
	s_barrier
	s_waitcnt lgkmcnt(3)
	v_mfma_f32_16x16x32_bf16 v[110:113], v[228:231], v[160:163], v[110:113]
	s_waitcnt lgkmcnt(1)
	v_mfma_f32_16x16x32_bf16 v[106:109], v[236:239], v[160:163], v[106:109]
	v_mfma_f32_16x16x32_bf16 v[94:97], v[228:231], v[192:195], v[94:97]
	v_mfma_f32_16x16x32_bf16 v[90:93], v[236:239], v[192:195], v[90:93]
	v_mfma_f32_16x16x32_bf16 v[78:81], v[228:231], v[200:203], v[78:81]
	v_mfma_f32_16x16x32_bf16 v[74:77], v[236:239], v[200:203], v[74:77]
	v_mfma_f32_16x16x32_bf16 v[70:73], v[228:231], v[220:223], v[70:73]
	v_mfma_f32_16x16x32_bf16 v[66:69], v[236:239], v[220:223], v[66:69]
	v_mfma_f32_16x16x32_bf16 v[110:113], v[232:235], v[188:191], v[110:113]
	s_waitcnt lgkmcnt(0)
	v_mfma_f32_16x16x32_bf16 v[106:109], v[240:243], v[188:191], v[106:109]
	v_mfma_f32_16x16x32_bf16 v[94:97], v[232:235], v[196:199], v[94:97]
	v_mfma_f32_16x16x32_bf16 v[90:93], v[240:243], v[196:199], v[90:93]
	v_mfma_f32_16x16x32_bf16 v[78:81], v[232:235], v[216:219], v[78:81]
	v_mfma_f32_16x16x32_bf16 v[74:77], v[240:243], v[216:219], v[74:77]
	v_mfma_f32_16x16x32_bf16 v[70:73], v[232:235], v[224:227], v[70:73]
	v_mfma_f32_16x16x32_bf16 v[66:69], v[240:243], v[224:227], v[66:69]
	s_mov_b32 m0, s78
	v_lshl_add_u64 v[164:165], v[244:245], 0, s[28:29]
	s_barrier
	ds_read_b128 v[160:163], v143 offset:49152
	ds_read_b128 v[188:191], v143 offset:50176
	ds_read_b128 v[192:195], v143 offset:51200
	ds_read_b128 v[196:199], v143 offset:52224
	ds_read_b128 v[200:203], v143 offset:53248
	ds_read_b128 v[216:219], v143 offset:54272
	ds_read_b128 v[220:223], v143 offset:55296
	ds_read_b128 v[224:227], v143 offset:56320
	global_load_lds_dwordx4 v[164:165], off
	v_lshl_add_u64 v[164:165], v[246:247], 0, s[28:29]
	s_mov_b32 m0, s79
	s_nop 0
	global_load_lds_dwordx4 v[164:165], off
	s_barrier
	s_waitcnt lgkmcnt(7)
	v_mfma_f32_16x16x32_bf16 v[62:65], v[144:147], v[160:163], v[62:65]
	v_mfma_f32_16x16x32_bf16 v[58:61], v[152:155], v[160:163], v[58:61]
	s_waitcnt lgkmcnt(5)
	v_mfma_f32_16x16x32_bf16 v[54:57], v[144:147], v[192:195], v[54:57]
	v_mfma_f32_16x16x32_bf16 v[50:53], v[152:155], v[192:195], v[50:53]
	s_waitcnt lgkmcnt(3)
	v_mfma_f32_16x16x32_bf16 v[38:41], v[144:147], v[200:203], v[38:41]
	v_mfma_f32_16x16x32_bf16 v[34:37], v[152:155], v[200:203], v[34:37]
	s_waitcnt lgkmcnt(1)
	v_mfma_f32_16x16x32_bf16 v[22:25], v[144:147], v[220:223], v[22:25]
	v_mfma_f32_16x16x32_bf16 v[18:21], v[152:155], v[220:223], v[18:21]
	v_mfma_f32_16x16x32_bf16 v[62:65], v[148:151], v[188:191], v[62:65]
	v_mfma_f32_16x16x32_bf16 v[58:61], v[156:159], v[188:191], v[58:61]
	v_mfma_f32_16x16x32_bf16 v[54:57], v[148:151], v[196:199], v[54:57]
	v_mfma_f32_16x16x32_bf16 v[50:53], v[156:159], v[196:199], v[50:53]
	v_mfma_f32_16x16x32_bf16 v[38:41], v[148:151], v[216:219], v[38:41]
	v_mfma_f32_16x16x32_bf16 v[34:37], v[156:159], v[216:219], v[34:37]
	s_waitcnt lgkmcnt(0)
	v_mfma_f32_16x16x32_bf16 v[22:25], v[148:151], v[224:227], v[22:25]
	v_mfma_f32_16x16x32_bf16 v[18:21], v[156:159], v[224:227], v[18:21]
	s_barrier
	s_add_u32 s44, s70, 0x80080
	s_addc_u32 s45, s71, 0
	s_add_i32 s2, s17, s3
	v_lshl_add_u64 v[144:145], s[44:45], 0, v[0:1]
	s_mov_b32 m0, s2
	s_nop 0
	global_load_lds_dwordx4 v[144:145], off
	v_lshl_add_u64 v[144:145], s[44:45], 0, v[130:131]
	s_add_i32 m0, s2, 0x2000
	s_nop 0
	global_load_lds_dwordx4 v[144:145], off
	s_waitcnt vmcnt(6)
	s_barrier
	v_mfma_f32_16x16x32_bf16 v[46:49], v[228:231], v[160:163], v[46:49]
	v_mfma_f32_16x16x32_bf16 v[42:45], v[236:239], v[160:163], v[42:45]
	v_mfma_f32_16x16x32_bf16 v[30:33], v[228:231], v[192:195], v[30:33]
	v_mfma_f32_16x16x32_bf16 v[26:29], v[236:239], v[192:195], v[26:29]
	v_mfma_f32_16x16x32_bf16 v[14:17], v[228:231], v[200:203], v[14:17]
	v_mfma_f32_16x16x32_bf16 v[10:13], v[236:239], v[200:203], v[10:13]
	v_mfma_f32_16x16x32_bf16 v[6:9], v[228:231], v[220:223], v[6:9]
	v_mfma_f32_16x16x32_bf16 v[2:5], v[236:239], v[220:223], v[2:5]
	v_mfma_f32_16x16x32_bf16 v[46:49], v[232:235], v[188:191], v[46:49]
	v_mfma_f32_16x16x32_bf16 v[42:45], v[240:243], v[188:191], v[42:45]
	v_mfma_f32_16x16x32_bf16 v[30:33], v[232:235], v[196:199], v[30:33]
	v_mfma_f32_16x16x32_bf16 v[26:29], v[240:243], v[196:199], v[26:29]
	v_mfma_f32_16x16x32_bf16 v[14:17], v[232:235], v[216:219], v[14:17]
	v_mfma_f32_16x16x32_bf16 v[10:13], v[240:243], v[216:219], v[10:13]
	v_mfma_f32_16x16x32_bf16 v[6:9], v[232:235], v[224:227], v[6:9]
	v_mfma_f32_16x16x32_bf16 v[2:5], v[240:243], v[224:227], v[2:5]
	s_add_i32 s83, s83, 2
	s_add_u32 s68, s68, 0x100
	s_addc_u32 s69, s69, 0
	s_add_u32 s43, s43, 0x100
	s_addc_u32 s82, s82, 0
	s_cmp_gt_u32 s83, 29
	s_barrier
	s_cbranch_scc0 .LBB0_724
	v_lshl_add_u32 v146, s47, 8, v140
	v_lshl_or_b32 v144, s46, 8, v142
	v_cvt_pk_bf16_f32 v126, v126, v127
	v_cvt_pk_bf16_f32 v127, v128, v129
	v_cvt_pk_bf16_f32 v128, v122, v123
	v_mov_b64_e32 v[122:123], s[22:23]
	v_ashrrev_i32_e32 v145, 31, v144
	v_cvt_pk_bf16_f32 v70, v70, v71
	v_cvt_pk_bf16_f32 v71, v72, v73
	v_cvt_pk_bf16_f32 v72, v66, v67
	v_add_u32_e32 v66, 0x80, v146
	v_cvt_pk_bf16_f32 v129, v124, v125
	v_mad_i64_i32 v[124:125], s[24:25], v146, s48, v[122:123]
	v_lshlrev_b64 v[144:145], 1, v[144:145]
	v_cvt_pk_bf16_f32 v62, v62, v63
	v_cvt_pk_bf16_f32 v63, v64, v65
	v_cvt_pk_bf16_f32 v64, v58, v59
	v_mad_i64_i32 v[58:59], s[24:25], v66, s48, v[122:123]
	v_lshl_add_u64 v[124:125], v[124:125], 0, v[144:145]
	v_cvt_pk_bf16_f32 v110, v110, v111
	v_cvt_pk_bf16_f32 v111, v112, v113
	v_cvt_pk_bf16_f32 v112, v106, v107
	v_cvt_pk_bf16_f32 v113, v108, v109
	v_lshl_add_u64 v[58:59], v[58:59], 0, v[144:145]
	v_cvt_pk_bf16_f32 v46, v46, v47
	v_cvt_pk_bf16_f32 v47, v48, v49
	v_cvt_pk_bf16_f32 v48, v42, v43
	v_cvt_pk_bf16_f32 v49, v44, v45
	global_store_dwordx4 v[124:125], v[110:113], off offset:256
	global_store_dwordx4 v[58:59], v[46:49], off offset:256
	v_cvt_pk_bf16_f32 v94, v94, v95
	v_or_b32_e32 v110, 16, v146
	v_add_u32_e32 v46, 0x90, v146
	v_mad_i64_i32 v[110:111], s[24:25], v110, s48, v[122:123]
	v_mad_i64_i32 v[46:47], s[24:25], v46, s48, v[122:123]
	v_lshl_add_u64 v[110:111], v[110:111], 0, v[144:145]
	v_cvt_pk_bf16_f32 v95, v96, v97
	v_cvt_pk_bf16_f32 v96, v90, v91
	v_cvt_pk_bf16_f32 v97, v92, v93
	v_lshl_add_u64 v[46:47], v[46:47], 0, v[144:145]
	v_cvt_pk_bf16_f32 v30, v30, v31
	v_cvt_pk_bf16_f32 v31, v32, v33
	v_cvt_pk_bf16_f32 v32, v26, v27
	v_cvt_pk_bf16_f32 v33, v28, v29
	global_store_dwordx4 v[110:111], v[94:97], off offset:256
	global_store_dwordx4 v[46:47], v[30:33], off offset:256
	v_cvt_pk_bf16_f32 v78, v78, v79
	v_or_b32_e32 v94, 32, v146
	v_add_u32_e32 v30, 0xa0, v146
	v_mad_i64_i32 v[94:95], s[24:25], v94, s48, v[122:123]
	v_mad_i64_i32 v[30:31], s[24:25], v30, s48, v[122:123]
	v_lshl_add_u64 v[94:95], v[94:95], 0, v[144:145]
	v_cvt_pk_bf16_f32 v79, v80, v81
	v_cvt_pk_bf16_f32 v80, v74, v75
	v_cvt_pk_bf16_f32 v81, v76, v77
	v_lshl_add_u64 v[30:31], v[30:31], 0, v[144:145]
	v_cvt_pk_bf16_f32 v14, v14, v15
	v_cvt_pk_bf16_f32 v15, v16, v17
	v_cvt_pk_bf16_f32 v16, v10, v11
	v_cvt_pk_bf16_f32 v17, v12, v13
	global_store_dwordx4 v[94:95], v[78:81], off offset:256
	global_store_dwordx4 v[30:31], v[14:17], off offset:256
	v_cvt_pk_bf16_f32 v106, v118, v119
	v_or_b32_e32 v78, 48, v146
	v_add_u32_e32 v14, 0xb0, v146
	v_mad_i64_i32 v[78:79], s[24:25], v78, s48, v[122:123]
	v_mad_i64_i32 v[14:15], s[24:25], v14, s48, v[122:123]
	v_cvt_pk_bf16_f32 v107, v120, v121
	v_cvt_pk_bf16_f32 v108, v114, v115
	v_cvt_pk_bf16_f32 v109, v116, v117
	v_cvt_pk_bf16_f32 v90, v102, v103
	v_cvt_pk_bf16_f32 v91, v104, v105
	v_cvt_pk_bf16_f32 v92, v98, v99
	v_cvt_pk_bf16_f32 v93, v100, v101
	v_cvt_pk_bf16_f32 v74, v86, v87
	v_cvt_pk_bf16_f32 v75, v88, v89
	v_cvt_pk_bf16_f32 v76, v82, v83
	v_cvt_pk_bf16_f32 v77, v84, v85
	v_lshl_add_u64 v[78:79], v[78:79], 0, v[144:145]
	v_cvt_pk_bf16_f32 v73, v68, v69
	v_cvt_pk_bf16_f32 v65, v60, v61
	v_cvt_pk_bf16_f32 v42, v54, v55
	v_cvt_pk_bf16_f32 v43, v56, v57
	v_cvt_pk_bf16_f32 v44, v50, v51
	v_cvt_pk_bf16_f32 v45, v52, v53
	v_cvt_pk_bf16_f32 v26, v38, v39
	v_cvt_pk_bf16_f32 v27, v40, v41
	v_cvt_pk_bf16_f32 v28, v34, v35
	v_cvt_pk_bf16_f32 v29, v36, v37
	v_cvt_pk_bf16_f32 v10, v22, v23
	v_cvt_pk_bf16_f32 v11, v24, v25
	v_cvt_pk_bf16_f32 v12, v18, v19
	v_cvt_pk_bf16_f32 v13, v20, v21
	v_lshl_add_u64 v[14:15], v[14:15], 0, v[144:145]
	v_cvt_pk_bf16_f32 v6, v6, v7
	v_cvt_pk_bf16_f32 v7, v8, v9
	v_cvt_pk_bf16_f32 v8, v2, v3
	v_cvt_pk_bf16_f32 v9, v4, v5
	s_and_b64 vcc, exec, s[0:1]
	s_mov_b32 s46, s42
	s_mov_b32 s47, s54
	s_mov_b64 s[70:71], s[64:65]
	s_mov_b64 s[68:69], s[62:63]
	global_store_dwordx4 v[124:125], v[126:129], off
	global_store_dwordx4 v[110:111], v[106:109], off
	global_store_dwordx4 v[94:95], v[90:93], off
	global_store_dwordx4 v[78:79], v[74:77], off
	global_store_dwordx4 v[78:79], v[70:73], off offset:256
	global_store_dwordx4 v[58:59], v[62:65], off
	global_store_dwordx4 v[46:47], v[42:45], off
	global_store_dwordx4 v[30:31], v[26:29], off
	global_store_dwordx4 v[14:15], v[10:13], off
	global_store_dwordx4 v[14:15], v[6:9], off offset:256
	s_cbranch_vccz .LBB0_721
	v_readlane_b32 s0, v254, 12
	s_waitcnt vmcnt(0)
	v_readlane_b32 s1, v254, 13
	s_andn2_b64 vcc, exec, s[0:1]
	s_cbranch_vccnz .LBB0_728
	s_barrier

.LBB0_977:
	s_add_u32 s2, s70, 0xfffc0080
	s_addc_u32 s17, s71, -1
	s_add_i32 s26, 0, 0x10000
	v_add_u32_e32 v152, s26, v163
	ds_read_b128 v[130:133], v152
	ds_read_b128 v[134:137], v152 offset:1024
	ds_read_b128 v[148:151], v152 offset:2048
	ds_read_b128 v[152:155], v152 offset:3072
	s_cmp_eq_u32 s44, 12
	s_cselect_b32 s75, s41, s17
	s_cselect_b32 s74, s24, s2
	s_cselect_b32 s73, s25, vcc_hi
	s_cselect_b32 s72, s93, vcc_lo
	v_lshl_add_u64 v[160:161], s[70:71], 0, v[144:145]
	s_add_i32 m0, s58, 0xc000
	ds_read_b128 v[156:159], v165
	ds_read_b128 v[188:191], v165 offset:1024
	ds_read_b128 v[192:195], v165 offset:2048
	ds_read_b128 v[196:199], v165 offset:3072
	ds_read_b128 v[200:203], v165 offset:4096
	ds_read_b128 v[216:219], v165 offset:5120
	ds_read_b128 v[220:223], v165 offset:6144
	ds_read_b128 v[224:227], v165 offset:7168
	global_load_lds_dwordx4 v[160:161], off
	v_lshl_add_u64 v[160:161], s[70:71], 0, v[146:147]
	s_add_i32 m0, s58, 0xe000
	s_nop 0
	global_load_lds_dwordx4 v[160:161], off
	s_waitcnt lgkmcnt(8)
	s_barrier
	s_waitcnt lgkmcnt(7)
	v_mfma_f32_16x16x32_bf16 v[126:129], v[130:133], v[156:159], v[126:129]
	v_mfma_f32_16x16x32_bf16 v[122:125], v[148:151], v[156:159], v[122:125]
	s_waitcnt lgkmcnt(5)
	v_mfma_f32_16x16x32_bf16 v[110:113], v[130:133], v[192:195], v[110:113]
	v_mfma_f32_16x16x32_bf16 v[106:109], v[148:151], v[192:195], v[106:109]
	s_waitcnt lgkmcnt(3)
	v_mfma_f32_16x16x32_bf16 v[94:97], v[130:133], v[200:203], v[94:97]
	v_mfma_f32_16x16x32_bf16 v[90:93], v[148:151], v[200:203], v[90:93]
	s_waitcnt lgkmcnt(1)
	v_mfma_f32_16x16x32_bf16 v[78:81], v[130:133], v[220:223], v[78:81]
	v_mfma_f32_16x16x32_bf16 v[74:77], v[148:151], v[220:223], v[74:77]
	s_add_i32 s2, 0, 0x14000
	v_add_u32_e32 v160, s2, v163
	ds_read_b128 v[228:231], v160
	ds_read_b128 v[232:235], v160 offset:1024
	ds_read_b128 v[236:239], v160 offset:2048
	ds_read_b128 v[240:243], v160 offset:3072
	v_mfma_f32_16x16x32_bf16 v[126:129], v[134:137], v[188:191], v[126:129]
	v_mfma_f32_16x16x32_bf16 v[122:125], v[152:155], v[188:191], v[122:125]
	v_mfma_f32_16x16x32_bf16 v[110:113], v[134:137], v[196:199], v[110:113]
	v_mfma_f32_16x16x32_bf16 v[106:109], v[152:155], v[196:199], v[106:109]
	v_mfma_f32_16x16x32_bf16 v[94:97], v[134:137], v[216:219], v[94:97]
	v_mfma_f32_16x16x32_bf16 v[90:93], v[152:155], v[216:219], v[90:93]
	s_waitcnt lgkmcnt(4)
	v_mfma_f32_16x16x32_bf16 v[78:81], v[134:137], v[224:227], v[78:81]
	v_mfma_f32_16x16x32_bf16 v[74:77], v[152:155], v[224:227], v[74:77]
	s_barrier
	s_add_i32 s17, s26, s3
	v_lshl_add_u64 v[160:161], s[72:73], 0, v[0:1]
	s_mov_b32 m0, s17
	v_lshl_add_u64 v[204:205], s[72:73], 0, v[138:139]
	global_load_lds_dwordx4 v[160:161], off
	s_add_i32 m0, s17, 0x2000
	s_nop 0
	global_load_lds_dwordx4 v[204:205], off
	s_barrier
	s_waitcnt lgkmcnt(3)
	v_mfma_f32_16x16x32_bf16 v[118:121], v[228:231], v[156:159], v[118:121]
	s_waitcnt lgkmcnt(1)
	v_mfma_f32_16x16x32_bf16 v[114:117], v[236:239], v[156:159], v[114:117]
	v_mfma_f32_16x16x32_bf16 v[102:105], v[228:231], v[192:195], v[102:105]
	v_mfma_f32_16x16x32_bf16 v[98:101], v[236:239], v[192:195], v[98:101]
	v_mfma_f32_16x16x32_bf16 v[86:89], v[228:231], v[200:203], v[86:89]
	v_mfma_f32_16x16x32_bf16 v[82:85], v[236:239], v[200:203], v[82:85]
	v_mfma_f32_16x16x32_bf16 v[70:73], v[228:231], v[220:223], v[70:73]
	v_mfma_f32_16x16x32_bf16 v[66:69], v[236:239], v[220:223], v[66:69]
	v_mfma_f32_16x16x32_bf16 v[118:121], v[232:235], v[188:191], v[118:121]
	s_waitcnt lgkmcnt(0)
	v_mfma_f32_16x16x32_bf16 v[114:117], v[240:243], v[188:191], v[114:117]
	v_mfma_f32_16x16x32_bf16 v[102:105], v[232:235], v[196:199], v[102:105]
	v_mfma_f32_16x16x32_bf16 v[98:101], v[240:243], v[196:199], v[98:101]
	v_mfma_f32_16x16x32_bf16 v[86:89], v[232:235], v[216:219], v[86:89]
	v_mfma_f32_16x16x32_bf16 v[82:85], v[240:243], v[216:219], v[82:85]
	v_mfma_f32_16x16x32_bf16 v[70:73], v[232:235], v[224:227], v[70:73]
	v_mfma_f32_16x16x32_bf16 v[66:69], v[240:243], v[224:227], v[66:69]
	s_mov_b32 m0, s58
	v_lshl_add_u64 v[244:245], s[74:75], 0, v[142:143]
	s_barrier
	ds_read_b128 v[156:159], v165 offset:16384
	ds_read_b128 v[188:191], v165 offset:17408
	ds_read_b128 v[192:195], v165 offset:18432
	ds_read_b128 v[196:199], v165 offset:19456
	ds_read_b128 v[200:203], v165 offset:20480
	ds_read_b128 v[216:219], v165 offset:21504
	ds_read_b128 v[220:223], v165 offset:22528
	ds_read_b128 v[224:227], v165 offset:23552
	global_load_lds_dwordx4 v[244:245], off
	v_lshl_add_u64 v[246:247], s[74:75], 0, v[140:141]
	s_mov_b32 m0, s76
	s_nop 0
	global_load_lds_dwordx4 v[246:247], off
	s_barrier
	s_waitcnt lgkmcnt(7)
	v_mfma_f32_16x16x32_bf16 v[62:65], v[130:133], v[156:159], v[62:65]
	v_mfma_f32_16x16x32_bf16 v[58:61], v[148:151], v[156:159], v[58:61]
	s_waitcnt lgkmcnt(5)
	v_mfma_f32_16x16x32_bf16 v[46:49], v[130:133], v[192:195], v[46:49]
	v_mfma_f32_16x16x32_bf16 v[42:45], v[148:151], v[192:195], v[42:45]
	s_waitcnt lgkmcnt(3)
	v_mfma_f32_16x16x32_bf16 v[30:33], v[130:133], v[200:203], v[30:33]
	v_mfma_f32_16x16x32_bf16 v[26:29], v[148:151], v[200:203], v[26:29]
	s_waitcnt lgkmcnt(1)
	v_mfma_f32_16x16x32_bf16 v[14:17], v[130:133], v[220:223], v[14:17]
	v_mfma_f32_16x16x32_bf16 v[10:13], v[148:151], v[220:223], v[10:13]
	v_mfma_f32_16x16x32_bf16 v[62:65], v[134:137], v[188:191], v[62:65]
	v_mfma_f32_16x16x32_bf16 v[58:61], v[152:155], v[188:191], v[58:61]
	v_mfma_f32_16x16x32_bf16 v[46:49], v[134:137], v[196:199], v[46:49]
	v_mfma_f32_16x16x32_bf16 v[42:45], v[152:155], v[196:199], v[42:45]
	v_mfma_f32_16x16x32_bf16 v[30:33], v[134:137], v[216:219], v[30:33]
	v_mfma_f32_16x16x32_bf16 v[26:29], v[152:155], v[216:219], v[26:29]
	s_waitcnt lgkmcnt(0)
	v_mfma_f32_16x16x32_bf16 v[14:17], v[134:137], v[224:227], v[14:17]
	v_mfma_f32_16x16x32_bf16 v[10:13], v[152:155], v[224:227], v[10:13]
	s_barrier
	s_add_u32 s26, s72, 0x40000
	s_addc_u32 s27, s73, 0
	s_add_i32 s2, s2, s3
	v_lshl_add_u64 v[130:131], s[26:27], 0, v[0:1]
	s_mov_b32 m0, s2
	s_nop 0
	global_load_lds_dwordx4 v[130:131], off
	v_lshl_add_u64 v[130:131], s[26:27], 0, v[138:139]
	s_add_i32 m0, s2, 0x2000
	s_nop 0
	global_load_lds_dwordx4 v[130:131], off
	s_waitcnt vmcnt(6)
	s_barrier
	v_mfma_f32_16x16x32_bf16 v[54:57], v[228:231], v[156:159], v[54:57]
	v_mfma_f32_16x16x32_bf16 v[50:53], v[236:239], v[156:159], v[50:53]
	v_mfma_f32_16x16x32_bf16 v[38:41], v[228:231], v[192:195], v[38:41]
	v_mfma_f32_16x16x32_bf16 v[34:37], v[236:239], v[192:195], v[34:37]
	v_mfma_f32_16x16x32_bf16 v[22:25], v[228:231], v[200:203], v[22:25]
	v_mfma_f32_16x16x32_bf16 v[18:21], v[236:239], v[200:203], v[18:21]
	v_mfma_f32_16x16x32_bf16 v[6:9], v[228:231], v[220:223], v[6:9]
	v_mfma_f32_16x16x32_bf16 v[2:5], v[236:239], v[220:223], v[2:5]
	v_mfma_f32_16x16x32_bf16 v[54:57], v[232:235], v[188:191], v[54:57]
	v_mfma_f32_16x16x32_bf16 v[50:53], v[240:243], v[188:191], v[50:53]
	v_mfma_f32_16x16x32_bf16 v[38:41], v[232:235], v[196:199], v[38:41]
	v_mfma_f32_16x16x32_bf16 v[34:37], v[240:243], v[196:199], v[34:37]
	v_mfma_f32_16x16x32_bf16 v[22:25], v[232:235], v[216:219], v[22:25]
	v_mfma_f32_16x16x32_bf16 v[18:21], v[240:243], v[216:219], v[18:21]
	v_mfma_f32_16x16x32_bf16 v[6:9], v[232:235], v[224:227], v[6:9]
	v_mfma_f32_16x16x32_bf16 v[2:5], v[240:243], v[224:227], v[2:5]
	s_add_i32 s2, 0, 0x18000
	v_add_u32_e32 v152, s2, v163
	s_barrier
	ds_read_b128 v[130:133], v152
	ds_read_b128 v[134:137], v152 offset:1024
	ds_read_b128 v[148:151], v152 offset:2048
	ds_read_b128 v[152:155], v152 offset:3072
	s_add_u32 s26, s74, 0x40000
	s_addc_u32 s27, s75, 0
	s_mov_b32 m0, s77
	v_lshl_add_u64 v[228:229], s[26:27], 0, v[142:143]
	ds_read_b128 v[156:159], v165 offset:32768
	ds_read_b128 v[188:191], v165 offset:33792
	ds_read_b128 v[192:195], v165 offset:34816
	ds_read_b128 v[196:199], v165 offset:35840
	ds_read_b128 v[200:203], v165 offset:36864
	ds_read_b128 v[216:219], v165 offset:37888
	ds_read_b128 v[220:223], v165 offset:38912
	ds_read_b128 v[224:227], v165 offset:39936
	global_load_lds_dwordx4 v[228:229], off
	v_lshl_add_u64 v[228:229], s[26:27], 0, v[140:141]
	s_mov_b32 m0, s78
	s_nop 0
	global_load_lds_dwordx4 v[228:229], off
	s_waitcnt lgkmcnt(8)
	s_barrier
	s_waitcnt lgkmcnt(7)
	v_mfma_f32_16x16x32_bf16 v[126:129], v[130:133], v[156:159], v[126:129]
	v_mfma_f32_16x16x32_bf16 v[122:125], v[148:151], v[156:159], v[122:125]
	s_waitcnt lgkmcnt(5)
	v_mfma_f32_16x16x32_bf16 v[110:113], v[130:133], v[192:195], v[110:113]
	v_mfma_f32_16x16x32_bf16 v[106:109], v[148:151], v[192:195], v[106:109]
	s_waitcnt lgkmcnt(3)
	v_mfma_f32_16x16x32_bf16 v[94:97], v[130:133], v[200:203], v[94:97]
	v_mfma_f32_16x16x32_bf16 v[90:93], v[148:151], v[200:203], v[90:93]
	s_waitcnt lgkmcnt(1)
	v_mfma_f32_16x16x32_bf16 v[78:81], v[130:133], v[220:223], v[78:81]
	v_mfma_f32_16x16x32_bf16 v[74:77], v[148:151], v[220:223], v[74:77]
	s_add_i32 s17, 0, 0x1c000
	v_add_u32_e32 v206, s17, v163
	ds_read_b128 v[228:231], v206
	ds_read_b128 v[232:235], v206 offset:1024
	ds_read_b128 v[236:239], v206 offset:2048
	ds_read_b128 v[240:243], v206 offset:3072
	v_mfma_f32_16x16x32_bf16 v[126:129], v[134:137], v[188:191], v[126:129]
	v_mfma_f32_16x16x32_bf16 v[122:125], v[152:155], v[188:191], v[122:125]
	v_mfma_f32_16x16x32_bf16 v[110:113], v[134:137], v[196:199], v[110:113]
	v_mfma_f32_16x16x32_bf16 v[106:109], v[152:155], v[196:199], v[106:109]
	v_mfma_f32_16x16x32_bf16 v[94:97], v[134:137], v[216:219], v[94:97]
	v_mfma_f32_16x16x32_bf16 v[90:93], v[152:155], v[216:219], v[90:93]
	s_waitcnt lgkmcnt(4)
	v_mfma_f32_16x16x32_bf16 v[78:81], v[134:137], v[224:227], v[78:81]
	v_mfma_f32_16x16x32_bf16 v[74:77], v[152:155], v[224:227], v[74:77]
	s_barrier
	s_add_i32 s2, s2, s3
	v_lshl_add_u64 v[160:161], v[160:161], 0, s[28:29]
	s_mov_b32 m0, s2
	global_load_lds_dwordx4 v[160:161], off
	v_lshl_add_u64 v[160:161], v[204:205], 0, s[28:29]
	s_add_i32 m0, s2, 0x2000
	s_nop 0
	global_load_lds_dwordx4 v[160:161], off
	s_barrier
	s_waitcnt lgkmcnt(3)
	v_mfma_f32_16x16x32_bf16 v[118:121], v[228:231], v[156:159], v[118:121]
	s_waitcnt lgkmcnt(1)
	v_mfma_f32_16x16x32_bf16 v[114:117], v[236:239], v[156:159], v[114:117]
	v_mfma_f32_16x16x32_bf16 v[102:105], v[228:231], v[192:195], v[102:105]
	v_mfma_f32_16x16x32_bf16 v[98:101], v[236:239], v[192:195], v[98:101]
	v_mfma_f32_16x16x32_bf16 v[86:89], v[228:231], v[200:203], v[86:89]
	v_mfma_f32_16x16x32_bf16 v[82:85], v[236:239], v[200:203], v[82:85]
	v_mfma_f32_16x16x32_bf16 v[70:73], v[228:231], v[220:223], v[70:73]
	v_mfma_f32_16x16x32_bf16 v[66:69], v[236:239], v[220:223], v[66:69]
	v_mfma_f32_16x16x32_bf16 v[118:121], v[232:235], v[188:191], v[118:121]
	s_waitcnt lgkmcnt(0)
	v_mfma_f32_16x16x32_bf16 v[114:117], v[240:243], v[188:191], v[114:117]
	v_mfma_f32_16x16x32_bf16 v[102:105], v[232:235], v[196:199], v[102:105]
	v_mfma_f32_16x16x32_bf16 v[98:101], v[240:243], v[196:199], v[98:101]
	v_mfma_f32_16x16x32_bf16 v[86:89], v[232:235], v[216:219], v[86:89]
	v_mfma_f32_16x16x32_bf16 v[82:85], v[240:243], v[216:219], v[82:85]
	v_mfma_f32_16x16x32_bf16 v[70:73], v[232:235], v[224:227], v[70:73]
	v_mfma_f32_16x16x32_bf16 v[66:69], v[240:243], v[224:227], v[66:69]
	s_mov_b32 m0, s79
	v_lshl_add_u64 v[160:161], v[244:245], 0, s[28:29]
	s_barrier
	ds_read_b128 v[156:159], v165 offset:49152
	ds_read_b128 v[188:191], v165 offset:50176
	ds_read_b128 v[192:195], v165 offset:51200
	ds_read_b128 v[196:199], v165 offset:52224
	ds_read_b128 v[200:203], v165 offset:53248
	ds_read_b128 v[216:219], v165 offset:54272
	ds_read_b128 v[220:223], v165 offset:55296
	ds_read_b128 v[224:227], v165 offset:56320
	global_load_lds_dwordx4 v[160:161], off
	v_lshl_add_u64 v[160:161], v[246:247], 0, s[28:29]
	s_mov_b32 m0, s83
	s_nop 0
	global_load_lds_dwordx4 v[160:161], off
	s_barrier
	s_waitcnt lgkmcnt(7)
	v_mfma_f32_16x16x32_bf16 v[62:65], v[130:133], v[156:159], v[62:65]
	v_mfma_f32_16x16x32_bf16 v[58:61], v[148:151], v[156:159], v[58:61]
	s_waitcnt lgkmcnt(5)
	v_mfma_f32_16x16x32_bf16 v[46:49], v[130:133], v[192:195], v[46:49]
	v_mfma_f32_16x16x32_bf16 v[42:45], v[148:151], v[192:195], v[42:45]
	s_waitcnt lgkmcnt(3)
	v_mfma_f32_16x16x32_bf16 v[30:33], v[130:133], v[200:203], v[30:33]
	v_mfma_f32_16x16x32_bf16 v[26:29], v[148:151], v[200:203], v[26:29]
	s_waitcnt lgkmcnt(1)
	v_mfma_f32_16x16x32_bf16 v[14:17], v[130:133], v[220:223], v[14:17]
	v_mfma_f32_16x16x32_bf16 v[10:13], v[148:151], v[220:223], v[10:13]
	v_mfma_f32_16x16x32_bf16 v[62:65], v[134:137], v[188:191], v[62:65]
	v_mfma_f32_16x16x32_bf16 v[58:61], v[152:155], v[188:191], v[58:61]
	v_mfma_f32_16x16x32_bf16 v[46:49], v[134:137], v[196:199], v[46:49]
	v_mfma_f32_16x16x32_bf16 v[42:45], v[152:155], v[196:199], v[42:45]
	v_mfma_f32_16x16x32_bf16 v[30:33], v[134:137], v[216:219], v[30:33]
	v_mfma_f32_16x16x32_bf16 v[26:29], v[152:155], v[216:219], v[26:29]
	s_waitcnt lgkmcnt(0)
	v_mfma_f32_16x16x32_bf16 v[14:17], v[134:137], v[224:227], v[14:17]
	v_mfma_f32_16x16x32_bf16 v[10:13], v[152:155], v[224:227], v[10:13]
	s_barrier
	s_add_u32 s26, s72, 0x40080
	s_addc_u32 s27, s73, 0
	s_add_i32 s2, s17, s3
	v_lshl_add_u64 v[130:131], s[26:27], 0, v[0:1]
	s_mov_b32 m0, s2
	s_nop 0
	global_load_lds_dwordx4 v[130:131], off
	v_lshl_add_u64 v[130:131], s[26:27], 0, v[138:139]
	s_add_i32 m0, s2, 0x2000
	s_nop 0
	global_load_lds_dwordx4 v[130:131], off
	s_waitcnt vmcnt(6)
	s_barrier
	v_mfma_f32_16x16x32_bf16 v[54:57], v[228:231], v[156:159], v[54:57]
	v_mfma_f32_16x16x32_bf16 v[50:53], v[236:239], v[156:159], v[50:53]
	v_mfma_f32_16x16x32_bf16 v[38:41], v[228:231], v[192:195], v[38:41]
	v_mfma_f32_16x16x32_bf16 v[34:37], v[236:239], v[192:195], v[34:37]
	v_mfma_f32_16x16x32_bf16 v[22:25], v[228:231], v[200:203], v[22:25]
	v_mfma_f32_16x16x32_bf16 v[18:21], v[236:239], v[200:203], v[18:21]
	v_mfma_f32_16x16x32_bf16 v[6:9], v[228:231], v[220:223], v[6:9]
	v_mfma_f32_16x16x32_bf16 v[2:5], v[236:239], v[220:223], v[2:5]
	v_mfma_f32_16x16x32_bf16 v[54:57], v[232:235], v[188:191], v[54:57]
	v_mfma_f32_16x16x32_bf16 v[50:53], v[240:243], v[188:191], v[50:53]
	v_mfma_f32_16x16x32_bf16 v[38:41], v[232:235], v[196:199], v[38:41]
	v_mfma_f32_16x16x32_bf16 v[34:37], v[240:243], v[196:199], v[34:37]
	v_mfma_f32_16x16x32_bf16 v[22:25], v[232:235], v[216:219], v[22:25]
	v_mfma_f32_16x16x32_bf16 v[18:21], v[240:243], v[216:219], v[18:21]
	v_mfma_f32_16x16x32_bf16 v[6:9], v[232:235], v[224:227], v[6:9]
	v_mfma_f32_16x16x32_bf16 v[2:5], v[240:243], v[224:227], v[2:5]
	s_add_i32 s44, s44, 2
	s_add_u32 s70, s70, 0x100
	s_addc_u32 s71, s71, 0
	s_add_u32 vcc_lo, vcc_lo, 0x100
	s_addc_u32 vcc_hi, vcc_hi, 0
	s_cmp_gt_u32 s44, 13
	s_barrier
	s_cbranch_scc0 .LBB0_977
	v_lshl_add_u32 v152, s47, 8, v162
	v_lshl_or_b32 v130, s46, 8, v164
	v_ashrrev_i32_e32 v153, 31, v152
	v_lshlrev_b64 v[136:137], 11, v[152:153]
	v_ashrrev_i32_e32 v131, 31, v130
	v_lshl_add_u64 v[136:137], s[56:57], 0, v[136:137]
	v_lshlrev_b64 v[150:151], 1, v[130:131]
	v_mov_b64_e32 v[154:155], s[22:23]
	v_lshl_add_u64 v[156:157], v[136:137], 0, v[150:151]
	v_mad_i64_i32 v[136:137], s[24:25], v152, s48, v[154:155]
	v_lshl_add_u64 v[160:161], v[136:137], 0, s[94:95]
	v_lshl_add_u64 v[148:149], v[130:131], 2, s[54:55]
	v_lshl_add_u64 v[136:137], v[160:161], 0, v[150:151]
	global_load_dwordx4 v[132:135], v[148:149], off offset:16
	global_load_dwordx4 v[188:191], v[148:149], off
	global_load_dwordx4 v[192:195], v[156:157], off
	global_load_dwordx4 v[196:199], v[136:137], off
	s_and_b64 vcc, exec, s[6:7]
	s_mov_b32 s46, s92
	s_mov_b32 s47, s40
	s_mov_b64 s[72:73], s[68:69]
	s_mov_b64 s[70:71], s[42:43]
	v_readlane_b32 s93, v251, 60
	s_waitcnt vmcnt(0)
	v_add_f32_e32 v122, v122, v132
	v_add_f32_e32 v126, v126, v188
	v_add_f32_e32 v127, v127, v189
	v_lshlrev_b32_e32 v158, 16, v196
	v_mul_f32_e32 v131, 0xbfb8aa3b, v158
	v_exp_f32_e32 v131, v131
	v_and_b32_e32 v159, 0xffff0000, v196
	v_mul_f32_e32 v126, 0xbfb8aa3b, v126
	v_mul_f32_e32 v127, 0xbfb8aa3b, v127
	v_add_f32_e32 v131, 1.0, v131
	v_rcp_f32_e32 v188, v131
	v_mul_f32_e32 v131, 0xbfb8aa3b, v159
	v_exp_f32_e32 v126, v126
	v_exp_f32_e32 v127, v127
	v_exp_f32_e32 v131, v131
	v_lshlrev_b32_e32 v136, 16, v192
	v_add_f32_e32 v126, 1.0, v126
	v_add_f32_e32 v127, 1.0, v127
	v_add_f32_e32 v131, 1.0, v131
	v_rcp_f32_e32 v126, v126
	v_rcp_f32_e32 v127, v127
	v_rcp_f32_e32 v189, v131
	v_and_b32_e32 v137, 0xffff0000, v192
	v_add_f32_e32 v123, v123, v133
	v_pk_mul_f32 v[126:127], v[126:127], v[136:137]
	v_pk_mul_f32 v[136:137], v[188:189], v[158:159]
	v_mul_f32_e32 v122, 0xbfb8aa3b, v122
	v_pk_mul_f32 v[126:127], v[126:127], v[136:137]
	v_lshlrev_b32_e32 v136, 16, v198
	v_mul_f32_e32 v131, 0xbfb8aa3b, v136
	v_exp_f32_e32 v131, v131
	v_and_b32_e32 v137, 0xffff0000, v198
	v_mul_f32_e32 v123, 0xbfb8aa3b, v123
	v_exp_f32_e32 v122, v122
	v_add_f32_e32 v131, 1.0, v131
	v_rcp_f32_e32 v158, v131
	v_mul_f32_e32 v131, 0xbfb8aa3b, v137
	v_exp_f32_e32 v123, v123
	v_exp_f32_e32 v131, v131
	v_add_f32_e32 v122, 1.0, v122
	v_rcp_f32_e32 v122, v122
	v_add_f32_e32 v123, 1.0, v123
	v_add_f32_e32 v131, 1.0, v131
	v_rcp_f32_e32 v123, v123
	v_rcp_f32_e32 v159, v131
	v_lshlrev_b32_e32 v132, 16, v194
	v_and_b32_e32 v133, 0xffff0000, v194
	v_pk_mul_f32 v[122:123], v[122:123], v[132:133]
	v_pk_mul_f32 v[132:133], v[158:159], v[136:137]
	v_lshlrev_b32_e32 v136, 16, v197
	v_pk_mul_f32 v[132:133], v[122:123], v[132:133]
	v_add_f32_e32 v123, v124, v134
	v_mul_f32_e32 v123, 0xbfb8aa3b, v123
	v_exp_f32_e32 v123, v123
	v_add_f32_e32 v122, v128, v190
	v_mul_f32_e32 v122, 0xbfb8aa3b, v122
	v_exp_f32_e32 v122, v122
	v_add_f32_e32 v123, 1.0, v123
	v_rcp_f32_e32 v124, v123
	v_add_f32_e32 v123, v129, v191
	v_mul_f32_e32 v123, 0xbfb8aa3b, v123
	v_exp_f32_e32 v123, v123
	v_add_f32_e32 v122, 1.0, v122
	v_rcp_f32_e32 v122, v122
	v_lshlrev_b32_e32 v128, 16, v193
	v_add_f32_e32 v123, 1.0, v123
	v_rcp_f32_e32 v123, v123
	v_and_b32_e32 v129, 0xffff0000, v193
	v_and_b32_e32 v137, 0xffff0000, v197
	v_mul_f32_e32 v131, 0xbfb8aa3b, v136
	v_pk_mul_f32 v[122:123], v[122:123], v[128:129]
	v_mul_f32_e32 v128, 0xbfb8aa3b, v137
	v_exp_f32_e32 v131, v131
	v_exp_f32_e32 v128, v128
	v_lshlrev_b32_e32 v134, 16, v199
	v_add_f32_e32 v131, 1.0, v131
	v_add_f32_e32 v128, 1.0, v128
	v_rcp_f32_e32 v158, v131
	v_rcp_f32_e32 v159, v128
	v_mul_f32_e32 v131, 0xbfb8aa3b, v134
	v_exp_f32_e32 v131, v131
	v_pk_mul_f32 v[128:129], v[158:159], v[136:137]
	s_nop 0
	v_pk_mul_f32 v[128:129], v[122:123], v[128:129]
	v_add_f32_e32 v122, v125, v135
	v_mul_f32_e32 v122, 0xbfb8aa3b, v122
	v_exp_f32_e32 v122, v122
	v_and_b32_e32 v123, 0xffff0000, v195
	v_and_b32_e32 v135, 0xffff0000, v199
	v_add_f32_e32 v131, 1.0, v131
	v_add_f32_e32 v122, 1.0, v122
	v_rcp_f32_e32 v125, v122
	v_lshlrev_b32_e32 v122, 16, v195
	v_rcp_f32_e32 v136, v131
	v_pk_mul_f32 v[122:123], v[124:125], v[122:123]
	v_mul_f32_e32 v124, 0xbfb8aa3b, v135
	v_exp_f32_e32 v124, v124
	s_nop 0
	v_add_f32_e32 v124, 1.0, v124
	v_rcp_f32_e32 v137, v124
	s_nop 0
	v_pk_mul_f32 v[124:125], v[136:137], v[134:135]
	s_nop 0
	v_pk_mul_f32 v[134:135], v[122:123], v[124:125]
	v_cvt_pk_bf16_f32 v122, v126, v127
	v_lshlrev_b64 v[126:127], 12, v[152:153]
	v_lshl_add_u64 v[126:127], s[36:37], 0, v[126:127]
	v_cvt_pk_bf16_f32 v123, v128, v129
	v_cvt_pk_bf16_f32 v124, v132, v133
	v_cvt_pk_bf16_f32 v125, v134, v135
	v_lshl_add_u64 v[158:159], v[126:127], 0, v[150:151]
	v_or_b32_e32 v126, 0x80, v130
	global_store_dwordx4 v[158:159], v[122:125], off offset:2048
	v_ashrrev_i32_e32 v127, 31, v126
	global_load_dwordx4 v[130:133], v[148:149], off offset:528
	global_load_dwordx4 v[134:137], v[148:149], off offset:512
	global_load_dwordx4 v[122:125], v[156:157], off offset:256
	v_lshlrev_b64 v[156:157], 1, v[126:127]
	v_lshl_add_u64 v[126:127], v[160:161], 0, v[156:157]
	global_load_dwordx4 v[126:129], v[126:127], off
	s_waitcnt vmcnt(0)
	v_add_f32_e32 v114, v114, v130
	v_add_f32_e32 v118, v118, v134
	v_add_f32_e32 v119, v119, v135
	v_lshlrev_b32_e32 v134, 16, v122
	v_and_b32_e32 v135, 0xffff0000, v122
	v_lshlrev_b32_e32 v160, 16, v126
	v_mul_f32_e32 v122, 0xbfb8aa3b, v160
	v_exp_f32_e32 v122, v122
	v_and_b32_e32 v161, 0xffff0000, v126
	v_mul_f32_e32 v118, 0xbfb8aa3b, v118
	v_mul_f32_e32 v119, 0xbfb8aa3b, v119
	v_add_f32_e32 v122, 1.0, v122
	v_rcp_f32_e32 v188, v122
	v_mul_f32_e32 v122, 0xbfb8aa3b, v161
	v_exp_f32_e32 v118, v118
	v_exp_f32_e32 v119, v119
	v_exp_f32_e32 v122, v122
	v_add_f32_e32 v120, v120, v136
	v_add_f32_e32 v118, 1.0, v118
	v_add_f32_e32 v119, 1.0, v119
	v_add_f32_e32 v122, 1.0, v122
	v_rcp_f32_e32 v118, v118
	v_rcp_f32_e32 v119, v119
	v_rcp_f32_e32 v189, v122
	v_add_f32_e32 v121, v121, v137
	v_mul_f32_e32 v120, 0xbfb8aa3b, v120
	v_pk_mul_f32 v[118:119], v[118:119], v[134:135]
	v_pk_mul_f32 v[134:135], v[188:189], v[160:161]
	v_mul_f32_e32 v121, 0xbfb8aa3b, v121
	v_pk_mul_f32 v[118:119], v[118:119], v[134:135]
	v_lshlrev_b32_e32 v134, 16, v128
	v_mul_f32_e32 v122, 0xbfb8aa3b, v134
	v_exp_f32_e32 v122, v122
	v_exp_f32_e32 v120, v120
	v_exp_f32_e32 v121, v121
	v_and_b32_e32 v135, 0xffff0000, v128
	v_add_f32_e32 v122, 1.0, v122
	v_rcp_f32_e32 v160, v122
	v_mul_f32_e32 v122, 0xbfb8aa3b, v135
	v_add_f32_e32 v115, v115, v131
	v_exp_f32_e32 v122, v122
	v_mul_f32_e32 v114, 0xbfb8aa3b, v114
	v_mul_f32_e32 v115, 0xbfb8aa3b, v115
	v_add_f32_e32 v120, 1.0, v120
	v_add_f32_e32 v121, 1.0, v121
	v_exp_f32_e32 v114, v114
	v_exp_f32_e32 v115, v115
	v_rcp_f32_e32 v120, v120
	v_rcp_f32_e32 v121, v121
	v_add_f32_e32 v122, 1.0, v122
	v_rcp_f32_e32 v161, v122
	v_lshlrev_b32_e32 v122, 16, v123
	v_and_b32_e32 v123, 0xffff0000, v123
	v_lshlrev_b32_e32 v126, 16, v127
	v_and_b32_e32 v127, 0xffff0000, v127
	v_add_f32_e32 v114, 1.0, v114
	v_add_f32_e32 v115, 1.0, v115
	v_lshlrev_b32_e32 v130, 16, v124
	v_and_b32_e32 v131, 0xffff0000, v124
	v_mul_f32_e32 v124, 0xbfb8aa3b, v126
	v_pk_mul_f32 v[120:121], v[120:121], v[122:123]
	v_mul_f32_e32 v122, 0xbfb8aa3b, v127
	v_rcp_f32_e32 v114, v114
	v_rcp_f32_e32 v115, v115
	v_add_f32_e32 v116, v116, v132
	v_exp_f32_e32 v124, v124
	v_exp_f32_e32 v122, v122
	v_add_f32_e32 v117, v117, v133
	v_mul_f32_e32 v116, 0xbfb8aa3b, v116
	v_mul_f32_e32 v117, 0xbfb8aa3b, v117
	v_exp_f32_e32 v116, v116
	v_exp_f32_e32 v117, v117
	v_pk_mul_f32 v[114:115], v[114:115], v[130:131]
	v_pk_mul_f32 v[130:131], v[160:161], v[134:135]
	v_add_f32_e32 v124, 1.0, v124
	v_add_f32_e32 v122, 1.0, v122
	v_pk_mul_f32 v[114:115], v[114:115], v[130:131]
	v_rcp_f32_e32 v130, v124
	v_rcp_f32_e32 v131, v122
	v_add_f32_e32 v116, 1.0, v116
	v_add_f32_e32 v117, 1.0, v117
	v_rcp_f32_e32 v116, v116
	v_rcp_f32_e32 v117, v117
	v_pk_mul_f32 v[122:123], v[130:131], v[126:127]
	v_lshlrev_b32_e32 v124, 16, v129
	v_pk_mul_f32 v[120:121], v[120:121], v[122:123]
	v_lshlrev_b32_e32 v122, 16, v125
	v_and_b32_e32 v123, 0xffff0000, v125
	v_and_b32_e32 v125, 0xffff0000, v129
	v_mul_f32_e32 v126, 0xbfb8aa3b, v124
	v_pk_mul_f32 v[116:117], v[116:117], v[122:123]
	v_mul_f32_e32 v122, 0xbfb8aa3b, v125
	v_exp_f32_e32 v126, v126
	v_exp_f32_e32 v122, v122
	v_or_b32_e32 v132, 16, v152
	v_ashrrev_i32_e32 v133, 31, v132
	v_add_f32_e32 v126, 1.0, v126
	v_add_f32_e32 v122, 1.0, v122
	v_rcp_f32_e32 v126, v126
	v_rcp_f32_e32 v127, v122
	s_nop 0
	v_pk_mul_f32 v[122:123], v[126:127], v[124:125]
	s_nop 0
	v_pk_mul_f32 v[122:123], v[116:117], v[122:123]
	v_cvt_pk_bf16_f32 v116, v118, v119
	v_cvt_pk_bf16_f32 v117, v120, v121
	v_cvt_pk_bf16_f32 v118, v114, v115
	v_cvt_pk_bf16_f32 v119, v122, v123
	global_store_dwordx4 v[158:159], v[116:119], off offset:2304
	global_load_dwordx4 v[114:117], v[148:149], off offset:16
	s_nop 0
	global_load_dwordx4 v[120:123], v[148:149], off
	v_lshlrev_b64 v[118:119], 11, v[132:133]
	v_lshl_add_u64 v[118:119], s[56:57], 0, v[118:119]
	v_lshl_add_u64 v[134:135], v[118:119], 0, v[150:151]
	v_mad_i64_i32 v[118:119], s[24:25], v132, s48, v[154:155]
	v_lshl_add_u64 v[118:119], v[118:119], 0, s[94:95]
	v_lshl_add_u64 v[128:129], v[118:119], 0, v[150:151]
	global_load_dwordx4 v[124:127], v[134:135], off
	v_lshl_add_u64 v[118:119], v[118:119], 0, v[156:157]
	global_load_dwordx4 v[128:131], v[128:129], off
	s_waitcnt vmcnt(0)
	v_add_f32_e32 v106, v106, v114
	v_add_f32_e32 v110, v110, v120
	v_add_f32_e32 v111, v111, v121
	v_mul_f32_e32 v110, 0xbfb8aa3b, v110
	v_mul_f32_e32 v111, 0xbfb8aa3b, v111
	v_exp_f32_e32 v110, v110
	v_exp_f32_e32 v111, v111
	v_add_f32_e32 v107, v107, v115
	v_mul_f32_e32 v106, 0xbfb8aa3b, v106
	v_mul_f32_e32 v107, 0xbfb8aa3b, v107
	v_exp_f32_e32 v106, v106
	v_lshlrev_b32_e32 v136, 16, v128
	v_mul_f32_e32 v114, 0xbfb8aa3b, v136
	v_exp_f32_e32 v114, v114
	v_and_b32_e32 v137, 0xffff0000, v128
	v_exp_f32_e32 v107, v107
	v_add_f32_e32 v110, 1.0, v110
	v_add_f32_e32 v114, 1.0, v114
	v_rcp_f32_e32 v158, v114
	v_mul_f32_e32 v114, 0xbfb8aa3b, v137
	v_exp_f32_e32 v114, v114
	v_add_f32_e32 v111, 1.0, v111
	v_rcp_f32_e32 v110, v110
	v_rcp_f32_e32 v111, v111
	v_add_f32_e32 v114, 1.0, v114
	v_rcp_f32_e32 v159, v114
	v_add_f32_e32 v106, 1.0, v106
	v_add_f32_e32 v107, 1.0, v107
	v_rcp_f32_e32 v106, v106
	v_rcp_f32_e32 v107, v107
	v_lshlrev_b32_e32 v120, 16, v124
	v_and_b32_e32 v121, 0xffff0000, v124
	v_pk_mul_f32 v[110:111], v[110:111], v[120:121]
	v_pk_mul_f32 v[120:121], v[158:159], v[136:137]
	v_lshlrev_b32_e32 v114, 16, v126
	v_pk_mul_f32 v[110:111], v[110:111], v[120:121]
	v_and_b32_e32 v115, 0xffff0000, v126
	v_lshlrev_b32_e32 v120, 16, v130
	v_and_b32_e32 v121, 0xffff0000, v130
	v_mul_f32_e32 v124, 0xbfb8aa3b, v120
	v_pk_mul_f32 v[106:107], v[106:107], v[114:115]
	v_mul_f32_e32 v114, 0xbfb8aa3b, v121
	v_exp_f32_e32 v124, v124
	v_exp_f32_e32 v114, v114
	v_add_f32_e32 v124, 1.0, v124
	v_add_f32_e32 v114, 1.0, v114
	v_rcp_f32_e32 v136, v124
	v_rcp_f32_e32 v137, v114
	s_nop 0
	v_pk_mul_f32 v[114:115], v[136:137], v[120:121]
	s_nop 0
	v_pk_mul_f32 v[114:115], v[106:107], v[114:115]
	v_add_f32_e32 v107, v108, v116
	v_mul_f32_e32 v107, 0xbfb8aa3b, v107
	v_exp_f32_e32 v107, v107
	v_add_f32_e32 v106, v112, v122
	v_mul_f32_e32 v106, 0xbfb8aa3b, v106
	v_exp_f32_e32 v106, v106
	v_add_f32_e32 v107, 1.0, v107
	v_rcp_f32_e32 v108, v107
	v_add_f32_e32 v107, v113, v123
	v_mul_f32_e32 v107, 0xbfb8aa3b, v107
	v_exp_f32_e32 v107, v107
	v_add_f32_e32 v106, 1.0, v106
	v_rcp_f32_e32 v106, v106
	v_lshlrev_b32_e32 v112, 16, v125
	v_add_f32_e32 v107, 1.0, v107
	v_rcp_f32_e32 v107, v107
	v_and_b32_e32 v113, 0xffff0000, v125
	v_lshlrev_b32_e32 v120, 16, v129
	v_and_b32_e32 v121, 0xffff0000, v129
	v_mul_f32_e32 v116, 0xbfb8aa3b, v120
	v_pk_mul_f32 v[106:107], v[106:107], v[112:113]
	v_mul_f32_e32 v112, 0xbfb8aa3b, v121
	v_exp_f32_e32 v116, v116
	v_exp_f32_e32 v112, v112
	v_add_f32_e32 v116, 1.0, v116
	v_add_f32_e32 v112, 1.0, v112
	v_rcp_f32_e32 v122, v116
	v_rcp_f32_e32 v123, v112
	v_lshlrev_b32_e32 v116, 16, v131
	v_pk_mul_f32 v[112:113], v[122:123], v[120:121]
	s_nop 0
	v_pk_mul_f32 v[112:113], v[106:107], v[112:113]
	v_add_f32_e32 v106, v109, v117
	v_mul_f32_e32 v106, 0xbfb8aa3b, v106
	v_exp_f32_e32 v106, v106
	v_and_b32_e32 v107, 0xffff0000, v127
	v_and_b32_e32 v117, 0xffff0000, v131
	v_mul_f32_e32 v120, 0xbfb8aa3b, v116
	v_add_f32_e32 v106, 1.0, v106
	v_rcp_f32_e32 v109, v106
	v_lshlrev_b32_e32 v106, 16, v127
	v_exp_f32_e32 v120, v120
	v_pk_mul_f32 v[106:107], v[108:109], v[106:107]
	v_mul_f32_e32 v108, 0xbfb8aa3b, v117
	v_exp_f32_e32 v108, v108
	v_add_f32_e32 v120, 1.0, v120
	v_rcp_f32_e32 v120, v120
	v_add_f32_e32 v108, 1.0, v108
	v_rcp_f32_e32 v121, v108
	s_nop 0
	v_pk_mul_f32 v[108:109], v[120:121], v[116:117]
	s_nop 0
	v_pk_mul_f32 v[116:117], v[106:107], v[108:109]
	v_cvt_pk_bf16_f32 v106, v110, v111
	v_lshlrev_b64 v[110:111], 12, v[132:133]
	v_lshl_add_u64 v[110:111], s[36:37], 0, v[110:111]
	v_cvt_pk_bf16_f32 v107, v112, v113
	v_cvt_pk_bf16_f32 v108, v114, v115
	v_cvt_pk_bf16_f32 v109, v116, v117
	v_lshl_add_u64 v[122:123], v[110:111], 0, v[150:151]
	global_store_dwordx4 v[122:123], v[106:109], off offset:2048
	global_load_dwordx4 v[110:113], v[148:149], off offset:528
	global_load_dwordx4 v[114:117], v[148:149], off offset:512
	s_nop 0
	global_load_dwordx4 v[106:109], v[134:135], off offset:256
	s_waitcnt vmcnt(0)
	v_add_f32_e32 v98, v98, v110
	global_load_dwordx4 v[118:121], v[118:119], off
	v_add_f32_e32 v102, v102, v114
	v_add_f32_e32 v103, v103, v115
	v_lshlrev_b32_e32 v114, 16, v106
	v_and_b32_e32 v115, 0xffff0000, v106
	v_mul_f32_e32 v102, 0xbfb8aa3b, v102
	v_mul_f32_e32 v103, 0xbfb8aa3b, v103
	v_exp_f32_e32 v102, v102
	v_exp_f32_e32 v103, v103
	v_add_f32_e32 v99, v99, v111
	v_mul_f32_e32 v98, 0xbfb8aa3b, v98
	v_add_f32_e32 v102, 1.0, v102
	v_add_f32_e32 v103, 1.0, v103
	v_rcp_f32_e32 v102, v102
	v_rcp_f32_e32 v103, v103
	v_mul_f32_e32 v99, 0xbfb8aa3b, v99
	v_exp_f32_e32 v98, v98
	v_exp_f32_e32 v99, v99
	v_pk_mul_f32 v[102:103], v[102:103], v[114:115]
	v_lshlrev_b32_e32 v110, 16, v108
	v_add_f32_e32 v98, 1.0, v98
	v_add_f32_e32 v99, 1.0, v99
	v_rcp_f32_e32 v98, v98
	v_rcp_f32_e32 v99, v99
	v_and_b32_e32 v111, 0xffff0000, v108
	v_pk_mul_f32 v[98:99], v[98:99], v[110:111]
	s_waitcnt vmcnt(0)
	v_lshlrev_b32_e32 v124, 16, v118
	v_mul_f32_e32 v106, 0xbfb8aa3b, v124
	v_exp_f32_e32 v106, v106
	v_and_b32_e32 v125, 0xffff0000, v118
	v_or_b32_e32 v118, 32, v152
	v_add_f32_e32 v106, 1.0, v106
	v_rcp_f32_e32 v126, v106
	v_mul_f32_e32 v106, 0xbfb8aa3b, v125
	v_exp_f32_e32 v106, v106
	s_nop 0
	v_add_f32_e32 v106, 1.0, v106
	v_rcp_f32_e32 v127, v106
	s_nop 0
	v_pk_mul_f32 v[114:115], v[126:127], v[124:125]
	s_nop 0
	v_pk_mul_f32 v[102:103], v[102:103], v[114:115]
	v_lshlrev_b32_e32 v114, 16, v120
	v_mul_f32_e32 v106, 0xbfb8aa3b, v114
	v_exp_f32_e32 v106, v106
	v_and_b32_e32 v115, 0xffff0000, v120
	v_add_f32_e32 v106, 1.0, v106
	v_rcp_f32_e32 v124, v106
	v_mul_f32_e32 v106, 0xbfb8aa3b, v115
	v_exp_f32_e32 v106, v106
	s_nop 0
	v_add_f32_e32 v106, 1.0, v106
	v_rcp_f32_e32 v125, v106
	v_lshlrev_b32_e32 v106, 16, v119
	v_mul_f32_e32 v108, 0xbfb8aa3b, v106
	v_exp_f32_e32 v108, v108
	v_pk_mul_f32 v[110:111], v[124:125], v[114:115]
	v_add_f32_e32 v108, 1.0, v108
	v_pk_mul_f32 v[110:111], v[98:99], v[110:111]
	v_add_f32_e32 v99, v100, v112
	v_mul_f32_e32 v99, 0xbfb8aa3b, v99
	v_exp_f32_e32 v99, v99
	v_add_f32_e32 v98, v104, v116
	v_mul_f32_e32 v98, 0xbfb8aa3b, v98
	v_exp_f32_e32 v98, v98
	v_add_f32_e32 v99, 1.0, v99
	v_rcp_f32_e32 v100, v99
	v_add_f32_e32 v99, v105, v117
	v_mul_f32_e32 v99, 0xbfb8aa3b, v99
	v_exp_f32_e32 v99, v99
	v_add_f32_e32 v98, 1.0, v98
	v_rcp_f32_e32 v98, v98
	v_lshlrev_b32_e32 v104, 16, v107
	v_add_f32_e32 v99, 1.0, v99
	v_rcp_f32_e32 v99, v99
	v_and_b32_e32 v105, 0xffff0000, v107
	v_and_b32_e32 v107, 0xffff0000, v119
	v_rcp_f32_e32 v114, v108
	v_pk_mul_f32 v[98:99], v[98:99], v[104:105]
	v_mul_f32_e32 v104, 0xbfb8aa3b, v107
	v_exp_f32_e32 v104, v104
	v_ashrrev_i32_e32 v119, 31, v118
	v_add_f32_e32 v104, 1.0, v104
	v_rcp_f32_e32 v115, v104
	s_nop 0
	v_pk_mul_f32 v[104:105], v[114:115], v[106:107]
	s_nop 0
	v_pk_mul_f32 v[104:105], v[98:99], v[104:105]
	v_add_f32_e32 v98, v101, v113
	v_mul_f32_e32 v98, 0xbfb8aa3b, v98
	v_exp_f32_e32 v98, v98
	v_and_b32_e32 v99, 0xffff0000, v109
	v_lshlrev_b32_e32 v106, 16, v121
	v_and_b32_e32 v107, 0xffff0000, v121
	v_add_f32_e32 v98, 1.0, v98
	v_rcp_f32_e32 v101, v98
	v_lshlrev_b32_e32 v98, 16, v109
	v_mul_f32_e32 v108, 0xbfb8aa3b, v106
	v_exp_f32_e32 v108, v108
	v_pk_mul_f32 v[98:99], v[100:101], v[98:99]
	v_mul_f32_e32 v100, 0xbfb8aa3b, v107
	v_exp_f32_e32 v100, v100
	v_add_f32_e32 v108, 1.0, v108
	v_rcp_f32_e32 v108, v108
	v_add_f32_e32 v100, 1.0, v100
	v_rcp_f32_e32 v109, v100
	s_nop 0
	v_pk_mul_f32 v[100:101], v[108:109], v[106:107]
	s_nop 0
	v_pk_mul_f32 v[106:107], v[98:99], v[100:101]
	v_cvt_pk_bf16_f32 v98, v102, v103
	v_cvt_pk_bf16_f32 v99, v104, v105
	v_cvt_pk_bf16_f32 v100, v110, v111
	v_cvt_pk_bf16_f32 v101, v106, v107
	global_store_dwordx4 v[122:123], v[98:101], off offset:2304
	global_load_dwordx4 v[102:105], v[148:149], off offset:16
	global_load_dwordx4 v[106:109], v[148:149], off
	v_lshlrev_b64 v[98:99], 11, v[118:119]
	v_lshl_add_u64 v[98:99], s[56:57], 0, v[98:99]
	v_lshl_add_u64 v[100:101], v[98:99], 0, v[150:151]
	v_mad_i64_i32 v[98:99], s[24:25], v118, s48, v[154:155]
	v_lshl_add_u64 v[98:99], v[98:99], 0, s[94:95]
	v_lshl_add_u64 v[114:115], v[98:99], 0, v[150:151]
	global_load_dwordx4 v[110:113], v[100:101], off
	v_lshl_add_u64 v[98:99], v[98:99], 0, v[156:157]
	global_load_dwordx4 v[114:117], v[114:115], off
	s_waitcnt vmcnt(0)
	v_add_f32_e32 v90, v90, v102
	v_add_f32_e32 v94, v94, v106
	v_add_f32_e32 v95, v95, v107
	v_mul_f32_e32 v94, 0xbfb8aa3b, v94
	v_mul_f32_e32 v95, 0xbfb8aa3b, v95
	v_exp_f32_e32 v94, v94
	v_exp_f32_e32 v95, v95
	v_add_f32_e32 v91, v91, v103
	v_mul_f32_e32 v90, 0xbfb8aa3b, v90
	v_mul_f32_e32 v91, 0xbfb8aa3b, v91
	v_exp_f32_e32 v90, v90
	v_lshlrev_b32_e32 v120, 16, v114
	v_mul_f32_e32 v102, 0xbfb8aa3b, v120
	v_exp_f32_e32 v102, v102
	v_and_b32_e32 v121, 0xffff0000, v114
	v_exp_f32_e32 v91, v91
	v_add_f32_e32 v94, 1.0, v94
	v_add_f32_e32 v102, 1.0, v102
	v_rcp_f32_e32 v122, v102
	v_mul_f32_e32 v102, 0xbfb8aa3b, v121
	v_exp_f32_e32 v102, v102
	v_add_f32_e32 v95, 1.0, v95
	v_rcp_f32_e32 v94, v94
	v_rcp_f32_e32 v95, v95
	v_add_f32_e32 v102, 1.0, v102
	v_rcp_f32_e32 v123, v102
	v_add_f32_e32 v90, 1.0, v90
	v_add_f32_e32 v91, 1.0, v91
	v_rcp_f32_e32 v90, v90
	v_rcp_f32_e32 v91, v91
	v_lshlrev_b32_e32 v106, 16, v110
	v_and_b32_e32 v107, 0xffff0000, v110
	v_pk_mul_f32 v[94:95], v[94:95], v[106:107]
	v_pk_mul_f32 v[106:107], v[122:123], v[120:121]
	v_lshlrev_b32_e32 v102, 16, v112
	v_pk_mul_f32 v[94:95], v[94:95], v[106:107]
	v_and_b32_e32 v103, 0xffff0000, v112
	v_lshlrev_b32_e32 v106, 16, v116
	v_and_b32_e32 v107, 0xffff0000, v116
	v_mul_f32_e32 v110, 0xbfb8aa3b, v106
	v_pk_mul_f32 v[90:91], v[90:91], v[102:103]
	v_mul_f32_e32 v102, 0xbfb8aa3b, v107
	v_exp_f32_e32 v110, v110
	v_exp_f32_e32 v102, v102
	v_add_f32_e32 v110, 1.0, v110
	v_add_f32_e32 v102, 1.0, v102
	v_rcp_f32_e32 v120, v110
	v_rcp_f32_e32 v121, v102
	s_nop 0
	v_pk_mul_f32 v[102:103], v[120:121], v[106:107]
	s_nop 0
	v_pk_mul_f32 v[102:103], v[90:91], v[102:103]
	v_add_f32_e32 v91, v92, v104
	v_mul_f32_e32 v91, 0xbfb8aa3b, v91
	v_exp_f32_e32 v91, v91
	v_add_f32_e32 v90, v96, v108
	v_mul_f32_e32 v90, 0xbfb8aa3b, v90
	v_exp_f32_e32 v90, v90
	v_add_f32_e32 v91, 1.0, v91
	v_rcp_f32_e32 v92, v91
	v_add_f32_e32 v91, v97, v109
	v_mul_f32_e32 v91, 0xbfb8aa3b, v91
	v_exp_f32_e32 v91, v91
	v_add_f32_e32 v90, 1.0, v90
	v_rcp_f32_e32 v90, v90
	v_lshlrev_b32_e32 v96, 16, v111
	v_add_f32_e32 v91, 1.0, v91
	v_rcp_f32_e32 v91, v91
	v_and_b32_e32 v97, 0xffff0000, v111
	v_lshlrev_b32_e32 v106, 16, v115
	v_and_b32_e32 v107, 0xffff0000, v115
	v_mul_f32_e32 v104, 0xbfb8aa3b, v106
	v_pk_mul_f32 v[90:91], v[90:91], v[96:97]
	v_mul_f32_e32 v96, 0xbfb8aa3b, v107
	v_exp_f32_e32 v104, v104
	v_exp_f32_e32 v96, v96
	v_add_f32_e32 v104, 1.0, v104
	v_add_f32_e32 v96, 1.0, v96
	v_rcp_f32_e32 v108, v104
	v_rcp_f32_e32 v109, v96
	v_lshlrev_b32_e32 v104, 16, v117
	v_pk_mul_f32 v[96:97], v[108:109], v[106:107]
	s_nop 0
	v_pk_mul_f32 v[96:97], v[90:91], v[96:97]
	v_add_f32_e32 v90, v93, v105
	v_mul_f32_e32 v90, 0xbfb8aa3b, v90
	v_exp_f32_e32 v90, v90
	v_and_b32_e32 v91, 0xffff0000, v113
	v_and_b32_e32 v105, 0xffff0000, v117
	v_mul_f32_e32 v106, 0xbfb8aa3b, v104
	v_add_f32_e32 v90, 1.0, v90
	v_rcp_f32_e32 v93, v90
	v_lshlrev_b32_e32 v90, 16, v113
	v_exp_f32_e32 v106, v106
	v_pk_mul_f32 v[90:91], v[92:93], v[90:91]
	v_mul_f32_e32 v92, 0xbfb8aa3b, v105
	v_exp_f32_e32 v92, v92
	v_add_f32_e32 v106, 1.0, v106
	v_rcp_f32_e32 v106, v106
	v_add_f32_e32 v92, 1.0, v92
	v_rcp_f32_e32 v107, v92
	s_nop 0
	v_pk_mul_f32 v[92:93], v[106:107], v[104:105]
	s_nop 0
	v_pk_mul_f32 v[104:105], v[90:91], v[92:93]
	v_cvt_pk_bf16_f32 v90, v94, v95
	v_lshlrev_b64 v[94:95], 12, v[118:119]
	v_lshl_add_u64 v[94:95], s[36:37], 0, v[94:95]
	v_cvt_pk_bf16_f32 v91, v96, v97
	v_cvt_pk_bf16_f32 v92, v102, v103
	v_cvt_pk_bf16_f32 v93, v104, v105
	v_lshl_add_u64 v[106:107], v[94:95], 0, v[150:151]
	global_store_dwordx4 v[106:107], v[90:93], off offset:2048
	global_load_dwordx4 v[90:93], v[148:149], off offset:528
	s_nop 0
	global_load_dwordx4 v[94:97], v[148:149], off offset:512
	global_load_dwordx4 v[102:105], v[100:101], off offset:256
	s_waitcnt vmcnt(0)
	v_add_f32_e32 v82, v82, v90
	global_load_dwordx4 v[98:101], v[98:99], off
	v_add_f32_e32 v86, v86, v94
	v_add_f32_e32 v87, v87, v95
	v_mul_f32_e32 v86, 0xbfb8aa3b, v86
	v_mul_f32_e32 v87, 0xbfb8aa3b, v87
	v_exp_f32_e32 v86, v86
	v_exp_f32_e32 v87, v87
	v_add_f32_e32 v83, v83, v91
	v_mul_f32_e32 v82, 0xbfb8aa3b, v82
	v_mul_f32_e32 v83, 0xbfb8aa3b, v83
	v_exp_f32_e32 v82, v82
	v_exp_f32_e32 v83, v83
	v_add_f32_e32 v86, 1.0, v86
	v_add_f32_e32 v87, 1.0, v87
	v_rcp_f32_e32 v86, v86
	v_rcp_f32_e32 v87, v87
	v_add_f32_e32 v82, 1.0, v82
	v_add_f32_e32 v83, 1.0, v83
	v_rcp_f32_e32 v82, v82
	v_rcp_f32_e32 v83, v83
	v_lshlrev_b32_e32 v94, 16, v102
	v_and_b32_e32 v95, 0xffff0000, v102
	v_pk_mul_f32 v[86:87], v[86:87], v[94:95]
	v_and_b32_e32 v91, 0xffff0000, v104
	v_or_b32_e32 v102, 48, v152
	s_waitcnt vmcnt(0)
	v_lshlrev_b32_e32 v108, 16, v98
	v_mul_f32_e32 v90, 0xbfb8aa3b, v108
	v_exp_f32_e32 v90, v90
	v_and_b32_e32 v109, 0xffff0000, v98
	v_add_f32_e32 v90, 1.0, v90
	v_rcp_f32_e32 v110, v90
	v_mul_f32_e32 v90, 0xbfb8aa3b, v109
	v_exp_f32_e32 v90, v90
	s_nop 0
	v_add_f32_e32 v90, 1.0, v90
	v_rcp_f32_e32 v111, v90
	v_lshlrev_b32_e32 v90, 16, v104
	v_pk_mul_f32 v[82:83], v[82:83], v[90:91]
	v_pk_mul_f32 v[94:95], v[110:111], v[108:109]
	s_nop 0
	v_pk_mul_f32 v[86:87], v[86:87], v[94:95]
	v_lshlrev_b32_e32 v94, 16, v100
	v_and_b32_e32 v95, 0xffff0000, v100
	v_mul_f32_e32 v98, 0xbfb8aa3b, v94
	v_mul_f32_e32 v90, 0xbfb8aa3b, v95
	v_exp_f32_e32 v98, v98
	v_exp_f32_e32 v90, v90
	v_add_f32_e32 v98, 1.0, v98
	v_add_f32_e32 v90, 1.0, v90
	v_rcp_f32_e32 v108, v98
	v_rcp_f32_e32 v109, v90
	s_nop 0
	v_pk_mul_f32 v[90:91], v[108:109], v[94:95]
	s_nop 0
	v_pk_mul_f32 v[90:91], v[82:83], v[90:91]
	v_add_f32_e32 v83, v84, v92
	v_mul_f32_e32 v83, 0xbfb8aa3b, v83
	v_exp_f32_e32 v83, v83
	v_add_f32_e32 v82, v88, v96
	v_mul_f32_e32 v82, 0xbfb8aa3b, v82
	v_exp_f32_e32 v82, v82
	v_add_f32_e32 v83, 1.0, v83
	v_rcp_f32_e32 v84, v83
	v_add_f32_e32 v83, v89, v97
	v_mul_f32_e32 v83, 0xbfb8aa3b, v83
	v_exp_f32_e32 v83, v83
	v_add_f32_e32 v82, 1.0, v82
	v_rcp_f32_e32 v82, v82
	v_lshlrev_b32_e32 v88, 16, v103
	v_add_f32_e32 v83, 1.0, v83
	v_rcp_f32_e32 v83, v83
	v_and_b32_e32 v89, 0xffff0000, v103
	v_lshlrev_b32_e32 v94, 16, v99
	v_and_b32_e32 v95, 0xffff0000, v99
	v_mul_f32_e32 v92, 0xbfb8aa3b, v94
	v_pk_mul_f32 v[82:83], v[82:83], v[88:89]
	v_mul_f32_e32 v88, 0xbfb8aa3b, v95
	v_exp_f32_e32 v92, v92
	v_exp_f32_e32 v88, v88
	v_ashrrev_i32_e32 v103, 31, v102
	v_add_f32_e32 v92, 1.0, v92
	v_add_f32_e32 v88, 1.0, v88
	v_rcp_f32_e32 v96, v92
	v_rcp_f32_e32 v97, v88
	v_lshlrev_b32_e32 v92, 16, v101
	v_pk_mul_f32 v[88:89], v[96:97], v[94:95]
	s_nop 0
	v_pk_mul_f32 v[88:89], v[82:83], v[88:89]
	v_add_f32_e32 v82, v85, v93
	v_mul_f32_e32 v82, 0xbfb8aa3b, v82
	v_exp_f32_e32 v82, v82
	v_and_b32_e32 v83, 0xffff0000, v105
	v_and_b32_e32 v93, 0xffff0000, v101
	v_mul_f32_e32 v94, 0xbfb8aa3b, v92
	v_add_f32_e32 v82, 1.0, v82
	v_rcp_f32_e32 v85, v82
	v_lshlrev_b32_e32 v82, 16, v105
	v_exp_f32_e32 v94, v94
	v_pk_mul_f32 v[82:83], v[84:85], v[82:83]
	v_mul_f32_e32 v84, 0xbfb8aa3b, v93
	v_exp_f32_e32 v84, v84
	v_add_f32_e32 v94, 1.0, v94
	v_rcp_f32_e32 v94, v94
	v_add_f32_e32 v84, 1.0, v84
	v_rcp_f32_e32 v95, v84
	s_nop 0
	v_pk_mul_f32 v[84:85], v[94:95], v[92:93]
	s_nop 0
	v_pk_mul_f32 v[92:93], v[82:83], v[84:85]
	v_cvt_pk_bf16_f32 v82, v86, v87
	v_cvt_pk_bf16_f32 v83, v88, v89
	v_cvt_pk_bf16_f32 v84, v90, v91
	v_cvt_pk_bf16_f32 v85, v92, v93
	global_store_dwordx4 v[106:107], v[82:85], off offset:2304
	global_load_dwordx4 v[86:89], v[148:149], off offset:16
	global_load_dwordx4 v[90:93], v[148:149], off
	v_lshlrev_b64 v[82:83], 11, v[102:103]
	v_lshl_add_u64 v[82:83], s[56:57], 0, v[82:83]
	v_lshl_add_u64 v[84:85], v[82:83], 0, v[150:151]
	v_mad_i64_i32 v[82:83], s[24:25], v102, s48, v[154:155]
	v_lshl_add_u64 v[82:83], v[82:83], 0, s[94:95]
	v_lshl_add_u64 v[98:99], v[82:83], 0, v[150:151]
	global_load_dwordx4 v[94:97], v[84:85], off
	v_lshl_add_u64 v[82:83], v[82:83], 0, v[156:157]
	global_load_dwordx4 v[98:101], v[98:99], off
	s_waitcnt vmcnt(0)
	v_add_f32_e32 v74, v74, v86
	v_add_f32_e32 v78, v78, v90
	v_add_f32_e32 v79, v79, v91
	v_mul_f32_e32 v78, 0xbfb8aa3b, v78
	v_mul_f32_e32 v79, 0xbfb8aa3b, v79
	v_exp_f32_e32 v78, v78
	v_exp_f32_e32 v79, v79
	v_add_f32_e32 v75, v75, v87
	v_mul_f32_e32 v74, 0xbfb8aa3b, v74
	v_mul_f32_e32 v75, 0xbfb8aa3b, v75
	v_exp_f32_e32 v74, v74
	v_lshlrev_b32_e32 v104, 16, v98
	v_mul_f32_e32 v86, 0xbfb8aa3b, v104
	v_exp_f32_e32 v86, v86
	v_and_b32_e32 v105, 0xffff0000, v98
	v_exp_f32_e32 v75, v75
	v_add_f32_e32 v78, 1.0, v78
	v_add_f32_e32 v86, 1.0, v86
	v_rcp_f32_e32 v106, v86
	v_mul_f32_e32 v86, 0xbfb8aa3b, v105
	v_exp_f32_e32 v86, v86
	v_add_f32_e32 v79, 1.0, v79
	v_rcp_f32_e32 v78, v78
	v_rcp_f32_e32 v79, v79
	v_add_f32_e32 v86, 1.0, v86
	v_rcp_f32_e32 v107, v86
	v_add_f32_e32 v74, 1.0, v74
	v_add_f32_e32 v75, 1.0, v75
	v_rcp_f32_e32 v74, v74
	v_rcp_f32_e32 v75, v75
	v_lshlrev_b32_e32 v90, 16, v94
	v_and_b32_e32 v91, 0xffff0000, v94
	v_pk_mul_f32 v[78:79], v[78:79], v[90:91]
	v_pk_mul_f32 v[90:91], v[106:107], v[104:105]
	v_lshlrev_b32_e32 v86, 16, v96
	v_pk_mul_f32 v[78:79], v[78:79], v[90:91]
	v_and_b32_e32 v87, 0xffff0000, v96
	v_lshlrev_b32_e32 v90, 16, v100
	v_and_b32_e32 v91, 0xffff0000, v100
	v_mul_f32_e32 v94, 0xbfb8aa3b, v90
	v_pk_mul_f32 v[74:75], v[74:75], v[86:87]
	v_mul_f32_e32 v86, 0xbfb8aa3b, v91
	v_exp_f32_e32 v94, v94
	v_exp_f32_e32 v86, v86
	v_add_f32_e32 v94, 1.0, v94
	v_add_f32_e32 v86, 1.0, v86
	v_rcp_f32_e32 v104, v94
	v_rcp_f32_e32 v105, v86
	s_nop 0
	v_pk_mul_f32 v[86:87], v[104:105], v[90:91]
	s_nop 0
	v_pk_mul_f32 v[86:87], v[74:75], v[86:87]
	v_add_f32_e32 v75, v76, v88
	v_mul_f32_e32 v75, 0xbfb8aa3b, v75
	v_exp_f32_e32 v75, v75
	v_add_f32_e32 v74, v80, v92
	v_mul_f32_e32 v74, 0xbfb8aa3b, v74
	v_exp_f32_e32 v74, v74
	v_add_f32_e32 v75, 1.0, v75
	v_rcp_f32_e32 v76, v75
	v_add_f32_e32 v75, v81, v93
	v_mul_f32_e32 v75, 0xbfb8aa3b, v75
	v_exp_f32_e32 v75, v75
	v_add_f32_e32 v74, 1.0, v74
	v_rcp_f32_e32 v74, v74
	v_lshlrev_b32_e32 v80, 16, v95
	v_add_f32_e32 v75, 1.0, v75
	v_rcp_f32_e32 v75, v75
	v_and_b32_e32 v81, 0xffff0000, v95
	v_lshlrev_b32_e32 v90, 16, v99
	v_and_b32_e32 v91, 0xffff0000, v99
	v_mul_f32_e32 v88, 0xbfb8aa3b, v90
	v_pk_mul_f32 v[74:75], v[74:75], v[80:81]
	v_mul_f32_e32 v80, 0xbfb8aa3b, v91
	v_exp_f32_e32 v88, v88
	v_exp_f32_e32 v80, v80
	v_add_f32_e32 v88, 1.0, v88
	v_add_f32_e32 v80, 1.0, v80
	v_rcp_f32_e32 v92, v88
	v_rcp_f32_e32 v93, v80
	v_lshlrev_b32_e32 v88, 16, v101
	v_pk_mul_f32 v[80:81], v[92:93], v[90:91]
	s_nop 0
	v_pk_mul_f32 v[80:81], v[74:75], v[80:81]
	v_add_f32_e32 v74, v77, v89
	v_mul_f32_e32 v74, 0xbfb8aa3b, v74
	v_exp_f32_e32 v74, v74
	v_and_b32_e32 v75, 0xffff0000, v97
	v_and_b32_e32 v89, 0xffff0000, v101
	v_mul_f32_e32 v90, 0xbfb8aa3b, v88
	v_add_f32_e32 v74, 1.0, v74
	v_rcp_f32_e32 v77, v74
	v_lshlrev_b32_e32 v74, 16, v97
	v_exp_f32_e32 v90, v90
	v_pk_mul_f32 v[74:75], v[76:77], v[74:75]
	v_mul_f32_e32 v76, 0xbfb8aa3b, v89
	v_exp_f32_e32 v76, v76
	v_add_f32_e32 v90, 1.0, v90
	v_rcp_f32_e32 v90, v90
	v_add_f32_e32 v76, 1.0, v76
	v_rcp_f32_e32 v91, v76
	s_nop 0
	v_pk_mul_f32 v[76:77], v[90:91], v[88:89]
	s_nop 0
	v_pk_mul_f32 v[88:89], v[74:75], v[76:77]
	v_cvt_pk_bf16_f32 v74, v78, v79
	v_lshlrev_b64 v[78:79], 12, v[102:103]
	v_lshl_add_u64 v[78:79], s[36:37], 0, v[78:79]
	v_cvt_pk_bf16_f32 v75, v80, v81
	v_cvt_pk_bf16_f32 v76, v86, v87
	v_cvt_pk_bf16_f32 v77, v88, v89
	v_lshl_add_u64 v[90:91], v[78:79], 0, v[150:151]
	global_store_dwordx4 v[90:91], v[74:77], off offset:2048
	global_load_dwordx4 v[74:77], v[148:149], off offset:528
	s_nop 0
	global_load_dwordx4 v[78:81], v[148:149], off offset:512
	global_load_dwordx4 v[86:89], v[84:85], off offset:256
	s_waitcnt vmcnt(0)
	v_add_f32_e32 v66, v66, v74
	global_load_dwordx4 v[82:85], v[82:83], off
	v_add_f32_e32 v70, v70, v78
	v_add_f32_e32 v71, v71, v79
	v_mul_f32_e32 v70, 0xbfb8aa3b, v70
	v_mul_f32_e32 v71, 0xbfb8aa3b, v71
	v_exp_f32_e32 v70, v70
	v_exp_f32_e32 v71, v71
	v_add_f32_e32 v67, v67, v75
	v_mul_f32_e32 v66, 0xbfb8aa3b, v66
	v_mul_f32_e32 v67, 0xbfb8aa3b, v67
	v_exp_f32_e32 v66, v66
	v_exp_f32_e32 v67, v67
	v_add_f32_e32 v70, 1.0, v70
	v_add_f32_e32 v71, 1.0, v71
	v_rcp_f32_e32 v70, v70
	v_rcp_f32_e32 v71, v71
	v_add_f32_e32 v66, 1.0, v66
	v_add_f32_e32 v67, 1.0, v67
	v_rcp_f32_e32 v66, v66
	v_rcp_f32_e32 v67, v67
	v_lshlrev_b32_e32 v78, 16, v86
	v_and_b32_e32 v79, 0xffff0000, v86
	v_pk_mul_f32 v[70:71], v[70:71], v[78:79]
	v_and_b32_e32 v75, 0xffff0000, v88
	v_add_u32_e32 v86, 0x80, v152
	s_waitcnt vmcnt(0)
	v_lshlrev_b32_e32 v92, 16, v82
	v_mul_f32_e32 v74, 0xbfb8aa3b, v92
	v_exp_f32_e32 v74, v74
	v_and_b32_e32 v93, 0xffff0000, v82
	v_add_f32_e32 v74, 1.0, v74
	v_rcp_f32_e32 v94, v74
	v_mul_f32_e32 v74, 0xbfb8aa3b, v93
	v_exp_f32_e32 v74, v74
	s_nop 0
	v_add_f32_e32 v74, 1.0, v74
	v_rcp_f32_e32 v95, v74
	v_lshlrev_b32_e32 v74, 16, v88
	v_pk_mul_f32 v[66:67], v[66:67], v[74:75]
	v_pk_mul_f32 v[78:79], v[94:95], v[92:93]
	s_nop 0
	v_pk_mul_f32 v[70:71], v[70:71], v[78:79]
	v_lshlrev_b32_e32 v78, 16, v84
	v_and_b32_e32 v79, 0xffff0000, v84
	v_mul_f32_e32 v82, 0xbfb8aa3b, v78
	v_mul_f32_e32 v74, 0xbfb8aa3b, v79
	v_exp_f32_e32 v82, v82
	v_exp_f32_e32 v74, v74
	v_add_f32_e32 v82, 1.0, v82
	v_add_f32_e32 v74, 1.0, v74
	v_rcp_f32_e32 v92, v82
	v_rcp_f32_e32 v93, v74
	s_nop 0
	v_pk_mul_f32 v[74:75], v[92:93], v[78:79]
	s_nop 0
	v_pk_mul_f32 v[74:75], v[66:67], v[74:75]
	v_add_f32_e32 v67, v68, v76
	v_mul_f32_e32 v67, 0xbfb8aa3b, v67
	v_exp_f32_e32 v67, v67
	v_add_f32_e32 v66, v72, v80
	v_mul_f32_e32 v66, 0xbfb8aa3b, v66
	v_exp_f32_e32 v66, v66
	v_add_f32_e32 v67, 1.0, v67
	v_rcp_f32_e32 v68, v67
	v_add_f32_e32 v67, v73, v81
	v_mul_f32_e32 v67, 0xbfb8aa3b, v67
	v_exp_f32_e32 v67, v67
	v_add_f32_e32 v66, 1.0, v66
	v_rcp_f32_e32 v66, v66
	v_lshlrev_b32_e32 v72, 16, v87
	v_add_f32_e32 v67, 1.0, v67
	v_rcp_f32_e32 v67, v67
	v_and_b32_e32 v73, 0xffff0000, v87
	v_lshlrev_b32_e32 v78, 16, v83
	v_and_b32_e32 v79, 0xffff0000, v83
	v_mul_f32_e32 v76, 0xbfb8aa3b, v78
	v_pk_mul_f32 v[66:67], v[66:67], v[72:73]
	v_mul_f32_e32 v72, 0xbfb8aa3b, v79
	v_exp_f32_e32 v76, v76
	v_exp_f32_e32 v72, v72
	v_ashrrev_i32_e32 v87, 31, v86
	v_add_f32_e32 v76, 1.0, v76
	v_add_f32_e32 v72, 1.0, v72
	v_rcp_f32_e32 v80, v76
	v_rcp_f32_e32 v81, v72
	v_lshlrev_b32_e32 v76, 16, v85
	v_pk_mul_f32 v[72:73], v[80:81], v[78:79]
	s_nop 0
	v_pk_mul_f32 v[72:73], v[66:67], v[72:73]
	v_add_f32_e32 v66, v69, v77
	v_mul_f32_e32 v66, 0xbfb8aa3b, v66
	v_exp_f32_e32 v66, v66
	v_and_b32_e32 v67, 0xffff0000, v89
	v_and_b32_e32 v77, 0xffff0000, v85
	v_mul_f32_e32 v78, 0xbfb8aa3b, v76
	v_add_f32_e32 v66, 1.0, v66
	v_rcp_f32_e32 v69, v66
	v_lshlrev_b32_e32 v66, 16, v89
	v_exp_f32_e32 v78, v78
	v_pk_mul_f32 v[66:67], v[68:69], v[66:67]
	v_mul_f32_e32 v68, 0xbfb8aa3b, v77
	v_exp_f32_e32 v68, v68
	v_add_f32_e32 v78, 1.0, v78
	v_rcp_f32_e32 v78, v78
	v_add_f32_e32 v68, 1.0, v68
	v_rcp_f32_e32 v79, v68
	s_nop 0
	v_pk_mul_f32 v[68:69], v[78:79], v[76:77]
	s_nop 0
	v_pk_mul_f32 v[76:77], v[66:67], v[68:69]
	v_cvt_pk_bf16_f32 v66, v70, v71
	v_cvt_pk_bf16_f32 v67, v72, v73
	v_cvt_pk_bf16_f32 v68, v74, v75
	v_cvt_pk_bf16_f32 v69, v76, v77
	global_store_dwordx4 v[90:91], v[66:69], off offset:2304
	global_load_dwordx4 v[70:73], v[148:149], off offset:16
	global_load_dwordx4 v[74:77], v[148:149], off
	v_lshlrev_b64 v[66:67], 11, v[86:87]
	v_lshl_add_u64 v[66:67], s[56:57], 0, v[66:67]
	v_lshl_add_u64 v[68:69], v[66:67], 0, v[150:151]
	v_mad_i64_i32 v[66:67], s[24:25], v86, s48, v[154:155]
	v_lshl_add_u64 v[66:67], v[66:67], 0, s[94:95]
	v_lshl_add_u64 v[82:83], v[66:67], 0, v[150:151]
	global_load_dwordx4 v[78:81], v[68:69], off
	v_lshl_add_u64 v[66:67], v[66:67], 0, v[156:157]
	global_load_dwordx4 v[82:85], v[82:83], off
	s_waitcnt vmcnt(0)
	v_add_f32_e32 v58, v58, v70
	v_add_f32_e32 v62, v62, v74
	v_add_f32_e32 v63, v63, v75
	v_mul_f32_e32 v62, 0xbfb8aa3b, v62
	v_mul_f32_e32 v63, 0xbfb8aa3b, v63
	v_exp_f32_e32 v62, v62
	v_exp_f32_e32 v63, v63
	v_add_f32_e32 v59, v59, v71
	v_mul_f32_e32 v58, 0xbfb8aa3b, v58
	v_mul_f32_e32 v59, 0xbfb8aa3b, v59
	v_exp_f32_e32 v58, v58
	v_lshlrev_b32_e32 v88, 16, v82
	v_mul_f32_e32 v70, 0xbfb8aa3b, v88
	v_exp_f32_e32 v70, v70
	v_and_b32_e32 v89, 0xffff0000, v82
	v_exp_f32_e32 v59, v59
	v_add_f32_e32 v62, 1.0, v62
	v_add_f32_e32 v70, 1.0, v70
	v_rcp_f32_e32 v90, v70
	v_mul_f32_e32 v70, 0xbfb8aa3b, v89
	v_exp_f32_e32 v70, v70
	v_add_f32_e32 v63, 1.0, v63
	v_rcp_f32_e32 v62, v62
	v_rcp_f32_e32 v63, v63
	v_add_f32_e32 v70, 1.0, v70
	v_rcp_f32_e32 v91, v70
	v_add_f32_e32 v58, 1.0, v58
	v_add_f32_e32 v59, 1.0, v59
	v_rcp_f32_e32 v58, v58
	v_rcp_f32_e32 v59, v59
	v_lshlrev_b32_e32 v74, 16, v78
	v_and_b32_e32 v75, 0xffff0000, v78
	v_pk_mul_f32 v[62:63], v[62:63], v[74:75]
	v_pk_mul_f32 v[74:75], v[90:91], v[88:89]
	v_lshlrev_b32_e32 v70, 16, v80
	v_pk_mul_f32 v[62:63], v[62:63], v[74:75]
	v_and_b32_e32 v71, 0xffff0000, v80
	v_lshlrev_b32_e32 v74, 16, v84
	v_and_b32_e32 v75, 0xffff0000, v84
	v_mul_f32_e32 v78, 0xbfb8aa3b, v74
	v_pk_mul_f32 v[58:59], v[58:59], v[70:71]
	v_mul_f32_e32 v70, 0xbfb8aa3b, v75
	v_exp_f32_e32 v78, v78
	v_exp_f32_e32 v70, v70
	v_add_f32_e32 v78, 1.0, v78
	v_add_f32_e32 v70, 1.0, v70
	v_rcp_f32_e32 v88, v78
	v_rcp_f32_e32 v89, v70
	s_nop 0
	v_pk_mul_f32 v[70:71], v[88:89], v[74:75]
	s_nop 0
	v_pk_mul_f32 v[70:71], v[58:59], v[70:71]
	v_add_f32_e32 v59, v60, v72
	v_mul_f32_e32 v59, 0xbfb8aa3b, v59
	v_exp_f32_e32 v59, v59
	v_add_f32_e32 v58, v64, v76
	v_mul_f32_e32 v58, 0xbfb8aa3b, v58
	v_exp_f32_e32 v58, v58
	v_add_f32_e32 v59, 1.0, v59
	v_rcp_f32_e32 v60, v59
	v_add_f32_e32 v59, v65, v77
	v_mul_f32_e32 v59, 0xbfb8aa3b, v59
	v_exp_f32_e32 v59, v59
	v_add_f32_e32 v58, 1.0, v58
	v_rcp_f32_e32 v58, v58
	v_lshlrev_b32_e32 v64, 16, v79
	v_add_f32_e32 v59, 1.0, v59
	v_rcp_f32_e32 v59, v59
	v_and_b32_e32 v65, 0xffff0000, v79
	v_lshlrev_b32_e32 v74, 16, v83
	v_and_b32_e32 v75, 0xffff0000, v83
	v_mul_f32_e32 v72, 0xbfb8aa3b, v74
	v_pk_mul_f32 v[58:59], v[58:59], v[64:65]
	v_mul_f32_e32 v64, 0xbfb8aa3b, v75
	v_exp_f32_e32 v72, v72
	v_exp_f32_e32 v64, v64
	v_add_f32_e32 v72, 1.0, v72
	v_add_f32_e32 v64, 1.0, v64
	v_rcp_f32_e32 v76, v72
	v_rcp_f32_e32 v77, v64
	v_lshlrev_b32_e32 v72, 16, v85
	v_pk_mul_f32 v[64:65], v[76:77], v[74:75]
	s_nop 0
	v_pk_mul_f32 v[64:65], v[58:59], v[64:65]
	v_add_f32_e32 v58, v61, v73
	v_mul_f32_e32 v58, 0xbfb8aa3b, v58
	v_exp_f32_e32 v58, v58
	v_and_b32_e32 v59, 0xffff0000, v81
	v_and_b32_e32 v73, 0xffff0000, v85
	v_mul_f32_e32 v74, 0xbfb8aa3b, v72
	v_add_f32_e32 v58, 1.0, v58
	v_rcp_f32_e32 v61, v58
	v_lshlrev_b32_e32 v58, 16, v81
	v_exp_f32_e32 v74, v74
	v_pk_mul_f32 v[58:59], v[60:61], v[58:59]
	v_mul_f32_e32 v60, 0xbfb8aa3b, v73
	v_exp_f32_e32 v60, v60
	v_add_f32_e32 v74, 1.0, v74
	v_rcp_f32_e32 v74, v74
	v_add_f32_e32 v60, 1.0, v60
	v_rcp_f32_e32 v75, v60
	s_nop 0
	v_pk_mul_f32 v[60:61], v[74:75], v[72:73]
	s_nop 0
	v_pk_mul_f32 v[72:73], v[58:59], v[60:61]
	v_cvt_pk_bf16_f32 v58, v62, v63
	v_lshlrev_b64 v[62:63], 12, v[86:87]
	v_lshl_add_u64 v[62:63], s[36:37], 0, v[62:63]
	v_cvt_pk_bf16_f32 v59, v64, v65
	v_cvt_pk_bf16_f32 v60, v70, v71
	v_cvt_pk_bf16_f32 v61, v72, v73
	v_lshl_add_u64 v[74:75], v[62:63], 0, v[150:151]
	global_store_dwordx4 v[74:75], v[58:61], off offset:2048
	global_load_dwordx4 v[58:61], v[148:149], off offset:528
	s_nop 0
	global_load_dwordx4 v[62:65], v[148:149], off offset:512
	global_load_dwordx4 v[70:73], v[68:69], off offset:256
	s_waitcnt vmcnt(0)
	v_add_f32_e32 v50, v50, v58
	global_load_dwordx4 v[66:69], v[66:67], off
	v_add_f32_e32 v54, v54, v62
	v_add_f32_e32 v55, v55, v63
	v_mul_f32_e32 v54, 0xbfb8aa3b, v54
	v_mul_f32_e32 v55, 0xbfb8aa3b, v55
	v_exp_f32_e32 v54, v54
	v_exp_f32_e32 v55, v55
	v_add_f32_e32 v51, v51, v59
	v_mul_f32_e32 v50, 0xbfb8aa3b, v50
	v_mul_f32_e32 v51, 0xbfb8aa3b, v51
	v_exp_f32_e32 v50, v50
	v_exp_f32_e32 v51, v51
	v_add_f32_e32 v54, 1.0, v54
	v_add_f32_e32 v55, 1.0, v55
	v_rcp_f32_e32 v54, v54
	v_rcp_f32_e32 v55, v55
	v_add_f32_e32 v50, 1.0, v50
	v_add_f32_e32 v51, 1.0, v51
	v_rcp_f32_e32 v50, v50
	v_rcp_f32_e32 v51, v51
	v_lshlrev_b32_e32 v62, 16, v70
	v_and_b32_e32 v63, 0xffff0000, v70
	v_pk_mul_f32 v[54:55], v[54:55], v[62:63]
	v_and_b32_e32 v59, 0xffff0000, v72
	v_add_u32_e32 v70, 0x90, v152
	s_waitcnt vmcnt(0)
	v_lshlrev_b32_e32 v76, 16, v66
	v_mul_f32_e32 v58, 0xbfb8aa3b, v76
	v_exp_f32_e32 v58, v58
	v_and_b32_e32 v77, 0xffff0000, v66
	v_add_f32_e32 v58, 1.0, v58
	v_rcp_f32_e32 v78, v58
	v_mul_f32_e32 v58, 0xbfb8aa3b, v77
	v_exp_f32_e32 v58, v58
	s_nop 0
	v_add_f32_e32 v58, 1.0, v58
	v_rcp_f32_e32 v79, v58
	v_lshlrev_b32_e32 v58, 16, v72
	v_pk_mul_f32 v[50:51], v[50:51], v[58:59]
	v_pk_mul_f32 v[62:63], v[78:79], v[76:77]
	s_nop 0
	v_pk_mul_f32 v[54:55], v[54:55], v[62:63]
	v_lshlrev_b32_e32 v62, 16, v68
	v_and_b32_e32 v63, 0xffff0000, v68
	v_mul_f32_e32 v66, 0xbfb8aa3b, v62
	v_mul_f32_e32 v58, 0xbfb8aa3b, v63
	v_exp_f32_e32 v66, v66
	v_exp_f32_e32 v58, v58
	v_add_f32_e32 v66, 1.0, v66
	v_add_f32_e32 v58, 1.0, v58
	v_rcp_f32_e32 v76, v66
	v_rcp_f32_e32 v77, v58
	s_nop 0
	v_pk_mul_f32 v[58:59], v[76:77], v[62:63]
	s_nop 0
	v_pk_mul_f32 v[58:59], v[50:51], v[58:59]
	v_add_f32_e32 v51, v52, v60
	v_mul_f32_e32 v51, 0xbfb8aa3b, v51
	v_exp_f32_e32 v51, v51
	v_add_f32_e32 v50, v56, v64
	v_mul_f32_e32 v50, 0xbfb8aa3b, v50
	v_exp_f32_e32 v50, v50
	v_add_f32_e32 v51, 1.0, v51
	v_rcp_f32_e32 v52, v51
	v_add_f32_e32 v51, v57, v65
	v_mul_f32_e32 v51, 0xbfb8aa3b, v51
	v_exp_f32_e32 v51, v51
	v_add_f32_e32 v50, 1.0, v50
	v_rcp_f32_e32 v50, v50
	v_lshlrev_b32_e32 v56, 16, v71
	v_add_f32_e32 v51, 1.0, v51
	v_rcp_f32_e32 v51, v51
	v_and_b32_e32 v57, 0xffff0000, v71
	v_lshlrev_b32_e32 v62, 16, v67
	v_and_b32_e32 v63, 0xffff0000, v67
	v_mul_f32_e32 v60, 0xbfb8aa3b, v62
	v_pk_mul_f32 v[50:51], v[50:51], v[56:57]
	v_mul_f32_e32 v56, 0xbfb8aa3b, v63
	v_exp_f32_e32 v60, v60
	v_exp_f32_e32 v56, v56
	v_ashrrev_i32_e32 v71, 31, v70
	v_add_f32_e32 v60, 1.0, v60
	v_add_f32_e32 v56, 1.0, v56
	v_rcp_f32_e32 v64, v60
	v_rcp_f32_e32 v65, v56
	v_lshlrev_b32_e32 v60, 16, v69
	v_pk_mul_f32 v[56:57], v[64:65], v[62:63]
	s_nop 0
	v_pk_mul_f32 v[56:57], v[50:51], v[56:57]
	v_add_f32_e32 v50, v53, v61
	v_mul_f32_e32 v50, 0xbfb8aa3b, v50
	v_exp_f32_e32 v50, v50
	v_and_b32_e32 v51, 0xffff0000, v73
	v_and_b32_e32 v61, 0xffff0000, v69
	v_mul_f32_e32 v62, 0xbfb8aa3b, v60
	v_add_f32_e32 v50, 1.0, v50
	v_rcp_f32_e32 v53, v50
	v_lshlrev_b32_e32 v50, 16, v73
	v_exp_f32_e32 v62, v62
	v_pk_mul_f32 v[50:51], v[52:53], v[50:51]
	v_mul_f32_e32 v52, 0xbfb8aa3b, v61
	v_exp_f32_e32 v52, v52
	v_add_f32_e32 v62, 1.0, v62
	v_rcp_f32_e32 v62, v62
	v_add_f32_e32 v52, 1.0, v52
	v_rcp_f32_e32 v63, v52
	s_nop 0
	v_pk_mul_f32 v[52:53], v[62:63], v[60:61]
	s_nop 0
	v_pk_mul_f32 v[60:61], v[50:51], v[52:53]
	v_cvt_pk_bf16_f32 v50, v54, v55
	v_cvt_pk_bf16_f32 v51, v56, v57
	v_cvt_pk_bf16_f32 v52, v58, v59
	v_cvt_pk_bf16_f32 v53, v60, v61
	global_store_dwordx4 v[74:75], v[50:53], off offset:2304
	global_load_dwordx4 v[54:57], v[148:149], off offset:16
	global_load_dwordx4 v[58:61], v[148:149], off
	v_lshlrev_b64 v[50:51], 11, v[70:71]
	v_lshl_add_u64 v[50:51], s[56:57], 0, v[50:51]
	v_lshl_add_u64 v[52:53], v[50:51], 0, v[150:151]
	v_mad_i64_i32 v[50:51], s[24:25], v70, s48, v[154:155]
	v_lshl_add_u64 v[50:51], v[50:51], 0, s[94:95]
	v_lshl_add_u64 v[66:67], v[50:51], 0, v[150:151]
	global_load_dwordx4 v[62:65], v[52:53], off
	v_lshl_add_u64 v[50:51], v[50:51], 0, v[156:157]
	global_load_dwordx4 v[66:69], v[66:67], off
	s_waitcnt vmcnt(0)
	v_add_f32_e32 v42, v42, v54
	v_add_f32_e32 v46, v46, v58
	v_add_f32_e32 v47, v47, v59
	v_mul_f32_e32 v46, 0xbfb8aa3b, v46
	v_mul_f32_e32 v47, 0xbfb8aa3b, v47
	v_exp_f32_e32 v46, v46
	v_exp_f32_e32 v47, v47
	v_add_f32_e32 v43, v43, v55
	v_mul_f32_e32 v42, 0xbfb8aa3b, v42
	v_mul_f32_e32 v43, 0xbfb8aa3b, v43
	v_exp_f32_e32 v42, v42
	v_lshlrev_b32_e32 v72, 16, v66
	v_mul_f32_e32 v54, 0xbfb8aa3b, v72
	v_exp_f32_e32 v54, v54
	v_and_b32_e32 v73, 0xffff0000, v66
	v_exp_f32_e32 v43, v43
	v_add_f32_e32 v46, 1.0, v46
	v_add_f32_e32 v54, 1.0, v54
	v_rcp_f32_e32 v74, v54
	v_mul_f32_e32 v54, 0xbfb8aa3b, v73
	v_exp_f32_e32 v54, v54
	v_add_f32_e32 v47, 1.0, v47
	v_rcp_f32_e32 v46, v46
	v_rcp_f32_e32 v47, v47
	v_add_f32_e32 v54, 1.0, v54
	v_rcp_f32_e32 v75, v54
	v_add_f32_e32 v42, 1.0, v42
	v_add_f32_e32 v43, 1.0, v43
	v_rcp_f32_e32 v42, v42
	v_rcp_f32_e32 v43, v43
	v_lshlrev_b32_e32 v58, 16, v62
	v_and_b32_e32 v59, 0xffff0000, v62
	v_pk_mul_f32 v[46:47], v[46:47], v[58:59]
	v_pk_mul_f32 v[58:59], v[74:75], v[72:73]
	v_lshlrev_b32_e32 v54, 16, v64
	v_pk_mul_f32 v[46:47], v[46:47], v[58:59]
	v_and_b32_e32 v55, 0xffff0000, v64
	v_lshlrev_b32_e32 v58, 16, v68
	v_and_b32_e32 v59, 0xffff0000, v68
	v_mul_f32_e32 v62, 0xbfb8aa3b, v58
	v_pk_mul_f32 v[42:43], v[42:43], v[54:55]
	v_mul_f32_e32 v54, 0xbfb8aa3b, v59
	v_exp_f32_e32 v62, v62
	v_exp_f32_e32 v54, v54
	v_add_f32_e32 v62, 1.0, v62
	v_add_f32_e32 v54, 1.0, v54
	v_rcp_f32_e32 v72, v62
	v_rcp_f32_e32 v73, v54
	s_nop 0
	v_pk_mul_f32 v[54:55], v[72:73], v[58:59]
	s_nop 0
	v_pk_mul_f32 v[54:55], v[42:43], v[54:55]
	v_add_f32_e32 v43, v44, v56
	v_mul_f32_e32 v43, 0xbfb8aa3b, v43
	v_exp_f32_e32 v43, v43
	v_add_f32_e32 v42, v48, v60
	v_mul_f32_e32 v42, 0xbfb8aa3b, v42
	v_exp_f32_e32 v42, v42
	v_add_f32_e32 v43, 1.0, v43
	v_rcp_f32_e32 v44, v43
	v_add_f32_e32 v43, v49, v61
	v_mul_f32_e32 v43, 0xbfb8aa3b, v43
	v_exp_f32_e32 v43, v43
	v_add_f32_e32 v42, 1.0, v42
	v_rcp_f32_e32 v42, v42
	v_lshlrev_b32_e32 v48, 16, v63
	v_add_f32_e32 v43, 1.0, v43
	v_rcp_f32_e32 v43, v43
	v_and_b32_e32 v49, 0xffff0000, v63
	v_lshlrev_b32_e32 v58, 16, v67
	v_and_b32_e32 v59, 0xffff0000, v67
	v_mul_f32_e32 v56, 0xbfb8aa3b, v58
	v_pk_mul_f32 v[42:43], v[42:43], v[48:49]
	v_mul_f32_e32 v48, 0xbfb8aa3b, v59
	v_exp_f32_e32 v56, v56
	v_exp_f32_e32 v48, v48
	v_add_f32_e32 v56, 1.0, v56
	v_add_f32_e32 v48, 1.0, v48
	v_rcp_f32_e32 v60, v56
	v_rcp_f32_e32 v61, v48
	v_lshlrev_b32_e32 v56, 16, v69
	v_pk_mul_f32 v[48:49], v[60:61], v[58:59]
	s_nop 0
	v_pk_mul_f32 v[48:49], v[42:43], v[48:49]
	v_add_f32_e32 v42, v45, v57
	v_mul_f32_e32 v42, 0xbfb8aa3b, v42
	v_exp_f32_e32 v42, v42
	v_and_b32_e32 v43, 0xffff0000, v65
	v_and_b32_e32 v57, 0xffff0000, v69
	v_mul_f32_e32 v58, 0xbfb8aa3b, v56
	v_add_f32_e32 v42, 1.0, v42
	v_rcp_f32_e32 v45, v42
	v_lshlrev_b32_e32 v42, 16, v65
	v_exp_f32_e32 v58, v58
	v_pk_mul_f32 v[42:43], v[44:45], v[42:43]
	v_mul_f32_e32 v44, 0xbfb8aa3b, v57
	v_exp_f32_e32 v44, v44
	v_add_f32_e32 v58, 1.0, v58
	v_rcp_f32_e32 v58, v58
	v_add_f32_e32 v44, 1.0, v44
	v_rcp_f32_e32 v59, v44
	s_nop 0
	v_pk_mul_f32 v[44:45], v[58:59], v[56:57]
	s_nop 0
	v_pk_mul_f32 v[56:57], v[42:43], v[44:45]
	v_cvt_pk_bf16_f32 v42, v46, v47
	v_lshlrev_b64 v[46:47], 12, v[70:71]
	v_lshl_add_u64 v[46:47], s[36:37], 0, v[46:47]
	v_cvt_pk_bf16_f32 v43, v48, v49
	v_cvt_pk_bf16_f32 v44, v54, v55
	v_cvt_pk_bf16_f32 v45, v56, v57
	v_lshl_add_u64 v[58:59], v[46:47], 0, v[150:151]
	global_store_dwordx4 v[58:59], v[42:45], off offset:2048
	global_load_dwordx4 v[42:45], v[148:149], off offset:528
	s_nop 0
	global_load_dwordx4 v[46:49], v[148:149], off offset:512
	global_load_dwordx4 v[54:57], v[52:53], off offset:256
	s_waitcnt vmcnt(0)
	v_add_f32_e32 v34, v34, v42
	global_load_dwordx4 v[50:53], v[50:51], off
	v_add_f32_e32 v38, v38, v46
	v_add_f32_e32 v39, v39, v47
	v_mul_f32_e32 v38, 0xbfb8aa3b, v38
	v_mul_f32_e32 v39, 0xbfb8aa3b, v39
	v_exp_f32_e32 v38, v38
	v_exp_f32_e32 v39, v39
	v_add_f32_e32 v35, v35, v43
	v_mul_f32_e32 v34, 0xbfb8aa3b, v34
	v_mul_f32_e32 v35, 0xbfb8aa3b, v35
	v_exp_f32_e32 v34, v34
	v_exp_f32_e32 v35, v35
	v_add_f32_e32 v38, 1.0, v38
	v_add_f32_e32 v39, 1.0, v39
	v_rcp_f32_e32 v38, v38
	v_rcp_f32_e32 v39, v39
	v_add_f32_e32 v34, 1.0, v34
	v_add_f32_e32 v35, 1.0, v35
	v_rcp_f32_e32 v34, v34
	v_rcp_f32_e32 v35, v35
	v_lshlrev_b32_e32 v46, 16, v54
	v_and_b32_e32 v47, 0xffff0000, v54
	v_pk_mul_f32 v[38:39], v[38:39], v[46:47]
	v_and_b32_e32 v43, 0xffff0000, v56
	v_add_u32_e32 v54, 0xa0, v152
	s_waitcnt vmcnt(0)
	v_lshlrev_b32_e32 v60, 16, v50
	v_mul_f32_e32 v42, 0xbfb8aa3b, v60
	v_exp_f32_e32 v42, v42
	v_and_b32_e32 v61, 0xffff0000, v50
	v_add_f32_e32 v42, 1.0, v42
	v_rcp_f32_e32 v62, v42
	v_mul_f32_e32 v42, 0xbfb8aa3b, v61
	v_exp_f32_e32 v42, v42
	s_nop 0
	v_add_f32_e32 v42, 1.0, v42
	v_rcp_f32_e32 v63, v42
	v_lshlrev_b32_e32 v42, 16, v56
	v_pk_mul_f32 v[34:35], v[34:35], v[42:43]
	v_pk_mul_f32 v[46:47], v[62:63], v[60:61]
	s_nop 0
	v_pk_mul_f32 v[38:39], v[38:39], v[46:47]
	v_lshlrev_b32_e32 v46, 16, v52
	v_and_b32_e32 v47, 0xffff0000, v52
	v_mul_f32_e32 v50, 0xbfb8aa3b, v46
	v_mul_f32_e32 v42, 0xbfb8aa3b, v47
	v_exp_f32_e32 v50, v50
	v_exp_f32_e32 v42, v42
	v_add_f32_e32 v50, 1.0, v50
	v_add_f32_e32 v42, 1.0, v42
	v_rcp_f32_e32 v60, v50
	v_rcp_f32_e32 v61, v42
	s_nop 0
	v_pk_mul_f32 v[42:43], v[60:61], v[46:47]
	s_nop 0
	v_pk_mul_f32 v[42:43], v[34:35], v[42:43]
	v_add_f32_e32 v35, v36, v44
	v_mul_f32_e32 v35, 0xbfb8aa3b, v35
	v_exp_f32_e32 v35, v35
	v_add_f32_e32 v34, v40, v48
	v_mul_f32_e32 v34, 0xbfb8aa3b, v34
	v_exp_f32_e32 v34, v34
	v_add_f32_e32 v35, 1.0, v35
	v_rcp_f32_e32 v36, v35
	v_add_f32_e32 v35, v41, v49
	v_mul_f32_e32 v35, 0xbfb8aa3b, v35
	v_exp_f32_e32 v35, v35
	v_add_f32_e32 v34, 1.0, v34
	v_rcp_f32_e32 v34, v34
	v_lshlrev_b32_e32 v40, 16, v55
	v_add_f32_e32 v35, 1.0, v35
	v_rcp_f32_e32 v35, v35
	v_and_b32_e32 v41, 0xffff0000, v55
	v_lshlrev_b32_e32 v46, 16, v51
	v_and_b32_e32 v47, 0xffff0000, v51
	v_mul_f32_e32 v44, 0xbfb8aa3b, v46
	v_pk_mul_f32 v[34:35], v[34:35], v[40:41]
	v_mul_f32_e32 v40, 0xbfb8aa3b, v47
	v_exp_f32_e32 v44, v44
	v_exp_f32_e32 v40, v40
	v_ashrrev_i32_e32 v55, 31, v54
	v_add_f32_e32 v44, 1.0, v44
	v_add_f32_e32 v40, 1.0, v40
	v_rcp_f32_e32 v48, v44
	v_rcp_f32_e32 v49, v40
	v_lshlrev_b32_e32 v44, 16, v53
	v_pk_mul_f32 v[40:41], v[48:49], v[46:47]
	s_nop 0
	v_pk_mul_f32 v[40:41], v[34:35], v[40:41]
	v_add_f32_e32 v34, v37, v45
	v_mul_f32_e32 v34, 0xbfb8aa3b, v34
	v_exp_f32_e32 v34, v34
	v_and_b32_e32 v35, 0xffff0000, v57
	v_and_b32_e32 v45, 0xffff0000, v53
	v_mul_f32_e32 v46, 0xbfb8aa3b, v44
	v_add_f32_e32 v34, 1.0, v34
	v_rcp_f32_e32 v37, v34
	v_lshlrev_b32_e32 v34, 16, v57
	v_exp_f32_e32 v46, v46
	v_pk_mul_f32 v[34:35], v[36:37], v[34:35]
	v_mul_f32_e32 v36, 0xbfb8aa3b, v45
	v_exp_f32_e32 v36, v36
	v_add_f32_e32 v46, 1.0, v46
	v_rcp_f32_e32 v46, v46
	v_add_f32_e32 v36, 1.0, v36
	v_rcp_f32_e32 v47, v36
	s_nop 0
	v_pk_mul_f32 v[36:37], v[46:47], v[44:45]
	s_nop 0
	v_pk_mul_f32 v[44:45], v[34:35], v[36:37]
	v_cvt_pk_bf16_f32 v34, v38, v39
	v_cvt_pk_bf16_f32 v35, v40, v41
	v_cvt_pk_bf16_f32 v36, v42, v43
	v_cvt_pk_bf16_f32 v37, v44, v45
	global_store_dwordx4 v[58:59], v[34:37], off offset:2304
	global_load_dwordx4 v[38:41], v[148:149], off offset:16
	global_load_dwordx4 v[42:45], v[148:149], off
	v_lshlrev_b64 v[34:35], 11, v[54:55]
	v_lshl_add_u64 v[34:35], s[56:57], 0, v[34:35]
	v_lshl_add_u64 v[36:37], v[34:35], 0, v[150:151]
	v_mad_i64_i32 v[34:35], s[24:25], v54, s48, v[154:155]
	v_lshl_add_u64 v[34:35], v[34:35], 0, s[94:95]
	v_lshl_add_u64 v[50:51], v[34:35], 0, v[150:151]
	global_load_dwordx4 v[46:49], v[36:37], off
	v_lshl_add_u64 v[34:35], v[34:35], 0, v[156:157]
	global_load_dwordx4 v[50:53], v[50:51], off
	s_waitcnt vmcnt(0)
	v_add_f32_e32 v26, v26, v38
	v_add_f32_e32 v30, v30, v42
	v_add_f32_e32 v31, v31, v43
	v_mul_f32_e32 v30, 0xbfb8aa3b, v30
	v_mul_f32_e32 v31, 0xbfb8aa3b, v31
	v_exp_f32_e32 v30, v30
	v_exp_f32_e32 v31, v31
	v_add_f32_e32 v27, v27, v39
	v_mul_f32_e32 v26, 0xbfb8aa3b, v26
	v_mul_f32_e32 v27, 0xbfb8aa3b, v27
	v_exp_f32_e32 v26, v26
	v_lshlrev_b32_e32 v56, 16, v50
	v_mul_f32_e32 v38, 0xbfb8aa3b, v56
	v_exp_f32_e32 v38, v38
	v_and_b32_e32 v57, 0xffff0000, v50
	v_exp_f32_e32 v27, v27
	v_add_f32_e32 v30, 1.0, v30
	v_add_f32_e32 v38, 1.0, v38
	v_rcp_f32_e32 v58, v38
	v_mul_f32_e32 v38, 0xbfb8aa3b, v57
	v_exp_f32_e32 v38, v38
	v_add_f32_e32 v31, 1.0, v31
	v_rcp_f32_e32 v30, v30
	v_rcp_f32_e32 v31, v31
	v_add_f32_e32 v38, 1.0, v38
	v_rcp_f32_e32 v59, v38
	v_add_f32_e32 v26, 1.0, v26
	v_add_f32_e32 v27, 1.0, v27
	v_rcp_f32_e32 v26, v26
	v_rcp_f32_e32 v27, v27
	v_lshlrev_b32_e32 v42, 16, v46
	v_and_b32_e32 v43, 0xffff0000, v46
	v_pk_mul_f32 v[30:31], v[30:31], v[42:43]
	v_pk_mul_f32 v[42:43], v[58:59], v[56:57]
	v_lshlrev_b32_e32 v38, 16, v48
	v_pk_mul_f32 v[30:31], v[30:31], v[42:43]
	v_and_b32_e32 v39, 0xffff0000, v48
	v_lshlrev_b32_e32 v42, 16, v52
	v_and_b32_e32 v43, 0xffff0000, v52
	v_mul_f32_e32 v46, 0xbfb8aa3b, v42
	v_pk_mul_f32 v[26:27], v[26:27], v[38:39]
	v_mul_f32_e32 v38, 0xbfb8aa3b, v43
	v_exp_f32_e32 v46, v46
	v_exp_f32_e32 v38, v38
	v_add_f32_e32 v46, 1.0, v46
	v_add_f32_e32 v38, 1.0, v38
	v_rcp_f32_e32 v56, v46
	v_rcp_f32_e32 v57, v38
	s_nop 0
	v_pk_mul_f32 v[38:39], v[56:57], v[42:43]
	s_nop 0
	v_pk_mul_f32 v[38:39], v[26:27], v[38:39]
	v_add_f32_e32 v27, v28, v40
	v_mul_f32_e32 v27, 0xbfb8aa3b, v27
	v_exp_f32_e32 v27, v27
	v_add_f32_e32 v26, v32, v44
	v_mul_f32_e32 v26, 0xbfb8aa3b, v26
	v_exp_f32_e32 v26, v26
	v_add_f32_e32 v27, 1.0, v27
	v_rcp_f32_e32 v28, v27
	v_add_f32_e32 v27, v33, v45
	v_mul_f32_e32 v27, 0xbfb8aa3b, v27
	v_exp_f32_e32 v27, v27
	v_add_f32_e32 v26, 1.0, v26
	v_rcp_f32_e32 v26, v26
	v_lshlrev_b32_e32 v32, 16, v47
	v_add_f32_e32 v27, 1.0, v27
	v_rcp_f32_e32 v27, v27
	v_and_b32_e32 v33, 0xffff0000, v47
	v_lshlrev_b32_e32 v42, 16, v51
	v_and_b32_e32 v43, 0xffff0000, v51
	v_mul_f32_e32 v40, 0xbfb8aa3b, v42
	v_pk_mul_f32 v[26:27], v[26:27], v[32:33]
	v_mul_f32_e32 v32, 0xbfb8aa3b, v43
	v_exp_f32_e32 v40, v40
	v_exp_f32_e32 v32, v32
	v_add_f32_e32 v40, 1.0, v40
	v_add_f32_e32 v32, 1.0, v32
	v_rcp_f32_e32 v44, v40
	v_rcp_f32_e32 v45, v32
	v_lshlrev_b32_e32 v40, 16, v53
	v_pk_mul_f32 v[32:33], v[44:45], v[42:43]
	s_nop 0
	v_pk_mul_f32 v[32:33], v[26:27], v[32:33]
	v_add_f32_e32 v26, v29, v41
	v_mul_f32_e32 v26, 0xbfb8aa3b, v26
	v_exp_f32_e32 v26, v26
	v_and_b32_e32 v27, 0xffff0000, v49
	v_and_b32_e32 v41, 0xffff0000, v53
	v_mul_f32_e32 v42, 0xbfb8aa3b, v40
	v_add_f32_e32 v26, 1.0, v26
	v_rcp_f32_e32 v29, v26
	v_lshlrev_b32_e32 v26, 16, v49
	v_exp_f32_e32 v42, v42
	v_pk_mul_f32 v[26:27], v[28:29], v[26:27]
	v_mul_f32_e32 v28, 0xbfb8aa3b, v41
	v_exp_f32_e32 v28, v28
	v_add_f32_e32 v42, 1.0, v42
	v_rcp_f32_e32 v42, v42
	v_add_f32_e32 v28, 1.0, v28
	v_rcp_f32_e32 v43, v28
	s_nop 0
	v_pk_mul_f32 v[28:29], v[42:43], v[40:41]
	s_nop 0
	v_pk_mul_f32 v[40:41], v[26:27], v[28:29]
	v_cvt_pk_bf16_f32 v26, v30, v31
	v_lshlrev_b64 v[30:31], 12, v[54:55]
	v_lshl_add_u64 v[30:31], s[36:37], 0, v[30:31]
	v_cvt_pk_bf16_f32 v27, v32, v33
	v_cvt_pk_bf16_f32 v28, v38, v39
	v_cvt_pk_bf16_f32 v29, v40, v41
	v_lshl_add_u64 v[42:43], v[30:31], 0, v[150:151]
	global_store_dwordx4 v[42:43], v[26:29], off offset:2048
	global_load_dwordx4 v[26:29], v[148:149], off offset:528
	s_nop 0
	global_load_dwordx4 v[30:33], v[148:149], off offset:512
	global_load_dwordx4 v[38:41], v[36:37], off offset:256
	s_waitcnt vmcnt(0)
	v_add_f32_e32 v18, v18, v26
	global_load_dwordx4 v[34:37], v[34:35], off
	v_add_f32_e32 v22, v22, v30
	v_add_f32_e32 v23, v23, v31
	v_mul_f32_e32 v22, 0xbfb8aa3b, v22
	v_mul_f32_e32 v23, 0xbfb8aa3b, v23
	v_exp_f32_e32 v22, v22
	v_exp_f32_e32 v23, v23
	v_add_f32_e32 v19, v19, v27
	v_mul_f32_e32 v18, 0xbfb8aa3b, v18
	v_mul_f32_e32 v19, 0xbfb8aa3b, v19
	v_exp_f32_e32 v18, v18
	v_exp_f32_e32 v19, v19
	v_add_f32_e32 v22, 1.0, v22
	v_add_f32_e32 v23, 1.0, v23
	v_rcp_f32_e32 v22, v22
	v_rcp_f32_e32 v23, v23
	v_add_f32_e32 v18, 1.0, v18
	v_add_f32_e32 v19, 1.0, v19
	v_rcp_f32_e32 v18, v18
	v_rcp_f32_e32 v19, v19
	v_lshlrev_b32_e32 v30, 16, v38
	v_and_b32_e32 v31, 0xffff0000, v38
	v_pk_mul_f32 v[22:23], v[22:23], v[30:31]
	v_and_b32_e32 v27, 0xffff0000, v40
	v_add_u32_e32 v38, 0xb0, v152
	s_waitcnt vmcnt(0)
	v_lshlrev_b32_e32 v44, 16, v34
	v_mul_f32_e32 v26, 0xbfb8aa3b, v44
	v_exp_f32_e32 v26, v26
	v_and_b32_e32 v45, 0xffff0000, v34
	v_add_f32_e32 v26, 1.0, v26
	v_rcp_f32_e32 v46, v26
	v_mul_f32_e32 v26, 0xbfb8aa3b, v45
	v_exp_f32_e32 v26, v26
	s_nop 0
	v_add_f32_e32 v26, 1.0, v26
	v_rcp_f32_e32 v47, v26
	v_lshlrev_b32_e32 v26, 16, v40
	v_pk_mul_f32 v[18:19], v[18:19], v[26:27]
	v_pk_mul_f32 v[30:31], v[46:47], v[44:45]
	s_nop 0
	v_pk_mul_f32 v[22:23], v[22:23], v[30:31]
	v_lshlrev_b32_e32 v30, 16, v36
	v_and_b32_e32 v31, 0xffff0000, v36
	v_mul_f32_e32 v34, 0xbfb8aa3b, v30
	v_mul_f32_e32 v26, 0xbfb8aa3b, v31
	v_exp_f32_e32 v34, v34
	v_exp_f32_e32 v26, v26
	v_add_f32_e32 v34, 1.0, v34
	v_add_f32_e32 v26, 1.0, v26
	v_rcp_f32_e32 v44, v34
	v_rcp_f32_e32 v45, v26
	s_nop 0
	v_pk_mul_f32 v[26:27], v[44:45], v[30:31]
	s_nop 0
	v_pk_mul_f32 v[26:27], v[18:19], v[26:27]
	v_add_f32_e32 v19, v20, v28
	v_mul_f32_e32 v19, 0xbfb8aa3b, v19
	v_exp_f32_e32 v19, v19
	v_add_f32_e32 v18, v24, v32
	v_mul_f32_e32 v18, 0xbfb8aa3b, v18
	v_exp_f32_e32 v18, v18
	v_add_f32_e32 v19, 1.0, v19
	v_rcp_f32_e32 v20, v19
	v_add_f32_e32 v19, v25, v33
	v_mul_f32_e32 v19, 0xbfb8aa3b, v19
	v_exp_f32_e32 v19, v19
	v_add_f32_e32 v18, 1.0, v18
	v_rcp_f32_e32 v18, v18
	v_lshlrev_b32_e32 v24, 16, v39
	v_add_f32_e32 v19, 1.0, v19
	v_rcp_f32_e32 v19, v19
	v_and_b32_e32 v25, 0xffff0000, v39
	v_lshlrev_b32_e32 v30, 16, v35
	v_and_b32_e32 v31, 0xffff0000, v35
	v_mul_f32_e32 v28, 0xbfb8aa3b, v30
	v_pk_mul_f32 v[18:19], v[18:19], v[24:25]
	v_mul_f32_e32 v24, 0xbfb8aa3b, v31
	v_exp_f32_e32 v28, v28
	v_exp_f32_e32 v24, v24
	v_ashrrev_i32_e32 v39, 31, v38
	v_add_f32_e32 v28, 1.0, v28
	v_add_f32_e32 v24, 1.0, v24
	v_rcp_f32_e32 v32, v28
	v_rcp_f32_e32 v33, v24
	v_lshlrev_b32_e32 v28, 16, v37
	v_pk_mul_f32 v[24:25], v[32:33], v[30:31]
	s_nop 0
	v_pk_mul_f32 v[24:25], v[18:19], v[24:25]
	v_add_f32_e32 v18, v21, v29
	v_mul_f32_e32 v18, 0xbfb8aa3b, v18
	v_exp_f32_e32 v18, v18
	v_and_b32_e32 v19, 0xffff0000, v41
	v_and_b32_e32 v29, 0xffff0000, v37
	v_mul_f32_e32 v30, 0xbfb8aa3b, v28
	v_add_f32_e32 v18, 1.0, v18
	v_rcp_f32_e32 v21, v18
	v_lshlrev_b32_e32 v18, 16, v41
	v_exp_f32_e32 v30, v30
	v_pk_mul_f32 v[18:19], v[20:21], v[18:19]
	v_mul_f32_e32 v20, 0xbfb8aa3b, v29
	v_exp_f32_e32 v20, v20
	v_add_f32_e32 v30, 1.0, v30
	v_rcp_f32_e32 v30, v30
	v_add_f32_e32 v20, 1.0, v20
	v_rcp_f32_e32 v31, v20
	s_nop 0
	v_pk_mul_f32 v[20:21], v[30:31], v[28:29]
	s_nop 0
	v_pk_mul_f32 v[28:29], v[18:19], v[20:21]
	v_cvt_pk_bf16_f32 v18, v22, v23
	v_cvt_pk_bf16_f32 v19, v24, v25
	v_cvt_pk_bf16_f32 v20, v26, v27
	v_cvt_pk_bf16_f32 v21, v28, v29
	global_store_dwordx4 v[42:43], v[18:21], off offset:2304
	global_load_dwordx4 v[22:25], v[148:149], off offset:16
	global_load_dwordx4 v[26:29], v[148:149], off
	v_lshlrev_b64 v[18:19], 11, v[38:39]
	v_lshl_add_u64 v[18:19], s[56:57], 0, v[18:19]
	v_lshl_add_u64 v[20:21], v[18:19], 0, v[150:151]
	v_mad_i64_i32 v[18:19], s[24:25], v38, s48, v[154:155]
	v_lshl_add_u64 v[18:19], v[18:19], 0, s[94:95]
	v_lshl_add_u64 v[34:35], v[18:19], 0, v[150:151]
	global_load_dwordx4 v[30:33], v[20:21], off
	v_lshl_add_u64 v[18:19], v[18:19], 0, v[156:157]
	global_load_dwordx4 v[34:37], v[34:35], off
	s_waitcnt vmcnt(0)
	v_add_f32_e32 v10, v10, v22
	v_add_f32_e32 v14, v14, v26
	v_add_f32_e32 v15, v15, v27
	v_mul_f32_e32 v14, 0xbfb8aa3b, v14
	v_mul_f32_e32 v15, 0xbfb8aa3b, v15
	v_exp_f32_e32 v14, v14
	v_exp_f32_e32 v15, v15
	v_add_f32_e32 v11, v11, v23
	v_mul_f32_e32 v10, 0xbfb8aa3b, v10
	v_mul_f32_e32 v11, 0xbfb8aa3b, v11
	v_exp_f32_e32 v10, v10
	v_lshlrev_b32_e32 v40, 16, v34
	v_mul_f32_e32 v22, 0xbfb8aa3b, v40
	v_exp_f32_e32 v22, v22
	v_and_b32_e32 v41, 0xffff0000, v34
	v_exp_f32_e32 v11, v11
	v_add_f32_e32 v14, 1.0, v14
	v_add_f32_e32 v22, 1.0, v22
	v_rcp_f32_e32 v42, v22
	v_mul_f32_e32 v22, 0xbfb8aa3b, v41
	v_exp_f32_e32 v22, v22
	v_add_f32_e32 v15, 1.0, v15
	v_rcp_f32_e32 v14, v14
	v_rcp_f32_e32 v15, v15
	v_add_f32_e32 v22, 1.0, v22
	v_rcp_f32_e32 v43, v22
	v_add_f32_e32 v10, 1.0, v10
	v_add_f32_e32 v11, 1.0, v11
	v_rcp_f32_e32 v10, v10
	v_rcp_f32_e32 v11, v11
	v_lshlrev_b32_e32 v26, 16, v30
	v_and_b32_e32 v27, 0xffff0000, v30
	v_pk_mul_f32 v[14:15], v[14:15], v[26:27]
	v_pk_mul_f32 v[26:27], v[42:43], v[40:41]
	v_lshlrev_b32_e32 v22, 16, v32
	v_pk_mul_f32 v[14:15], v[14:15], v[26:27]
	v_and_b32_e32 v23, 0xffff0000, v32
	v_lshlrev_b32_e32 v26, 16, v36
	v_and_b32_e32 v27, 0xffff0000, v36
	v_mul_f32_e32 v30, 0xbfb8aa3b, v26
	v_pk_mul_f32 v[10:11], v[10:11], v[22:23]
	v_mul_f32_e32 v22, 0xbfb8aa3b, v27
	v_exp_f32_e32 v30, v30
	v_exp_f32_e32 v22, v22
	v_add_f32_e32 v30, 1.0, v30
	v_add_f32_e32 v22, 1.0, v22
	v_rcp_f32_e32 v40, v30
	v_rcp_f32_e32 v41, v22
	s_nop 0
	v_pk_mul_f32 v[22:23], v[40:41], v[26:27]
	s_nop 0
	v_pk_mul_f32 v[22:23], v[10:11], v[22:23]
	v_add_f32_e32 v11, v12, v24
	v_mul_f32_e32 v11, 0xbfb8aa3b, v11
	v_exp_f32_e32 v11, v11
	v_add_f32_e32 v10, v16, v28
	v_mul_f32_e32 v10, 0xbfb8aa3b, v10
	v_exp_f32_e32 v10, v10
	v_add_f32_e32 v11, 1.0, v11
	v_rcp_f32_e32 v12, v11
	v_add_f32_e32 v11, v17, v29
	v_mul_f32_e32 v11, 0xbfb8aa3b, v11
	v_exp_f32_e32 v11, v11
	v_add_f32_e32 v10, 1.0, v10
	v_rcp_f32_e32 v10, v10
	v_lshlrev_b32_e32 v16, 16, v31
	v_add_f32_e32 v11, 1.0, v11
	v_rcp_f32_e32 v11, v11
	v_and_b32_e32 v17, 0xffff0000, v31
	v_lshlrev_b32_e32 v26, 16, v35
	v_and_b32_e32 v27, 0xffff0000, v35
	v_mul_f32_e32 v24, 0xbfb8aa3b, v26
	v_pk_mul_f32 v[10:11], v[10:11], v[16:17]
	v_mul_f32_e32 v16, 0xbfb8aa3b, v27
	v_exp_f32_e32 v24, v24
	v_exp_f32_e32 v16, v16
	v_add_f32_e32 v24, 1.0, v24
	v_add_f32_e32 v16, 1.0, v16
	v_rcp_f32_e32 v28, v24
	v_rcp_f32_e32 v29, v16
	v_lshlrev_b32_e32 v24, 16, v37
	v_pk_mul_f32 v[16:17], v[28:29], v[26:27]
	s_nop 0
	v_pk_mul_f32 v[16:17], v[10:11], v[16:17]
	v_add_f32_e32 v10, v13, v25
	v_mul_f32_e32 v10, 0xbfb8aa3b, v10
	v_exp_f32_e32 v10, v10
	v_and_b32_e32 v11, 0xffff0000, v33
	v_and_b32_e32 v25, 0xffff0000, v37
	v_mul_f32_e32 v26, 0xbfb8aa3b, v24
	v_add_f32_e32 v10, 1.0, v10
	v_rcp_f32_e32 v13, v10
	v_lshlrev_b32_e32 v10, 16, v33
	v_exp_f32_e32 v26, v26
	v_pk_mul_f32 v[10:11], v[12:13], v[10:11]
	v_mul_f32_e32 v12, 0xbfb8aa3b, v25
	v_exp_f32_e32 v12, v12
	v_add_f32_e32 v26, 1.0, v26
	v_rcp_f32_e32 v26, v26
	v_add_f32_e32 v12, 1.0, v12
	v_rcp_f32_e32 v27, v12
	s_nop 0
	v_pk_mul_f32 v[12:13], v[26:27], v[24:25]
	s_nop 0
	v_pk_mul_f32 v[24:25], v[10:11], v[12:13]
	v_cvt_pk_bf16_f32 v10, v14, v15
	v_lshlrev_b64 v[14:15], 12, v[38:39]
	v_lshl_add_u64 v[14:15], s[36:37], 0, v[14:15]
	v_cvt_pk_bf16_f32 v11, v16, v17
	v_cvt_pk_bf16_f32 v12, v22, v23
	v_cvt_pk_bf16_f32 v13, v24, v25
	v_lshl_add_u64 v[26:27], v[14:15], 0, v[150:151]
	global_store_dwordx4 v[26:27], v[10:13], off offset:2048
	global_load_dwordx4 v[10:13], v[148:149], off offset:528
	s_nop 0
	global_load_dwordx4 v[14:17], v[148:149], off offset:512
	global_load_dwordx4 v[22:25], v[20:21], off offset:256
	s_waitcnt vmcnt(0)
	v_add_f32_e32 v2, v2, v10
	global_load_dwordx4 v[18:21], v[18:19], off
	v_add_f32_e32 v6, v6, v14
	v_add_f32_e32 v7, v7, v15
	v_mul_f32_e32 v6, 0xbfb8aa3b, v6
	v_mul_f32_e32 v7, 0xbfb8aa3b, v7
	v_exp_f32_e32 v6, v6
	v_exp_f32_e32 v7, v7
	v_add_f32_e32 v3, v3, v11
	v_mul_f32_e32 v2, 0xbfb8aa3b, v2
	v_mul_f32_e32 v3, 0xbfb8aa3b, v3
	v_exp_f32_e32 v2, v2
	v_exp_f32_e32 v3, v3
	v_add_f32_e32 v6, 1.0, v6
	v_add_f32_e32 v7, 1.0, v7
	v_rcp_f32_e32 v6, v6
	v_rcp_f32_e32 v7, v7
	v_add_f32_e32 v2, 1.0, v2
	v_add_f32_e32 v3, 1.0, v3
	v_rcp_f32_e32 v2, v2
	v_rcp_f32_e32 v3, v3
	v_lshlrev_b32_e32 v14, 16, v22
	v_and_b32_e32 v15, 0xffff0000, v22
	v_pk_mul_f32 v[6:7], v[6:7], v[14:15]
	v_and_b32_e32 v11, 0xffff0000, v24
	s_waitcnt vmcnt(0)
	v_lshlrev_b32_e32 v28, 16, v18
	v_mul_f32_e32 v10, 0xbfb8aa3b, v28
	v_exp_f32_e32 v10, v10
	v_and_b32_e32 v29, 0xffff0000, v18
	v_add_f32_e32 v10, 1.0, v10
	v_rcp_f32_e32 v30, v10
	v_mul_f32_e32 v10, 0xbfb8aa3b, v29
	v_exp_f32_e32 v10, v10
	s_nop 0
	v_add_f32_e32 v10, 1.0, v10
	v_rcp_f32_e32 v31, v10
	v_lshlrev_b32_e32 v10, 16, v24
	v_pk_mul_f32 v[2:3], v[2:3], v[10:11]
	v_pk_mul_f32 v[14:15], v[30:31], v[28:29]
	s_nop 0
	v_pk_mul_f32 v[6:7], v[6:7], v[14:15]
	v_lshlrev_b32_e32 v14, 16, v20
	v_and_b32_e32 v15, 0xffff0000, v20
	v_mul_f32_e32 v18, 0xbfb8aa3b, v14
	v_mul_f32_e32 v10, 0xbfb8aa3b, v15
	v_exp_f32_e32 v18, v18
	v_exp_f32_e32 v10, v10
	v_add_f32_e32 v18, 1.0, v18
	v_add_f32_e32 v10, 1.0, v10
	v_rcp_f32_e32 v28, v18
	v_rcp_f32_e32 v29, v10
	s_nop 0
	v_pk_mul_f32 v[10:11], v[28:29], v[14:15]
	s_nop 0
	v_pk_mul_f32 v[10:11], v[2:3], v[10:11]
	v_add_f32_e32 v3, v4, v12
	v_mul_f32_e32 v3, 0xbfb8aa3b, v3
	v_exp_f32_e32 v3, v3
	v_add_f32_e32 v2, v8, v16
	v_mul_f32_e32 v2, 0xbfb8aa3b, v2
	v_exp_f32_e32 v2, v2
	v_add_f32_e32 v3, 1.0, v3
	v_rcp_f32_e32 v4, v3
	v_add_f32_e32 v3, v9, v17
	v_mul_f32_e32 v3, 0xbfb8aa3b, v3
	v_exp_f32_e32 v3, v3
	v_add_f32_e32 v2, 1.0, v2
	v_rcp_f32_e32 v2, v2
	v_lshlrev_b32_e32 v8, 16, v23
	v_add_f32_e32 v3, 1.0, v3
	v_rcp_f32_e32 v3, v3
	v_and_b32_e32 v9, 0xffff0000, v23
	v_lshlrev_b32_e32 v14, 16, v19
	v_and_b32_e32 v15, 0xffff0000, v19
	v_mul_f32_e32 v12, 0xbfb8aa3b, v14
	v_pk_mul_f32 v[2:3], v[2:3], v[8:9]
	v_mul_f32_e32 v8, 0xbfb8aa3b, v15
	v_exp_f32_e32 v12, v12
	v_exp_f32_e32 v8, v8
	v_add_f32_e32 v12, 1.0, v12
	v_add_f32_e32 v8, 1.0, v8
	v_rcp_f32_e32 v16, v12
	v_rcp_f32_e32 v17, v8
	v_lshlrev_b32_e32 v12, 16, v21
	v_pk_mul_f32 v[8:9], v[16:17], v[14:15]
	s_nop 0
	v_pk_mul_f32 v[8:9], v[2:3], v[8:9]
	v_add_f32_e32 v2, v5, v13
	v_mul_f32_e32 v2, 0xbfb8aa3b, v2
	v_exp_f32_e32 v2, v2
	v_and_b32_e32 v3, 0xffff0000, v25
	v_and_b32_e32 v13, 0xffff0000, v21
	v_mul_f32_e32 v14, 0xbfb8aa3b, v12
	v_add_f32_e32 v2, 1.0, v2
	v_rcp_f32_e32 v5, v2
	v_lshlrev_b32_e32 v2, 16, v25
	v_exp_f32_e32 v14, v14
	v_pk_mul_f32 v[2:3], v[4:5], v[2:3]
	v_mul_f32_e32 v4, 0xbfb8aa3b, v13
	v_exp_f32_e32 v4, v4
	v_add_f32_e32 v14, 1.0, v14
	v_rcp_f32_e32 v14, v14
	v_add_f32_e32 v4, 1.0, v4
	v_rcp_f32_e32 v15, v4
	s_nop 0
	v_pk_mul_f32 v[4:5], v[14:15], v[12:13]
	s_nop 0
	v_pk_mul_f32 v[12:13], v[2:3], v[4:5]
	v_cvt_pk_bf16_f32 v2, v6, v7
	v_cvt_pk_bf16_f32 v3, v8, v9
	v_cvt_pk_bf16_f32 v4, v10, v11
	v_cvt_pk_bf16_f32 v5, v12, v13
	global_store_dwordx4 v[26:27], v[2:5], off offset:2304
	s_cbranch_vccz .LBB0_970
	v_readlane_b32 s4, v254, 12
	s_waitcnt vmcnt(0)
	v_readlane_b32 s5, v254, 13
	s_andn2_b64 vcc, exec, s[4:5]
	s_cbranch_vccnz .LBB0_981
	s_barrier

.LBB0_1044:
	s_add_u32 s2, s68, 0xfff80080
	s_addc_u32 s17, s69, -1
	s_add_i32 s26, 0, 0x10000
	v_add_u32_e32 v156, s26, v141
	ds_read_b128 v[144:147], v156
	ds_read_b128 v[148:151], v156 offset:1024
	ds_read_b128 v[152:155], v156 offset:2048
	ds_read_b128 v[156:159], v156 offset:3072
	s_cmp_eq_u32 s44, 28
	s_cselect_b32 s73, s55, s17
	s_cselect_b32 s72, s24, s2
	s_cselect_b32 s71, s25, s92
	s_cselect_b32 s70, s43, s83
	v_lshl_add_u64 v[164:165], s[68:69], 0, v[136:137]
	s_add_i32 m0, s58, 0xc000
	ds_read_b128 v[160:163], v143
	ds_read_b128 v[188:191], v143 offset:1024
	ds_read_b128 v[192:195], v143 offset:2048
	ds_read_b128 v[196:199], v143 offset:3072
	ds_read_b128 v[200:203], v143 offset:4096
	ds_read_b128 v[216:219], v143 offset:5120
	ds_read_b128 v[220:223], v143 offset:6144
	ds_read_b128 v[224:227], v143 offset:7168
	global_load_lds_dwordx4 v[164:165], off
	v_lshl_add_u64 v[164:165], s[68:69], 0, v[138:139]
	s_add_i32 m0, s58, 0xe000
	s_nop 0
	global_load_lds_dwordx4 v[164:165], off
	s_waitcnt lgkmcnt(8)
	s_barrier
	s_waitcnt lgkmcnt(7)
	v_mfma_f32_16x16x32_bf16 v[126:129], v[144:147], v[160:163], v[126:129]
	v_mfma_f32_16x16x32_bf16 v[122:125], v[152:155], v[160:163], v[122:125]
	s_waitcnt lgkmcnt(5)
	v_mfma_f32_16x16x32_bf16 v[118:121], v[144:147], v[192:195], v[118:121]
	v_mfma_f32_16x16x32_bf16 v[114:117], v[152:155], v[192:195], v[114:117]
	s_waitcnt lgkmcnt(3)
	v_mfma_f32_16x16x32_bf16 v[102:105], v[144:147], v[200:203], v[102:105]
	v_mfma_f32_16x16x32_bf16 v[98:101], v[152:155], v[200:203], v[98:101]
	s_waitcnt lgkmcnt(1)
	v_mfma_f32_16x16x32_bf16 v[86:89], v[144:147], v[220:223], v[86:89]
	v_mfma_f32_16x16x32_bf16 v[82:85], v[152:155], v[220:223], v[82:85]
	s_add_i32 s2, 0, 0x14000
	v_add_u32_e32 v164, s2, v141
	ds_read_b128 v[228:231], v164
	ds_read_b128 v[232:235], v164 offset:1024
	ds_read_b128 v[236:239], v164 offset:2048
	ds_read_b128 v[240:243], v164 offset:3072
	v_mfma_f32_16x16x32_bf16 v[126:129], v[148:151], v[188:191], v[126:129]
	v_mfma_f32_16x16x32_bf16 v[122:125], v[156:159], v[188:191], v[122:125]
	v_mfma_f32_16x16x32_bf16 v[118:121], v[148:151], v[196:199], v[118:121]
	v_mfma_f32_16x16x32_bf16 v[114:117], v[156:159], v[196:199], v[114:117]
	v_mfma_f32_16x16x32_bf16 v[102:105], v[148:151], v[216:219], v[102:105]
	v_mfma_f32_16x16x32_bf16 v[98:101], v[156:159], v[216:219], v[98:101]
	s_waitcnt lgkmcnt(4)
	v_mfma_f32_16x16x32_bf16 v[86:89], v[148:151], v[224:227], v[86:89]
	v_mfma_f32_16x16x32_bf16 v[82:85], v[156:159], v[224:227], v[82:85]
	s_barrier
	s_add_i32 s17, s26, s3
	v_lshl_add_u64 v[164:165], s[70:71], 0, v[0:1]
	s_mov_b32 m0, s17
	v_lshl_add_u64 v[204:205], s[70:71], 0, v[130:131]
	global_load_lds_dwordx4 v[164:165], off
	s_add_i32 m0, s17, 0x2000
	s_nop 0
	global_load_lds_dwordx4 v[204:205], off
	s_barrier
	s_waitcnt lgkmcnt(3)
	v_mfma_f32_16x16x32_bf16 v[110:113], v[228:231], v[160:163], v[110:113]
	s_waitcnt lgkmcnt(1)
	v_mfma_f32_16x16x32_bf16 v[106:109], v[236:239], v[160:163], v[106:109]
	v_mfma_f32_16x16x32_bf16 v[94:97], v[228:231], v[192:195], v[94:97]
	v_mfma_f32_16x16x32_bf16 v[90:93], v[236:239], v[192:195], v[90:93]
	v_mfma_f32_16x16x32_bf16 v[78:81], v[228:231], v[200:203], v[78:81]
	v_mfma_f32_16x16x32_bf16 v[74:77], v[236:239], v[200:203], v[74:77]
	v_mfma_f32_16x16x32_bf16 v[70:73], v[228:231], v[220:223], v[70:73]
	v_mfma_f32_16x16x32_bf16 v[66:69], v[236:239], v[220:223], v[66:69]
	v_mfma_f32_16x16x32_bf16 v[110:113], v[232:235], v[188:191], v[110:113]
	s_waitcnt lgkmcnt(0)
	v_mfma_f32_16x16x32_bf16 v[106:109], v[240:243], v[188:191], v[106:109]
	v_mfma_f32_16x16x32_bf16 v[94:97], v[232:235], v[196:199], v[94:97]
	v_mfma_f32_16x16x32_bf16 v[90:93], v[240:243], v[196:199], v[90:93]
	v_mfma_f32_16x16x32_bf16 v[78:81], v[232:235], v[216:219], v[78:81]
	v_mfma_f32_16x16x32_bf16 v[74:77], v[240:243], v[216:219], v[74:77]
	v_mfma_f32_16x16x32_bf16 v[70:73], v[232:235], v[224:227], v[70:73]
	v_mfma_f32_16x16x32_bf16 v[66:69], v[240:243], v[224:227], v[66:69]
	s_mov_b32 m0, s58
	v_lshl_add_u64 v[244:245], s[72:73], 0, v[134:135]
	s_barrier
	ds_read_b128 v[160:163], v143 offset:16384
	ds_read_b128 v[188:191], v143 offset:17408
	ds_read_b128 v[192:195], v143 offset:18432
	ds_read_b128 v[196:199], v143 offset:19456
	ds_read_b128 v[200:203], v143 offset:20480
	ds_read_b128 v[216:219], v143 offset:21504
	ds_read_b128 v[220:223], v143 offset:22528
	ds_read_b128 v[224:227], v143 offset:23552
	global_load_lds_dwordx4 v[244:245], off
	v_lshl_add_u64 v[246:247], s[72:73], 0, v[132:133]
	s_mov_b32 m0, s74
	s_nop 0
	global_load_lds_dwordx4 v[246:247], off
	s_barrier
	s_waitcnt lgkmcnt(7)
	v_mfma_f32_16x16x32_bf16 v[62:65], v[144:147], v[160:163], v[62:65]
	v_mfma_f32_16x16x32_bf16 v[58:61], v[152:155], v[160:163], v[58:61]
	s_waitcnt lgkmcnt(5)
	v_mfma_f32_16x16x32_bf16 v[54:57], v[144:147], v[192:195], v[54:57]
	v_mfma_f32_16x16x32_bf16 v[50:53], v[152:155], v[192:195], v[50:53]
	s_waitcnt lgkmcnt(3)
	v_mfma_f32_16x16x32_bf16 v[38:41], v[144:147], v[200:203], v[38:41]
	v_mfma_f32_16x16x32_bf16 v[34:37], v[152:155], v[200:203], v[34:37]
	s_waitcnt lgkmcnt(1)
	v_mfma_f32_16x16x32_bf16 v[22:25], v[144:147], v[220:223], v[22:25]
	v_mfma_f32_16x16x32_bf16 v[18:21], v[152:155], v[220:223], v[18:21]
	v_mfma_f32_16x16x32_bf16 v[62:65], v[148:151], v[188:191], v[62:65]
	v_mfma_f32_16x16x32_bf16 v[58:61], v[156:159], v[188:191], v[58:61]
	v_mfma_f32_16x16x32_bf16 v[54:57], v[148:151], v[196:199], v[54:57]
	v_mfma_f32_16x16x32_bf16 v[50:53], v[156:159], v[196:199], v[50:53]
	v_mfma_f32_16x16x32_bf16 v[38:41], v[148:151], v[216:219], v[38:41]
	v_mfma_f32_16x16x32_bf16 v[34:37], v[156:159], v[216:219], v[34:37]
	s_waitcnt lgkmcnt(0)
	v_mfma_f32_16x16x32_bf16 v[22:25], v[148:151], v[224:227], v[22:25]
	v_mfma_f32_16x16x32_bf16 v[18:21], v[156:159], v[224:227], v[18:21]
	s_barrier
	s_add_u32 s26, s70, 0x80000
	s_addc_u32 s27, s71, 0
	s_add_i32 s2, s2, s3
	v_lshl_add_u64 v[144:145], s[26:27], 0, v[0:1]
	s_mov_b32 m0, s2
	s_nop 0
	global_load_lds_dwordx4 v[144:145], off
	v_lshl_add_u64 v[144:145], s[26:27], 0, v[130:131]
	s_add_i32 m0, s2, 0x2000
	s_nop 0
	global_load_lds_dwordx4 v[144:145], off
	s_waitcnt vmcnt(6)
	s_barrier
	v_mfma_f32_16x16x32_bf16 v[46:49], v[228:231], v[160:163], v[46:49]
	v_mfma_f32_16x16x32_bf16 v[42:45], v[236:239], v[160:163], v[42:45]
	v_mfma_f32_16x16x32_bf16 v[30:33], v[228:231], v[192:195], v[30:33]
	v_mfma_f32_16x16x32_bf16 v[26:29], v[236:239], v[192:195], v[26:29]
	v_mfma_f32_16x16x32_bf16 v[14:17], v[228:231], v[200:203], v[14:17]
	v_mfma_f32_16x16x32_bf16 v[10:13], v[236:239], v[200:203], v[10:13]
	v_mfma_f32_16x16x32_bf16 v[6:9], v[228:231], v[220:223], v[6:9]
	v_mfma_f32_16x16x32_bf16 v[2:5], v[236:239], v[220:223], v[2:5]
	v_mfma_f32_16x16x32_bf16 v[46:49], v[232:235], v[188:191], v[46:49]
	v_mfma_f32_16x16x32_bf16 v[42:45], v[240:243], v[188:191], v[42:45]
	v_mfma_f32_16x16x32_bf16 v[30:33], v[232:235], v[196:199], v[30:33]
	v_mfma_f32_16x16x32_bf16 v[26:29], v[240:243], v[196:199], v[26:29]
	v_mfma_f32_16x16x32_bf16 v[14:17], v[232:235], v[216:219], v[14:17]
	v_mfma_f32_16x16x32_bf16 v[10:13], v[240:243], v[216:219], v[10:13]
	v_mfma_f32_16x16x32_bf16 v[6:9], v[232:235], v[224:227], v[6:9]
	v_mfma_f32_16x16x32_bf16 v[2:5], v[240:243], v[224:227], v[2:5]
	s_add_i32 s2, 0, 0x18000
	v_add_u32_e32 v156, s2, v141
	s_barrier
	ds_read_b128 v[144:147], v156
	ds_read_b128 v[148:151], v156 offset:1024
	ds_read_b128 v[152:155], v156 offset:2048
	ds_read_b128 v[156:159], v156 offset:3072
	s_add_u32 s26, s72, 0x80000
	s_addc_u32 s27, s73, 0
	s_mov_b32 m0, s75
	v_lshl_add_u64 v[228:229], s[26:27], 0, v[134:135]
	ds_read_b128 v[160:163], v143 offset:32768
	ds_read_b128 v[188:191], v143 offset:33792
	ds_read_b128 v[192:195], v143 offset:34816
	ds_read_b128 v[196:199], v143 offset:35840
	ds_read_b128 v[200:203], v143 offset:36864
	ds_read_b128 v[216:219], v143 offset:37888
	ds_read_b128 v[220:223], v143 offset:38912
	ds_read_b128 v[224:227], v143 offset:39936
	global_load_lds_dwordx4 v[228:229], off
	v_lshl_add_u64 v[228:229], s[26:27], 0, v[132:133]
	s_mov_b32 m0, s79
	s_nop 0
	global_load_lds_dwordx4 v[228:229], off
	s_waitcnt lgkmcnt(8)
	s_barrier
	s_waitcnt lgkmcnt(7)
	v_mfma_f32_16x16x32_bf16 v[126:129], v[144:147], v[160:163], v[126:129]
	v_mfma_f32_16x16x32_bf16 v[122:125], v[152:155], v[160:163], v[122:125]
	s_waitcnt lgkmcnt(5)
	v_mfma_f32_16x16x32_bf16 v[118:121], v[144:147], v[192:195], v[118:121]
	v_mfma_f32_16x16x32_bf16 v[114:117], v[152:155], v[192:195], v[114:117]
	s_waitcnt lgkmcnt(3)
	v_mfma_f32_16x16x32_bf16 v[102:105], v[144:147], v[200:203], v[102:105]
	v_mfma_f32_16x16x32_bf16 v[98:101], v[152:155], v[200:203], v[98:101]
	s_waitcnt lgkmcnt(1)
	v_mfma_f32_16x16x32_bf16 v[86:89], v[144:147], v[220:223], v[86:89]
	v_mfma_f32_16x16x32_bf16 v[82:85], v[152:155], v[220:223], v[82:85]
	s_add_i32 s17, 0, 0x1c000
	v_add_u32_e32 v206, s17, v141
	ds_read_b128 v[228:231], v206
	ds_read_b128 v[232:235], v206 offset:1024
	ds_read_b128 v[236:239], v206 offset:2048
	ds_read_b128 v[240:243], v206 offset:3072
	v_mfma_f32_16x16x32_bf16 v[126:129], v[148:151], v[188:191], v[126:129]
	v_mfma_f32_16x16x32_bf16 v[122:125], v[156:159], v[188:191], v[122:125]
	v_mfma_f32_16x16x32_bf16 v[118:121], v[148:151], v[196:199], v[118:121]
	v_mfma_f32_16x16x32_bf16 v[114:117], v[156:159], v[196:199], v[114:117]
	v_mfma_f32_16x16x32_bf16 v[102:105], v[148:151], v[216:219], v[102:105]
	v_mfma_f32_16x16x32_bf16 v[98:101], v[156:159], v[216:219], v[98:101]
	s_waitcnt lgkmcnt(4)
	v_mfma_f32_16x16x32_bf16 v[86:89], v[148:151], v[224:227], v[86:89]
	v_mfma_f32_16x16x32_bf16 v[82:85], v[156:159], v[224:227], v[82:85]
	s_barrier
	s_add_i32 s2, s2, s3
	v_lshl_add_u64 v[164:165], v[164:165], 0, s[28:29]
	s_mov_b32 m0, s2
	global_load_lds_dwordx4 v[164:165], off
	v_lshl_add_u64 v[164:165], v[204:205], 0, s[28:29]
	s_add_i32 m0, s2, 0x2000
	s_nop 0
	global_load_lds_dwordx4 v[164:165], off
	s_barrier
	s_waitcnt lgkmcnt(3)
	v_mfma_f32_16x16x32_bf16 v[110:113], v[228:231], v[160:163], v[110:113]
	s_waitcnt lgkmcnt(1)
	v_mfma_f32_16x16x32_bf16 v[106:109], v[236:239], v[160:163], v[106:109]
	v_mfma_f32_16x16x32_bf16 v[94:97], v[228:231], v[192:195], v[94:97]
	v_mfma_f32_16x16x32_bf16 v[90:93], v[236:239], v[192:195], v[90:93]
	v_mfma_f32_16x16x32_bf16 v[78:81], v[228:231], v[200:203], v[78:81]
	v_mfma_f32_16x16x32_bf16 v[74:77], v[236:239], v[200:203], v[74:77]
	v_mfma_f32_16x16x32_bf16 v[70:73], v[228:231], v[220:223], v[70:73]
	v_mfma_f32_16x16x32_bf16 v[66:69], v[236:239], v[220:223], v[66:69]
	v_mfma_f32_16x16x32_bf16 v[110:113], v[232:235], v[188:191], v[110:113]
	s_waitcnt lgkmcnt(0)
	v_mfma_f32_16x16x32_bf16 v[106:109], v[240:243], v[188:191], v[106:109]
	v_mfma_f32_16x16x32_bf16 v[94:97], v[232:235], v[196:199], v[94:97]
	v_mfma_f32_16x16x32_bf16 v[90:93], v[240:243], v[196:199], v[90:93]
	v_mfma_f32_16x16x32_bf16 v[78:81], v[232:235], v[216:219], v[78:81]
	v_mfma_f32_16x16x32_bf16 v[74:77], v[240:243], v[216:219], v[74:77]
	v_mfma_f32_16x16x32_bf16 v[70:73], v[232:235], v[224:227], v[70:73]
	v_mfma_f32_16x16x32_bf16 v[66:69], v[240:243], v[224:227], v[66:69]
	s_mov_b32 m0, s80
	v_lshl_add_u64 v[164:165], v[244:245], 0, s[28:29]
	s_barrier
	ds_read_b128 v[160:163], v143 offset:49152
	ds_read_b128 v[188:191], v143 offset:50176
	ds_read_b128 v[192:195], v143 offset:51200
	ds_read_b128 v[196:199], v143 offset:52224
	ds_read_b128 v[200:203], v143 offset:53248
	ds_read_b128 v[216:219], v143 offset:54272
	ds_read_b128 v[220:223], v143 offset:55296
	ds_read_b128 v[224:227], v143 offset:56320
	global_load_lds_dwordx4 v[164:165], off
	v_lshl_add_u64 v[164:165], v[246:247], 0, s[28:29]
	s_mov_b32 m0, s81
	s_nop 0
	global_load_lds_dwordx4 v[164:165], off
	s_barrier
	s_waitcnt lgkmcnt(7)
	v_mfma_f32_16x16x32_bf16 v[62:65], v[144:147], v[160:163], v[62:65]
	v_mfma_f32_16x16x32_bf16 v[58:61], v[152:155], v[160:163], v[58:61]
	s_waitcnt lgkmcnt(5)
	v_mfma_f32_16x16x32_bf16 v[54:57], v[144:147], v[192:195], v[54:57]
	v_mfma_f32_16x16x32_bf16 v[50:53], v[152:155], v[192:195], v[50:53]
	s_waitcnt lgkmcnt(3)
	v_mfma_f32_16x16x32_bf16 v[38:41], v[144:147], v[200:203], v[38:41]
	v_mfma_f32_16x16x32_bf16 v[34:37], v[152:155], v[200:203], v[34:37]
	s_waitcnt lgkmcnt(1)
	v_mfma_f32_16x16x32_bf16 v[22:25], v[144:147], v[220:223], v[22:25]
	v_mfma_f32_16x16x32_bf16 v[18:21], v[152:155], v[220:223], v[18:21]
	v_mfma_f32_16x16x32_bf16 v[62:65], v[148:151], v[188:191], v[62:65]
	v_mfma_f32_16x16x32_bf16 v[58:61], v[156:159], v[188:191], v[58:61]
	v_mfma_f32_16x16x32_bf16 v[54:57], v[148:151], v[196:199], v[54:57]
	v_mfma_f32_16x16x32_bf16 v[50:53], v[156:159], v[196:199], v[50:53]
	v_mfma_f32_16x16x32_bf16 v[38:41], v[148:151], v[216:219], v[38:41]
	v_mfma_f32_16x16x32_bf16 v[34:37], v[156:159], v[216:219], v[34:37]
	s_waitcnt lgkmcnt(0)
	v_mfma_f32_16x16x32_bf16 v[22:25], v[148:151], v[224:227], v[22:25]
	v_mfma_f32_16x16x32_bf16 v[18:21], v[156:159], v[224:227], v[18:21]
	s_barrier
	s_add_u32 s26, s70, 0x80080
	s_addc_u32 s27, s71, 0
	s_add_i32 s2, s17, s3
	v_lshl_add_u64 v[144:145], s[26:27], 0, v[0:1]
	s_mov_b32 m0, s2
	s_nop 0
	global_load_lds_dwordx4 v[144:145], off
	v_lshl_add_u64 v[144:145], s[26:27], 0, v[130:131]
	s_add_i32 m0, s2, 0x2000
	s_nop 0
	global_load_lds_dwordx4 v[144:145], off
	s_waitcnt vmcnt(6)
	s_barrier
	v_mfma_f32_16x16x32_bf16 v[46:49], v[228:231], v[160:163], v[46:49]
	v_mfma_f32_16x16x32_bf16 v[42:45], v[236:239], v[160:163], v[42:45]
	v_mfma_f32_16x16x32_bf16 v[30:33], v[228:231], v[192:195], v[30:33]
	v_mfma_f32_16x16x32_bf16 v[26:29], v[236:239], v[192:195], v[26:29]
	v_mfma_f32_16x16x32_bf16 v[14:17], v[228:231], v[200:203], v[14:17]
	v_mfma_f32_16x16x32_bf16 v[10:13], v[236:239], v[200:203], v[10:13]
	v_mfma_f32_16x16x32_bf16 v[6:9], v[228:231], v[220:223], v[6:9]
	v_mfma_f32_16x16x32_bf16 v[2:5], v[236:239], v[220:223], v[2:5]
	v_mfma_f32_16x16x32_bf16 v[46:49], v[232:235], v[188:191], v[46:49]
	v_mfma_f32_16x16x32_bf16 v[42:45], v[240:243], v[188:191], v[42:45]
	v_mfma_f32_16x16x32_bf16 v[30:33], v[232:235], v[196:199], v[30:33]
	v_mfma_f32_16x16x32_bf16 v[26:29], v[240:243], v[196:199], v[26:29]
	v_mfma_f32_16x16x32_bf16 v[14:17], v[232:235], v[216:219], v[14:17]
	v_mfma_f32_16x16x32_bf16 v[10:13], v[240:243], v[216:219], v[10:13]
	v_mfma_f32_16x16x32_bf16 v[6:9], v[232:235], v[224:227], v[6:9]
	v_mfma_f32_16x16x32_bf16 v[2:5], v[240:243], v[224:227], v[2:5]
	s_add_i32 s44, s44, 2
	s_add_u32 s68, s68, 0x100
	s_addc_u32 s69, s69, 0
	s_add_u32 s83, s83, 0x100
	s_addc_u32 s92, s92, 0
	s_cmp_gt_u32 s44, 29
	s_barrier
	s_cbranch_scc0 .LBB0_1044
	v_lshl_add_u32 v144, s47, 8, v140
	v_lshl_or_b32 v146, s46, 8, v142
	v_ashrrev_i32_e32 v145, 31, v144
	v_cvt_pk_bf16_f32 v126, v126, v127
	v_cvt_pk_bf16_f32 v127, v128, v129
	v_cvt_pk_bf16_f32 v128, v122, v123
	v_lshlrev_b64 v[122:123], 12, v[144:145]
	v_ashrrev_i32_e32 v147, 31, v146
	v_cvt_pk_bf16_f32 v129, v124, v125
	v_lshl_add_u64 v[122:123], s[22:23], 0, v[122:123]
	v_lshlrev_b64 v[124:125], 1, v[146:147]
	v_lshl_add_u64 v[122:123], v[122:123], 0, v[124:125]
	v_cvt_pk_bf16_f32 v110, v110, v111
	v_cvt_pk_bf16_f32 v111, v112, v113
	v_cvt_pk_bf16_f32 v112, v106, v107
	v_cvt_pk_bf16_f32 v113, v108, v109
	global_store_dwordx4 v[122:123], v[110:113], off offset:256
	v_cvt_pk_bf16_f32 v94, v94, v95
	v_cvt_pk_bf16_f32 v95, v96, v97
	v_or_b32_e32 v110, 16, v144
	v_ashrrev_i32_e32 v111, 31, v110
	v_lshlrev_b64 v[110:111], 12, v[110:111]
	v_lshl_add_u64 v[110:111], s[22:23], 0, v[110:111]
	v_lshl_add_u64 v[110:111], v[110:111], 0, v[124:125]
	v_cvt_pk_bf16_f32 v96, v90, v91
	v_cvt_pk_bf16_f32 v97, v92, v93
	global_store_dwordx4 v[110:111], v[94:97], off offset:256
	s_mov_b32 s2, 0x80000
	v_cvt_pk_bf16_f32 v62, v62, v63
	v_or_b32_e32 v94, 32, v144
	v_ashrrev_i32_e32 v95, 31, v94
	v_cvt_pk_bf16_f32 v63, v64, v65
	v_cvt_pk_bf16_f32 v65, v60, v61
	s_mov_b64 s[4:5], 0x80000
	v_add_co_u32_e32 v60, vcc, s2, v122
	v_lshlrev_b64 v[94:95], 12, v[94:95]
	v_cvt_pk_bf16_f32 v64, v58, v59
	v_lshl_add_u64 v[58:59], v[122:123], 0, s[4:5]
	v_addc_co_u32_e32 v61, vcc, 0, v123, vcc
	v_cvt_pk_bf16_f32 v46, v46, v47
	v_cvt_pk_bf16_f32 v47, v48, v49
	v_cvt_pk_bf16_f32 v48, v42, v43
	v_cvt_pk_bf16_f32 v49, v44, v45
	s_mov_b32 s2, 0x90000
	v_lshl_add_u64 v[94:95], s[22:23], 0, v[94:95]
	global_store_dwordx4 v[58:59], v[46:49], off offset:256
	s_mov_b64 s[4:5], 0x90000
	v_lshl_add_u64 v[94:95], v[94:95], 0, v[124:125]
	v_add_co_u32_e32 v48, vcc, s2, v122
	v_cvt_pk_bf16_f32 v78, v78, v79
	v_cvt_pk_bf16_f32 v79, v80, v81
	v_cvt_pk_bf16_f32 v80, v74, v75
	v_cvt_pk_bf16_f32 v81, v76, v77
	v_lshl_add_u64 v[46:47], v[122:123], 0, s[4:5]
	v_addc_co_u32_e32 v49, vcc, 0, v123, vcc
	v_cvt_pk_bf16_f32 v30, v30, v31
	v_cvt_pk_bf16_f32 v31, v32, v33
	v_cvt_pk_bf16_f32 v32, v26, v27
	v_cvt_pk_bf16_f32 v33, v28, v29
	s_mov_b32 s2, 0xa0000
	global_store_dwordx4 v[94:95], v[78:81], off offset:256
	global_store_dwordx4 v[46:47], v[30:33], off offset:256
	s_mov_b64 s[4:5], 0xa0000
	v_or_b32_e32 v78, 48, v144
	v_add_co_u32_e32 v32, vcc, s2, v122
	v_ashrrev_i32_e32 v79, 31, v78
	v_lshl_add_u64 v[30:31], v[122:123], 0, s[4:5]
	v_addc_co_u32_e32 v33, vcc, 0, v123, vcc
	v_cvt_pk_bf16_f32 v14, v14, v15
	v_cvt_pk_bf16_f32 v15, v16, v17
	v_cvt_pk_bf16_f32 v16, v10, v11
	v_cvt_pk_bf16_f32 v17, v12, v13
	s_mov_b32 s2, 0xb0000
	v_lshlrev_b64 v[78:79], 12, v[78:79]
	global_store_dwordx4 v[30:31], v[14:17], off offset:256
	v_lshl_add_u64 v[78:79], s[22:23], 0, v[78:79]
	s_mov_b64 s[4:5], 0xb0000
	v_add_co_u32_e32 v16, vcc, s2, v122
	v_cvt_pk_bf16_f32 v106, v118, v119
	s_nop 0
	v_addc_co_u32_e32 v17, vcc, 0, v123, vcc
	v_cvt_pk_bf16_f32 v107, v120, v121
	v_cvt_pk_bf16_f32 v108, v114, v115
	v_cvt_pk_bf16_f32 v109, v116, v117
	v_cvt_pk_bf16_f32 v90, v102, v103
	v_cvt_pk_bf16_f32 v91, v104, v105
	v_cvt_pk_bf16_f32 v92, v98, v99
	v_cvt_pk_bf16_f32 v93, v100, v101
	v_cvt_pk_bf16_f32 v74, v86, v87
	v_cvt_pk_bf16_f32 v75, v88, v89
	v_cvt_pk_bf16_f32 v76, v82, v83
	v_cvt_pk_bf16_f32 v77, v84, v85
	v_lshl_add_u64 v[78:79], v[78:79], 0, v[124:125]
	v_cvt_pk_bf16_f32 v70, v70, v71
	v_cvt_pk_bf16_f32 v71, v72, v73
	v_cvt_pk_bf16_f32 v72, v66, v67
	v_cvt_pk_bf16_f32 v73, v68, v69
	v_cvt_pk_bf16_f32 v42, v54, v55
	v_cvt_pk_bf16_f32 v43, v56, v57
	v_cvt_pk_bf16_f32 v44, v50, v51
	v_cvt_pk_bf16_f32 v45, v52, v53
	v_cvt_pk_bf16_f32 v26, v38, v39
	v_cvt_pk_bf16_f32 v27, v40, v41
	v_cvt_pk_bf16_f32 v28, v34, v35
	v_cvt_pk_bf16_f32 v29, v36, v37
	v_cvt_pk_bf16_f32 v10, v22, v23
	v_cvt_pk_bf16_f32 v11, v24, v25
	v_cvt_pk_bf16_f32 v12, v18, v19
	v_cvt_pk_bf16_f32 v13, v20, v21
	v_lshl_add_u64 v[14:15], v[122:123], 0, s[4:5]
	v_cvt_pk_bf16_f32 v6, v6, v7
	v_cvt_pk_bf16_f32 v7, v8, v9
	v_cvt_pk_bf16_f32 v8, v2, v3
	v_cvt_pk_bf16_f32 v9, v4, v5
	s_and_b64 vcc, exec, s[0:1]
	s_mov_b32 s46, s42
	s_mov_b32 s47, s54
	s_mov_b64 s[70:71], s[64:65]
	s_mov_b64 s[68:69], s[62:63]
	global_store_dwordx4 v[122:123], v[126:129], off
	global_store_dwordx4 v[110:111], v[106:109], off
	global_store_dwordx4 v[94:95], v[90:93], off
	global_store_dwordx4 v[78:79], v[74:77], off
	global_store_dwordx4 v[78:79], v[70:73], off offset:256
	global_store_dwordx4 v[60:61], v[62:65], off
	global_store_dwordx4 v[48:49], v[42:45], off
	global_store_dwordx4 v[32:33], v[26:29], off
	global_store_dwordx4 v[16:17], v[10:13], off
	global_store_dwordx4 v[14:15], v[6:9], off offset:256
	s_cbranch_vccz .LBB0_1041
	v_readlane_b32 s0, v254, 12
	s_waitcnt vmcnt(0)
	v_readlane_b32 s1, v254, 13
	v_readlane_b32 s84, v251, 38
	s_andn2_b64 vcc, exec, s[0:1]
	v_readlane_b32 s85, v251, 39
	v_readlane_b32 s86, v251, 40
	v_readlane_b32 s87, v251, 41
	s_cbranch_vccnz .LBB0_1048
	s_barrier
